# GEMM load segments: dead m0 save/restore around each LDS-DMA stage removed (105 pairs), vmcnt+lgkmcnt waits before each phase barrier fused
# speedup vs baseline: 1.0107x; 1.0024x over previous
.LBB0_78:
	s_mov_b64 s[52:53], s[58:59]
	s_mov_b32 s0, s77
	s_mov_b32 s96, s97
	s_cmp_lg_u32 s85, 0
	s_nop 0
	v_writelane_b32 v254, s0, 55
	s_cbranch_scc0 .LBB0_87
	s_add_i32 s0, s85, -1
	s_mul_hi_i32 s3, s0, 0x38e38e39
	s_lshr_b32 s4, s3, 31
	s_ashr_i32 s35, s3, 1
	s_add_i32 s35, s35, s4
	s_mul_i32 s3, s35, 9
	s_sub_i32 s0, s0, s3
	s_add_u32 s2, s52, 0x7128000
	v_writelane_b32 v254, s2, 56
	s_addc_u32 s2, s53, 0
	v_writelane_b32 v254, s2, 57
	v_writelane_b32 v254, s0, 58
	s_mov_b64 s[2:3], 0
	v_writelane_b32 v254, s2, 59
	s_mov_b64 s[4:5], -1
	s_mov_b64 s[78:79], 0
	s_cmp_lt_i32 s0, 4
	v_writelane_b32 v254, s3, 60
	s_cbranch_scc1 .LBB0_350
	v_readlane_b32 s83, v254, 58
	v_writelane_b32 v254, s52, 61
	s_cmp_gt_i32 s83, 5
	s_nop 0
	v_writelane_b32 v254, s53, 62
	s_cbranch_scc0 .LBB0_101
	s_cmp_gt_i32 s83, 6
	s_cbranch_scc0 .LBB0_102
	s_cmp_eq_u32 s83, 7
	s_mov_b64 s[2:3], -1
	s_movk_i32 s25, 0x1fff
	s_movk_i32 s26, 0x1000
	s_mov_b64 s[28:29], 0x1000
	s_mov_b32 s30, 0x3a800000
	s_cbranch_scc0 .LBB0_105
	v_readlane_b32 s21, v254, 55
	s_cmpk_lt_i32 s21, 0x840
	s_cselect_b32 s0, s21, 0
	s_ashr_i32 s3, s0, 31
	s_lshr_b32 s3, s3, 29
	s_add_i32 s3, s0, s3
	s_ashr_i32 s4, s3, 3
	s_and_b32 s3, s3, -8
	s_sub_i32 s0, s0, s3
	s_cmp_lt_i32 s0, 0
	s_movk_i32 s2, 0x109
	s_cselect_b32 s3, s2, 0x108
	s_mul_i32 s0, s0, s3
	s_add_i32 s0, s0, s4
	s_mul_hi_i32 s3, s0, 0x2e8ba2e9
	s_lshr_b32 s4, s3, 31
	s_ashr_i32 s3, s3, 5
	s_add_i32 s3, s3, s4
	s_lshl_b32 s4, s3, 3
	s_sub_i32 s5, 0x60, s4
	s_min_i32 s5, s5, 8
	s_abs_i32 s6, s5
	v_cvt_f32_u32_e32 v2, s6
	s_sub_i32 s10, 0, s6
	s_mulk_i32 s3, 0xb0
	s_sub_i32 s0, s0, s3
	v_rcp_iflag_f32_e32 v2, v2
	s_abs_i32 s7, s0
	s_xor_b32 s3, s0, s5
	s_ashr_i32 s3, s3, 31
	v_mul_f32_e32 v2, 0x4f7ffffe, v2
	v_cvt_u32_f32_e32 v2, v2
	v_mov_b32_e32 v0, v249
	s_movk_i32 s38, 0x400
	v_readfirstlane_b32 s11, v2
	s_mul_i32 s10, s10, s11
	s_mul_hi_u32 s10, s11, s10
	s_add_i32 s11, s11, s10
	s_mul_hi_u32 s10, s7, s11
	s_mul_i32 s11, s10, s6
	s_sub_i32 s7, s7, s11
	s_add_i32 s11, s10, 1
	s_sub_i32 s20, s7, s6
	s_cmp_ge_u32 s7, s6
	s_cselect_b32 s10, s11, s10
	s_cselect_b32 s7, s20, s7
	s_add_i32 s11, s10, 1
	s_cmp_ge_u32 s7, s6
	s_cselect_b32 s6, s11, s10
	s_xor_b32 s6, s6, s3
	s_sub_i32 s3, s6, s3
	s_mul_i32 s5, s3, s5
	s_sub_i32 s0, s0, s5
	s_add_i32 s50, s4, s0
	v_readfirstlane_b32 s24, v0
	s_movk_i32 s40, 0x400
	s_cmpk_gt_i32 s21, 0x83f
	s_cbranch_scc1 .LBB0_104
	v_bfe_i32 v4, v0, 27, 1
	v_lshlrev_b32_e32 v2, 4, v0
	v_lshrrev_b32_e32 v4, 22, v4
	v_add_u32_e32 v4, v2, v4
	v_and_b32_e32 v4, 0xfffffc00, v4
	v_sub_u32_e32 v4, v2, v4
	v_lshrrev_b32_e32 v5, 4, v4
	v_ashrrev_i32_e32 v3, 31, v0
	v_bitop3_b32 v4, v5, v4, 32 bitop3:0x6c
	v_lshrrev_b32_e32 v3, 26, v3
	v_ashrrev_i32_e32 v6, 31, v4
	v_add_u32_e32 v3, v0, v3
	v_lshrrev_b32_e32 v6, 26, v6
	v_ashrrev_i32_e32 v3, 6, v3
	v_add_u32_e32 v6, v4, v6
	v_lshlrev_b32_e32 v5, 3, v3
	v_ashrrev_i32_e32 v7, 6, v6
	v_and_b32_e32 v6, 0xc0, v6
	v_and_b32_e32 v5, -16, v5
	v_lshlrev_b32_e32 v3, 5, v3
	v_sub_u32_e32 v4, v4, v6
	v_add_u32_e32 v5, v7, v5
	v_and_b32_e32 v3, 32, v3
	v_ashrrev_i16_sdwa v4, v214, sext(v4) dst_sel:DWORD dst_unused:UNUSED_PAD src0_sel:DWORD src1_sel:BYTE_0
	v_add_u32_sdwa v3, v3, sext(v4) dst_sel:DWORD dst_unused:UNUSED_PAD src0_sel:DWORD src1_sel:WORD_0
	v_mul_lo_u32 v4, v5, s40
	v_add_lshl_u32 v130, v3, v4, 1
	v_lshlrev_b32_e32 v4, 1, v5
	v_and_b32_e32 v5, 31, v5
	s_mov_b32 s2, 0x7fffffc0
	v_and_or_b32 v4, v4, s2, v5
	v_mul_lo_u32 v4, v4, s38
	v_add_u32_e32 v2, 0x2000, v2
	v_add_lshl_u32 v131, v4, v3, 1
	v_ashrrev_i32_e32 v3, 31, v2
	v_lshrrev_b32_e32 v3, 22, v3
	v_add_u32_e32 v3, v2, v3
	v_ashrrev_i32_e32 v3, 10, v3
	v_mul_i32_i24_e32 v4, 0x400, v3
	v_sub_u32_e32 v2, v2, v4
	v_lshrrev_b32_e32 v4, 4, v2
	s_mul_i32 s4, s35, 0xb00000
	v_bitop3_b32 v2, v4, v2, 32 bitop3:0x6c
	s_mul_hi_i32 s0, s35, 0xb00000
	s_add_u32 s4, s52, s4
	v_ashrrev_i32_e32 v5, 31, v2
	s_addc_u32 s5, s53, s0
	v_lshrrev_b32_e32 v5, 26, v5
	s_add_u32 s0, s4, 0x1728000
	v_add_u32_e32 v5, v2, v5
	s_addc_u32 s10, s5, 0
	v_lshlrev_b32_e32 v4, 3, v3
	v_ashrrev_i32_e32 v6, 6, v5
	v_and_b32_e32 v5, 0xc0, v5
	s_ashr_i32 s41, s40, 31
	v_and_b32_e32 v4, -16, v4
	v_lshlrev_b32_e32 v3, 5, v3
	v_sub_u32_e32 v2, v2, v5
	s_lshl_b64 s[6:7], s[40:41], 9
	s_ashr_i32 s27, s50, 31
	v_add_u32_e32 v4, v6, v4
	v_and_b32_e32 v3, 32, v3
	v_ashrrev_i16_sdwa v2, v214, sext(v2) dst_sel:DWORD dst_unused:UNUSED_PAD src0_sel:DWORD src1_sel:BYTE_0
	s_mul_i32 s27, s6, s27
	s_mul_hi_u32 s28, s6, s50
	v_add_u32_sdwa v2, v3, sext(v2) dst_sel:DWORD dst_unused:UNUSED_PAD src0_sel:DWORD src1_sel:WORD_0
	v_mul_lo_u32 v3, v4, s40
	s_add_i32 s27, s28, s27
	s_lshr_b64 s[28:29], s[40:41], 23
	v_add_lshl_u32 v132, v2, v3, 1
	v_lshlrev_b32_e32 v3, 1, v4
	v_and_b32_e32 v4, 31, v4
	s_ashr_i32 s26, s24, 6
	s_ashr_i32 s39, s38, 31
	s_mul_i32 s28, s28, s50
	s_ashr_i32 s25, s24, 8
	v_and_or_b32 v3, v3, s2, v4
	s_lshl_b64 s[4:5], s[40:41], 8
	s_lshl_b64 s[20:21], s[38:39], 6
	s_lshl_b64 s[22:23], s[38:39], 9
	s_lshl_b32 s11, s26, 10
	s_add_i32 s27, s27, s28
	s_mul_i32 s28, s6, s50
	v_readlane_b32 s2, v254, 56
	s_mov_b64 s[86:87], s[52:53]
	s_add_u32 s52, s2, s28
	v_readlane_b32 s2, v254, 57
	s_addc_u32 s53, s2, s27
	s_ashr_i32 s27, s3, 31
	s_mul_i32 s27, s22, s27
	s_mul_hi_u32 s28, s22, s3
	s_add_i32 s27, s28, s27
	s_lshr_b64 s[28:29], s[38:39], 23
	s_mul_i32 s28, s28, s3
	s_add_i32 s27, s27, s28
	s_mul_i32 s28, s22, s3
	s_add_u32 s54, s0, s28
	s_addc_u32 s55, s10, s27
	s_add_i32 s11, s11, 0
	v_mul_lo_u32 v3, v3, s38
	s_add_i32 s28, s11, 0x10000
	s_add_i32 s29, s11, 0x12000
	v_add_lshl_u32 v133, v3, v2, 1
	s_mov_b32 m0, s28
	s_nop 0
	global_load_lds_dwordx4 v131, s[54:55]
	s_mov_b32 m0, s29
	s_nop 0
	global_load_lds_dwordx4 v133, s[54:55]
	s_add_u32 s38, s54, s20
	s_addc_u32 s39, s55, s21
	s_add_i32 s30, s11, 0x14000
	s_add_i32 s31, s11, 0x16000
	s_mov_b32 m0, s30
	s_nop 0
	global_load_lds_dwordx4 v131, s[38:39]
	s_mov_b32 m0, s31
	s_nop 0
	global_load_lds_dwordx4 v133, s[38:39]
	s_add_i32 s60, s11, 0x2000
	s_mov_b32 m0, s11
	s_nop 0
	global_load_lds_dwordx4 v130, s[52:53]
	s_mov_b32 m0, s60
	s_nop 0
	global_load_lds_dwordx4 v132, s[52:53]
	s_add_u32 s40, s52, s4
	s_addc_u32 s41, s53, s5
	s_add_i32 s61, s11, 0x4000
	s_add_i32 s62, s11, 0x6000
	s_mov_b32 m0, s61
	s_nop 0
	global_load_lds_dwordx4 v130, s[40:41]
	s_mov_b32 m0, s62
	s_nop 0
	global_load_lds_dwordx4 v132, s[40:41]
	s_cmp_eq_u32 s25, 1
	s_cselect_b64 s[42:43], -1, 0
	s_cmp_lg_u32 s25, 1
	s_cbranch_scc1 .LBB0_86
	s_barrier
.LBB0_86:
	s_mov_b64 s[40:41], s[86:87]
	s_add_u32 s44, s40, 0xa128000
	v_and_b32_e32 v2, 48, v0
	v_lshlrev_b32_e32 v3, 6, v0
	s_movk_i32 s2, 0x3c0
	v_lshlrev_b32_e32 v0, 2, v0
	s_addc_u32 s45, s41, 0
	s_lshl_b32 s63, s25, 6
	s_lshl_b32 s25, s25, 13
	v_and_or_b32 v2, v3, s2, v2
	v_and_b32_e32 v0, 32, v0
	v_bitop3_b32 v3, v2, s25, v0 bitop3:0xde
	s_lshl_b32 s25, s26, 5
	s_and_b32 s64, s25, 0x60
	s_lshl_b32 s25, s64, 7
	s_add_u32 s26, s54, 0x80
	s_addc_u32 s27, s55, 0
	s_add_i32 s65, s11, 0x18000
	s_add_i32 s66, s11, 0x1a000
	v_bitop3_b32 v0, s25, v2, v0 bitop3:0xf6
	s_waitcnt vmcnt(2)
	s_barrier
	s_mov_b32 m0, s65
	s_nop 0
	global_load_lds_dwordx4 v131, s[26:27]
	s_mov_b32 m0, s66
	s_nop 0
	global_load_lds_dwordx4 v133, s[26:27]
	s_add_u32 s26, s52, 0x80
	s_addc_u32 s27, s53, 0
	s_add_i32 s67, s11, 0x8000
	s_add_i32 s68, s11, 0xa000
	s_mov_b32 m0, s67
	s_nop 0
	global_load_lds_dwordx4 v130, s[26:27]
	s_mov_b32 m0, s68
	s_nop 0
	global_load_lds_dwordx4 v132, s[26:27]
	s_add_u32 s26, s38, 0x80
	s_addc_u32 s27, s39, 0
	s_add_i32 s69, s11, 0x1c000
	s_add_i32 s70, s11, 0x1e000
	s_mov_b32 m0, s69
	s_nop 0
	global_load_lds_dwordx4 v131, s[26:27]
	s_mov_b32 m0, s70
	s_nop 0
	global_load_lds_dwordx4 v133, s[26:27]
	s_waitcnt vmcnt(6)
	s_add_i32 s71, s11, 0xc000
	s_add_i32 s72, s11, 0xe000
	s_cmpk_lt_u32 s24, 0x100
	v_readlane_b32 s2, v254, 55
	s_cselect_b64 s[46:47], -1, 0
	s_ashr_i32 s73, s63, 31
	s_ashr_i32 s74, s96, 31
	s_ashr_i32 s75, s2, 31
	s_mov_b32 s80, 0
	v_add_u32_e32 v134, 0, v0
	v_add_u32_e32 v135, 0, v3
	s_mov_b64 s[48:49], s[52:53]
	s_barrier
	s_branch .LBB0_90

.LBB0_95:
	v_add_u32_e32 v0, 0x10000, v134
	ds_read_b128 v[136:139], v0
	ds_read_b128 v[140:143], v0 offset:1024
	ds_read_b128 v[144:147], v0 offset:2048
	ds_read_b128 v[148:151], v0 offset:3072
	v_add_u32_e32 v0, 0x14000, v134
	ds_read_b128 v[152:155], v0
	ds_read_b128 v[156:159], v0 offset:1024
	ds_read_b128 v[160:163], v0 offset:2048
	ds_read_b128 v[164:167], v0 offset:3072
	s_cmp_eq_u32 s51, 12
	s_cselect_b32 s56, s48, s26
	s_cselect_b32 s57, s49, s27
	s_cselect_b32 s54, s40, s24
	s_cselect_b32 s55, s41, s25
	s_add_u32 s52, s56, 0x80
	s_addc_u32 s53, s57, 0
	ds_read_b128 v[168:171], v135
	ds_read_b128 v[172:175], v135 offset:1024
	ds_read_b128 v[176:179], v135 offset:2048
	ds_read_b128 v[180:183], v135 offset:3072
	ds_read_b128 v[184:187], v135 offset:4096
	ds_read_b128 v[188:191], v135 offset:5120
	ds_read_b128 v[192:195], v135 offset:6144
	ds_read_b128 v[196:199], v135 offset:7168
	s_add_u32 s58, s26, s4
	s_addc_u32 s59, s27, s5
	s_add_u32 s58, s58, 0xffffff80
	s_addc_u32 s59, s59, -1
	s_mov_b32 m0, s71
	s_nop 0
	global_load_lds_dwordx4 v130, s[58:59]
	s_mov_b32 m0, s72
	s_nop 0
	global_load_lds_dwordx4 v132, s[58:59]
	s_waitcnt vmcnt(8) lgkmcnt(0)
	s_barrier
	s_setprio 1
	v_mfma_f32_16x16x32_bf16 v[126:129], v[136:139], v[168:171], v[126:129]
	v_mfma_f32_16x16x32_bf16 v[122:125], v[144:147], v[168:171], v[122:125]
	v_mfma_f32_16x16x32_bf16 v[110:113], v[136:139], v[176:179], v[110:113]
	v_mfma_f32_16x16x32_bf16 v[106:109], v[144:147], v[176:179], v[106:109]
	v_mfma_f32_16x16x32_bf16 v[94:97], v[136:139], v[184:187], v[94:97]
	v_mfma_f32_16x16x32_bf16 v[90:93], v[144:147], v[184:187], v[90:93]
	v_mfma_f32_16x16x32_bf16 v[78:81], v[136:139], v[192:195], v[78:81]
	v_mfma_f32_16x16x32_bf16 v[74:77], v[144:147], v[192:195], v[74:77]
	v_mfma_f32_16x16x32_bf16 v[126:129], v[140:143], v[172:175], v[126:129]
	v_mfma_f32_16x16x32_bf16 v[122:125], v[148:151], v[172:175], v[122:125]
	v_mfma_f32_16x16x32_bf16 v[110:113], v[140:143], v[180:183], v[110:113]
	v_mfma_f32_16x16x32_bf16 v[106:109], v[148:151], v[180:183], v[106:109]
	v_mfma_f32_16x16x32_bf16 v[94:97], v[140:143], v[188:191], v[94:97]
	v_mfma_f32_16x16x32_bf16 v[90:93], v[148:151], v[188:191], v[90:93]
	v_mfma_f32_16x16x32_bf16 v[78:81], v[140:143], v[196:199], v[78:81]
	v_mfma_f32_16x16x32_bf16 v[74:77], v[148:151], v[196:199], v[74:77]
	v_mfma_f32_16x16x32_bf16 v[118:121], v[152:155], v[168:171], v[118:121]
	v_mfma_f32_16x16x32_bf16 v[114:117], v[160:163], v[168:171], v[114:117]
	v_mfma_f32_16x16x32_bf16 v[102:105], v[152:155], v[176:179], v[102:105]
	v_mfma_f32_16x16x32_bf16 v[98:101], v[160:163], v[176:179], v[98:101]
	v_mfma_f32_16x16x32_bf16 v[86:89], v[152:155], v[184:187], v[86:89]
	v_mfma_f32_16x16x32_bf16 v[82:85], v[160:163], v[184:187], v[82:85]
	v_mfma_f32_16x16x32_bf16 v[70:73], v[152:155], v[192:195], v[70:73]
	v_mfma_f32_16x16x32_bf16 v[66:69], v[160:163], v[192:195], v[66:69]
	v_mfma_f32_16x16x32_bf16 v[118:121], v[156:159], v[172:175], v[118:121]
	v_mfma_f32_16x16x32_bf16 v[114:117], v[164:167], v[172:175], v[114:117]
	v_mfma_f32_16x16x32_bf16 v[102:105], v[156:159], v[180:183], v[102:105]
	v_mfma_f32_16x16x32_bf16 v[98:101], v[164:167], v[180:183], v[98:101]
	v_mfma_f32_16x16x32_bf16 v[86:89], v[156:159], v[188:191], v[86:89]
	v_mfma_f32_16x16x32_bf16 v[82:85], v[164:167], v[188:191], v[82:85]
	v_mfma_f32_16x16x32_bf16 v[70:73], v[156:159], v[196:199], v[70:73]
	v_mfma_f32_16x16x32_bf16 v[66:69], v[164:167], v[196:199], v[66:69]
	s_setprio 0
	s_barrier
	ds_read_b128 v[168:171], v135 offset:16384
	ds_read_b128 v[172:175], v135 offset:17408
	ds_read_b128 v[176:179], v135 offset:18432
	ds_read_b128 v[180:183], v135 offset:19456
	ds_read_b128 v[184:187], v135 offset:20480
	ds_read_b128 v[188:191], v135 offset:21504
	ds_read_b128 v[192:195], v135 offset:22528
	ds_read_b128 v[196:199], v135 offset:23552
	s_mov_b32 m0, s28
	s_nop 0
	global_load_lds_dwordx4 v131, s[54:55]
	s_mov_b32 m0, s29
	s_nop 0
	global_load_lds_dwordx4 v133, s[54:55]
	s_add_u32 s58, s54, s20
	s_addc_u32 s59, s55, s21
	s_mov_b32 m0, s30
	s_nop 0
	global_load_lds_dwordx4 v131, s[58:59]
	s_mov_b32 m0, s31
	s_nop 0
	global_load_lds_dwordx4 v133, s[58:59]
	s_nop 0
	s_mov_b32 m0, s11
	s_nop 0
	global_load_lds_dwordx4 v130, s[56:57]
	s_mov_b32 m0, s60
	s_nop 0
	global_load_lds_dwordx4 v132, s[56:57]
	s_waitcnt vmcnt(8) lgkmcnt(0)
	s_barrier
	s_setprio 1
	v_mfma_f32_16x16x32_bf16 v[62:65], v[136:139], v[168:171], v[62:65]
	v_mfma_f32_16x16x32_bf16 v[58:61], v[144:147], v[168:171], v[58:61]
	v_mfma_f32_16x16x32_bf16 v[46:49], v[136:139], v[176:179], v[46:49]
	v_mfma_f32_16x16x32_bf16 v[42:45], v[144:147], v[176:179], v[42:45]
	v_mfma_f32_16x16x32_bf16 v[30:33], v[136:139], v[184:187], v[30:33]
	v_mfma_f32_16x16x32_bf16 v[26:29], v[144:147], v[184:187], v[26:29]
	v_mfma_f32_16x16x32_bf16 v[14:17], v[136:139], v[192:195], v[14:17]
	v_mfma_f32_16x16x32_bf16 v[10:13], v[144:147], v[192:195], v[10:13]
	v_mfma_f32_16x16x32_bf16 v[62:65], v[140:143], v[172:175], v[62:65]
	v_mfma_f32_16x16x32_bf16 v[58:61], v[148:151], v[172:175], v[58:61]
	v_mfma_f32_16x16x32_bf16 v[46:49], v[140:143], v[180:183], v[46:49]
	v_mfma_f32_16x16x32_bf16 v[42:45], v[148:151], v[180:183], v[42:45]
	v_mfma_f32_16x16x32_bf16 v[30:33], v[140:143], v[188:191], v[30:33]
	v_mfma_f32_16x16x32_bf16 v[26:29], v[148:151], v[188:191], v[26:29]
	v_mfma_f32_16x16x32_bf16 v[14:17], v[140:143], v[196:199], v[14:17]
	v_mfma_f32_16x16x32_bf16 v[10:13], v[148:151], v[196:199], v[10:13]
	v_mfma_f32_16x16x32_bf16 v[54:57], v[152:155], v[168:171], v[54:57]
	v_mfma_f32_16x16x32_bf16 v[50:53], v[160:163], v[168:171], v[50:53]
	v_mfma_f32_16x16x32_bf16 v[38:41], v[152:155], v[176:179], v[38:41]
	v_mfma_f32_16x16x32_bf16 v[34:37], v[160:163], v[176:179], v[34:37]
	v_mfma_f32_16x16x32_bf16 v[22:25], v[152:155], v[184:187], v[22:25]
	v_mfma_f32_16x16x32_bf16 v[18:21], v[160:163], v[184:187], v[18:21]
	v_mfma_f32_16x16x32_bf16 v[6:9], v[152:155], v[192:195], v[6:9]
	v_mfma_f32_16x16x32_bf16 v[2:5], v[160:163], v[192:195], v[2:5]
	v_mfma_f32_16x16x32_bf16 v[54:57], v[156:159], v[172:175], v[54:57]
	v_mfma_f32_16x16x32_bf16 v[50:53], v[164:167], v[172:175], v[50:53]
	v_mfma_f32_16x16x32_bf16 v[38:41], v[156:159], v[180:183], v[38:41]
	v_mfma_f32_16x16x32_bf16 v[34:37], v[164:167], v[180:183], v[34:37]
	v_mfma_f32_16x16x32_bf16 v[22:25], v[156:159], v[188:191], v[22:25]
	v_mfma_f32_16x16x32_bf16 v[18:21], v[164:167], v[188:191], v[18:21]
	v_mfma_f32_16x16x32_bf16 v[6:9], v[156:159], v[196:199], v[6:9]
	v_mfma_f32_16x16x32_bf16 v[2:5], v[164:167], v[196:199], v[2:5]
	s_setprio 0
	s_barrier
	v_add_u32_e32 v0, 0x18000, v134
	ds_read_b128 v[136:139], v0
	ds_read_b128 v[140:143], v0 offset:1024
	ds_read_b128 v[144:147], v0 offset:2048
	ds_read_b128 v[148:151], v0 offset:3072
	v_add_u32_e32 v0, 0x1c000, v134
	ds_read_b128 v[152:155], v0
	ds_read_b128 v[156:159], v0 offset:1024
	ds_read_b128 v[160:163], v0 offset:2048
	ds_read_b128 v[164:167], v0 offset:3072
	ds_read_b128 v[168:171], v135 offset:32768
	ds_read_b128 v[172:175], v135 offset:33792
	ds_read_b128 v[176:179], v135 offset:34816
	ds_read_b128 v[180:183], v135 offset:35840
	ds_read_b128 v[184:187], v135 offset:36864
	ds_read_b128 v[188:191], v135 offset:37888
	ds_read_b128 v[192:195], v135 offset:38912
	ds_read_b128 v[196:199], v135 offset:39936
	s_add_u32 s56, s56, s4
	s_addc_u32 s57, s57, s5
	s_mov_b32 m0, s61
	s_nop 0
	global_load_lds_dwordx4 v130, s[56:57]
	s_mov_b32 m0, s62
	s_nop 0
	global_load_lds_dwordx4 v132, s[56:57]
	s_waitcnt vmcnt(8) lgkmcnt(0)
	s_barrier
	s_setprio 1
	v_mfma_f32_16x16x32_bf16 v[126:129], v[136:139], v[168:171], v[126:129]
	v_mfma_f32_16x16x32_bf16 v[122:125], v[144:147], v[168:171], v[122:125]
	v_mfma_f32_16x16x32_bf16 v[110:113], v[136:139], v[176:179], v[110:113]
	v_mfma_f32_16x16x32_bf16 v[106:109], v[144:147], v[176:179], v[106:109]
	v_mfma_f32_16x16x32_bf16 v[94:97], v[136:139], v[184:187], v[94:97]
	v_mfma_f32_16x16x32_bf16 v[90:93], v[144:147], v[184:187], v[90:93]
	v_mfma_f32_16x16x32_bf16 v[78:81], v[136:139], v[192:195], v[78:81]
	v_mfma_f32_16x16x32_bf16 v[74:77], v[144:147], v[192:195], v[74:77]
	v_mfma_f32_16x16x32_bf16 v[126:129], v[140:143], v[172:175], v[126:129]
	v_mfma_f32_16x16x32_bf16 v[122:125], v[148:151], v[172:175], v[122:125]
	v_mfma_f32_16x16x32_bf16 v[110:113], v[140:143], v[180:183], v[110:113]
	v_mfma_f32_16x16x32_bf16 v[106:109], v[148:151], v[180:183], v[106:109]
	v_mfma_f32_16x16x32_bf16 v[94:97], v[140:143], v[188:191], v[94:97]
	v_mfma_f32_16x16x32_bf16 v[90:93], v[148:151], v[188:191], v[90:93]
	v_mfma_f32_16x16x32_bf16 v[78:81], v[140:143], v[196:199], v[78:81]
	v_mfma_f32_16x16x32_bf16 v[74:77], v[148:151], v[196:199], v[74:77]
	v_mfma_f32_16x16x32_bf16 v[118:121], v[152:155], v[168:171], v[118:121]
	v_mfma_f32_16x16x32_bf16 v[114:117], v[160:163], v[168:171], v[114:117]
	v_mfma_f32_16x16x32_bf16 v[102:105], v[152:155], v[176:179], v[102:105]
	v_mfma_f32_16x16x32_bf16 v[98:101], v[160:163], v[176:179], v[98:101]
	v_mfma_f32_16x16x32_bf16 v[86:89], v[152:155], v[184:187], v[86:89]
	v_mfma_f32_16x16x32_bf16 v[82:85], v[160:163], v[184:187], v[82:85]
	v_mfma_f32_16x16x32_bf16 v[70:73], v[152:155], v[192:195], v[70:73]
	v_mfma_f32_16x16x32_bf16 v[66:69], v[160:163], v[192:195], v[66:69]
	v_mfma_f32_16x16x32_bf16 v[118:121], v[156:159], v[172:175], v[118:121]
	v_mfma_f32_16x16x32_bf16 v[114:117], v[164:167], v[172:175], v[114:117]
	v_mfma_f32_16x16x32_bf16 v[102:105], v[156:159], v[180:183], v[102:105]
	v_mfma_f32_16x16x32_bf16 v[98:101], v[164:167], v[180:183], v[98:101]
	v_mfma_f32_16x16x32_bf16 v[86:89], v[156:159], v[188:191], v[86:89]
	v_mfma_f32_16x16x32_bf16 v[82:85], v[164:167], v[188:191], v[82:85]
	v_mfma_f32_16x16x32_bf16 v[70:73], v[156:159], v[196:199], v[70:73]
	v_mfma_f32_16x16x32_bf16 v[66:69], v[164:167], v[196:199], v[66:69]
	s_setprio 0
	s_barrier
	ds_read_b128 v[168:171], v135 offset:49152
	ds_read_b128 v[172:175], v135 offset:50176
	ds_read_b128 v[176:179], v135 offset:51200
	ds_read_b128 v[180:183], v135 offset:52224
	ds_read_b128 v[184:187], v135 offset:53248
	ds_read_b128 v[188:191], v135 offset:54272
	ds_read_b128 v[192:195], v135 offset:55296
	ds_read_b128 v[196:199], v135 offset:56320
	s_add_u32 s54, s54, 0x80
	s_addc_u32 s55, s55, 0
	s_mov_b32 m0, s65
	s_nop 0
	global_load_lds_dwordx4 v131, s[54:55]
	s_mov_b32 m0, s66
	s_nop 0
	global_load_lds_dwordx4 v133, s[54:55]
	s_add_u32 s54, s58, 0x80
	s_addc_u32 s55, s59, 0
	s_mov_b32 m0, s69
	s_nop 0
	global_load_lds_dwordx4 v131, s[54:55]
	s_mov_b32 m0, s70
	s_nop 0
	global_load_lds_dwordx4 v133, s[54:55]
	s_mov_b32 m0, s67
	s_nop 0
	global_load_lds_dwordx4 v130, s[52:53]
	s_mov_b32 m0, s68
	s_nop 0
	global_load_lds_dwordx4 v132, s[52:53]
	s_waitcnt vmcnt(8) lgkmcnt(0)
	s_barrier
	s_setprio 1
	v_mfma_f32_16x16x32_bf16 v[62:65], v[136:139], v[168:171], v[62:65]
	v_mfma_f32_16x16x32_bf16 v[58:61], v[144:147], v[168:171], v[58:61]
	v_mfma_f32_16x16x32_bf16 v[46:49], v[136:139], v[176:179], v[46:49]
	v_mfma_f32_16x16x32_bf16 v[42:45], v[144:147], v[176:179], v[42:45]
	v_mfma_f32_16x16x32_bf16 v[30:33], v[136:139], v[184:187], v[30:33]
	v_mfma_f32_16x16x32_bf16 v[26:29], v[144:147], v[184:187], v[26:29]
	v_mfma_f32_16x16x32_bf16 v[14:17], v[136:139], v[192:195], v[14:17]
	v_mfma_f32_16x16x32_bf16 v[10:13], v[144:147], v[192:195], v[10:13]
	v_mfma_f32_16x16x32_bf16 v[62:65], v[140:143], v[172:175], v[62:65]
	v_mfma_f32_16x16x32_bf16 v[58:61], v[148:151], v[172:175], v[58:61]
	v_mfma_f32_16x16x32_bf16 v[46:49], v[140:143], v[180:183], v[46:49]
	v_mfma_f32_16x16x32_bf16 v[42:45], v[148:151], v[180:183], v[42:45]
	v_mfma_f32_16x16x32_bf16 v[30:33], v[140:143], v[188:191], v[30:33]
	v_mfma_f32_16x16x32_bf16 v[26:29], v[148:151], v[188:191], v[26:29]
	v_mfma_f32_16x16x32_bf16 v[14:17], v[140:143], v[196:199], v[14:17]
	v_mfma_f32_16x16x32_bf16 v[10:13], v[148:151], v[196:199], v[10:13]
	v_mfma_f32_16x16x32_bf16 v[54:57], v[152:155], v[168:171], v[54:57]
	v_mfma_f32_16x16x32_bf16 v[50:53], v[160:163], v[168:171], v[50:53]
	v_mfma_f32_16x16x32_bf16 v[38:41], v[152:155], v[176:179], v[38:41]
	v_mfma_f32_16x16x32_bf16 v[34:37], v[160:163], v[176:179], v[34:37]
	v_mfma_f32_16x16x32_bf16 v[22:25], v[152:155], v[184:187], v[22:25]
	v_mfma_f32_16x16x32_bf16 v[18:21], v[160:163], v[184:187], v[18:21]
	v_mfma_f32_16x16x32_bf16 v[6:9], v[152:155], v[192:195], v[6:9]
	v_mfma_f32_16x16x32_bf16 v[2:5], v[160:163], v[192:195], v[2:5]
	v_mfma_f32_16x16x32_bf16 v[54:57], v[156:159], v[172:175], v[54:57]
	v_mfma_f32_16x16x32_bf16 v[50:53], v[164:167], v[172:175], v[50:53]
	v_mfma_f32_16x16x32_bf16 v[38:41], v[156:159], v[180:183], v[38:41]
	v_mfma_f32_16x16x32_bf16 v[34:37], v[164:167], v[180:183], v[34:37]
	v_mfma_f32_16x16x32_bf16 v[22:25], v[156:159], v[188:191], v[22:25]
	v_mfma_f32_16x16x32_bf16 v[18:21], v[164:167], v[188:191], v[18:21]
	v_mfma_f32_16x16x32_bf16 v[6:9], v[156:159], v[196:199], v[6:9]
	v_mfma_f32_16x16x32_bf16 v[2:5], v[164:167], v[196:199], v[2:5]
	s_setprio 0
	s_barrier
	s_add_i32 s51, s51, 2
	s_add_u32 s24, s24, 0x100
	s_addc_u32 s25, s25, 0
	s_add_u32 s26, s26, 0x100
	s_addc_u32 s27, s27, 0
	s_cmp_gt_u32 s51, 13
	s_cbranch_scc0 .LBB0_95
	s_and_b64 vcc, exec, s[46:47]
	s_cbranch_vccz .LBB0_98
	s_barrier

.LBB0_111:
	s_cmp_gt_i32 s83, 4
	s_mov_b64 s[4:5], -1
	s_cbranch_scc0 .LBB0_131
	s_add_i32 s0, s85, 7
	s_cmp_lt_u32 s0, 17
	s_cselect_b64 s[4:5], -1, 0
	s_and_b64 s[6:7], s[4:5], exec
	s_movk_i32 s0, 0xc00
	v_readlane_b32 s2, v254, 55
	s_cselect_b32 s38, s0, 0x600
	s_cmpk_lt_i32 s2, 0x180
	s_cselect_b32 s0, s2, 0
	s_ashr_i32 s3, s0, 31
	s_lshr_b32 s3, s3, 29
	s_add_i32 s3, s0, s3
	s_ashr_i32 s6, s3, 3
	s_and_b32 s3, s3, -8
	s_sub_i32 s0, s0, s3
	s_cmp_lt_i32 s0, 0
	s_cselect_b32 s3, 49, 48
	s_mul_i32 s0, s0, s3
	s_add_i32 s0, s0, s6
	s_ashr_i32 s3, s0, 31
	s_lshr_b32 s3, s3, 27
	s_add_i32 s6, s0, s3
	s_ashr_i32 s3, s6, 5
	s_lshl_b32 s7, s3, 3
	s_sub_i32 s3, 0x60, s7
	s_min_i32 s10, s3, 8
	s_abs_i32 s11, s10
	v_cvt_f32_u32_e32 v2, s11
	s_sub_i32 s21, 0, s11
	s_andn2_b32 s6, s6, 31
	s_sub_i32 s0, s0, s6
	v_rcp_iflag_f32_e32 v2, v2
	s_abs_i32 s20, s0
	s_xor_b32 s6, s0, s10
	s_ashr_i32 s6, s6, 31
	v_mul_f32_e32 v2, 0x4f7ffffe, v2
	v_cvt_u32_f32_e32 v2, v2
	v_mov_b32_e32 v0, v249
	s_movk_i32 s40, 0x400
	v_readfirstlane_b32 s22, v2
	s_mul_i32 s21, s21, s22
	s_mul_hi_u32 s21, s22, s21
	s_add_i32 s22, s22, s21
	s_mul_hi_u32 s21, s20, s22
	s_mul_i32 s22, s21, s11
	s_sub_i32 s20, s20, s22
	s_add_i32 s22, s21, 1
	s_sub_i32 s23, s20, s11
	s_cmp_ge_u32 s20, s11
	s_cselect_b32 s21, s22, s21
	s_cselect_b32 s20, s23, s20
	s_add_i32 s22, s21, 1
	s_cmp_ge_u32 s20, s11
	s_cselect_b32 s11, s22, s21
	s_xor_b32 s11, s11, s6
	s_sub_i32 s67, s11, s6
	s_mul_i32 s6, s67, s10
	s_sub_i32 s0, s0, s6
	s_add_i32 s52, s7, s0
	v_readfirstlane_b32 s3, v0
	s_cmpk_gt_i32 s2, 0x17f
	s_cbranch_scc1 .LBB0_130
	v_bfe_i32 v4, v0, 27, 1
	v_lshlrev_b32_e32 v2, 4, v0
	v_lshrrev_b32_e32 v4, 22, v4
	v_add_u32_e32 v4, v2, v4
	v_and_b32_e32 v4, 0xfffffc00, v4
	v_sub_u32_e32 v4, v2, v4
	v_lshrrev_b32_e32 v5, 4, v4
	s_sub_i32 s0, s85, 19
	v_ashrrev_i32_e32 v3, 31, v0
	v_bitop3_b32 v4, v5, v4, 32 bitop3:0x6c
	s_cmp_lt_u32 s0, 9
	s_mov_b32 s0, 0x11128000
	v_lshrrev_b32_e32 v3, 26, v3
	v_ashrrev_i32_e32 v6, 31, v4
	s_cselect_b32 s0, s0, 0xa128000
	s_mov_b32 s6, 0x1028000
	v_readlane_b32 s20, v254, 61
	v_add_u32_e32 v3, v0, v3
	v_lshrrev_b32_e32 v6, 26, v6
	s_cselect_b32 s6, s6, 0x1528000
	v_readlane_b32 s21, v254, 62
	s_add_u32 s0, s20, s0
	v_ashrrev_i32_e32 v3, 6, v3
	v_add_u32_e32 v6, v4, v6
	s_addc_u32 s10, s21, 0
	s_add_i32 s7, s85, -10
	v_lshlrev_b32_e32 v5, 3, v3
	v_ashrrev_i32_e32 v7, 6, v6
	v_and_b32_e32 v6, 0xc0, v6
	s_cmp_gt_u32 s7, 8
	v_and_b32_e32 v5, -16, v5
	v_lshlrev_b32_e32 v3, 5, v3
	v_sub_u32_e32 v4, v4, v6
	s_cselect_b32 s6, s6, 0xbe8000
	s_and_b64 s[4:5], s[4:5], exec
	v_add_u32_e32 v5, v7, v5
	v_and_b32_e32 v3, 32, v3
	v_ashrrev_i16_sdwa v4, v214, sext(v4) dst_sel:DWORD dst_unused:UNUSED_PAD src0_sel:DWORD src1_sel:BYTE_0
	s_cselect_b32 s4, 0x6e8000, s6
	v_add_u32_sdwa v3, v3, sext(v4) dst_sel:DWORD dst_unused:UNUSED_PAD src0_sel:DWORD src1_sel:WORD_0
	v_mul_lo_u32 v4, v5, s38
	s_add_u32 s11, s20, s4
	v_add_lshl_u32 v164, v3, v4, 1
	v_lshlrev_b32_e32 v4, 1, v5
	v_and_b32_e32 v5, 31, v5
	s_mov_b32 s4, 0x7fffffc0
	v_and_or_b32 v4, v4, s4, v5
	v_mul_lo_u32 v4, v4, s40
	v_add_u32_e32 v2, 0x2000, v2
	v_add_lshl_u32 v165, v4, v3, 1
	v_ashrrev_i32_e32 v3, 31, v2
	v_lshrrev_b32_e32 v3, 22, v3
	v_add_u32_e32 v3, v2, v3
	v_ashrrev_i32_e32 v3, 10, v3
	v_mul_i32_i24_e32 v4, 0x400, v3
	v_sub_u32_e32 v2, v2, v4
	v_lshrrev_b32_e32 v4, 4, v2
	v_bitop3_b32 v2, v4, v2, 32 bitop3:0x6c
	v_ashrrev_i32_e32 v5, 31, v2
	v_lshrrev_b32_e32 v5, 26, v5
	v_add_u32_e32 v5, v2, v5
	s_addc_u32 s28, s21, 0
	v_lshlrev_b32_e32 v4, 3, v3
	v_ashrrev_i32_e32 v6, 6, v5
	v_and_b32_e32 v5, 0xc0, v5
	s_ashr_i32 s39, s38, 31
	v_and_b32_e32 v4, -16, v4
	v_lshlrev_b32_e32 v3, 5, v3
	v_sub_u32_e32 v2, v2, v5
	s_lshl_b64 s[6:7], s[38:39], 9
	s_ashr_i32 s26, s52, 31
	v_add_u32_e32 v4, v6, v4
	v_and_b32_e32 v3, 32, v3
	v_ashrrev_i16_sdwa v2, v214, sext(v2) dst_sel:DWORD dst_unused:UNUSED_PAD src0_sel:DWORD src1_sel:BYTE_0
	s_mul_i32 s26, s6, s26
	s_mul_hi_u32 s27, s6, s52
	v_add_u32_sdwa v2, v3, sext(v2) dst_sel:DWORD dst_unused:UNUSED_PAD src0_sel:DWORD src1_sel:WORD_0
	v_mul_lo_u32 v3, v4, s38
	s_add_i32 s30, s27, s26
	s_lshr_b64 s[26:27], s[38:39], 23
	s_ashr_i32 s24, s3, 6
	v_add_lshl_u32 v166, v2, v3, 1
	v_lshlrev_b32_e32 v3, 1, v4
	v_and_b32_e32 v4, 31, v4
	s_ashr_i32 s41, s40, 31
	s_mul_i32 s26, s26, s52
	v_and_or_b32 v3, v3, s4, v4
	s_ashr_i32 s25, s3, 8
	s_lshl_b64 s[4:5], s[38:39], 8
	s_lshl_b64 s[20:21], s[40:41], 6
	s_lshl_b64 s[22:23], s[40:41], 9
	s_lshl_b32 s29, s24, 10
	s_add_i32 s30, s30, s26
	s_mul_i32 s26, s6, s52
	s_add_u32 s54, s0, s26
	s_addc_u32 s55, s10, s30
	s_ashr_i32 s26, s67, 31
	s_mul_i32 s26, s22, s26
	s_mul_hi_u32 s27, s22, s67
	s_add_i32 s30, s27, s26
	s_lshr_b64 s[26:27], s[40:41], 23
	s_mul_i32 s26, s26, s67
	s_add_i32 s30, s30, s26
	s_mul_i32 s26, s22, s67
	s_add_u32 s48, s11, s26
	s_addc_u32 s49, s28, s30
	s_add_i32 s29, s29, 0
	v_mul_lo_u32 v3, v3, s40
	s_add_i32 s30, s29, 0x10000
	s_add_i32 s31, s29, 0x12000
	v_add_lshl_u32 v167, v3, v2, 1
	s_mov_b32 m0, s30
	s_nop 0
	global_load_lds_dwordx4 v165, s[48:49]
	s_mov_b32 m0, s31
	s_nop 0
	global_load_lds_dwordx4 v167, s[48:49]
	s_add_u32 s38, s48, s20
	s_addc_u32 s39, s49, s21
	s_add_i32 s64, s29, 0x14000
	s_add_i32 s65, s29, 0x16000
	s_mov_b32 m0, s64
	s_nop 0
	global_load_lds_dwordx4 v165, s[38:39]
	s_mov_b32 m0, s65
	s_nop 0
	global_load_lds_dwordx4 v167, s[38:39]
	s_add_i32 s66, s29, 0x2000
	s_mov_b32 m0, s29
	s_nop 0
	global_load_lds_dwordx4 v164, s[54:55]
	s_mov_b32 m0, s66
	s_nop 0
	global_load_lds_dwordx4 v166, s[54:55]
	s_add_u32 s26, s54, s4
	s_addc_u32 s27, s55, s5
	s_add_i32 s68, s29, 0x4000
	s_add_i32 s69, s29, 0x6000
	s_mov_b32 m0, s68
	s_nop 0
	global_load_lds_dwordx4 v164, s[26:27]
	s_mov_b32 m0, s69
	s_nop 0
	global_load_lds_dwordx4 v166, s[26:27]
	s_cmp_eq_u32 s25, 1
	s_mov_b32 s2, s85
	s_cselect_b64 s[44:45], -1, 0
	s_cmp_lg_u32 s25, 1
	s_cbranch_scc1 .LBB0_115
	s_barrier
.LBB0_115:
	v_readlane_b32 s40, v254, 61
	v_readlane_b32 s41, v254, 62
	s_add_u32 s70, s40, 0x16de8000
	s_addc_u32 s71, s41, 0
	s_mul_i32 s27, s35, 0x36000
	s_mul_hi_i32 s26, s35, 0x36000
	s_add_u32 s72, s40, s27
	s_addc_u32 s73, s41, s26
	s_and_b32 s26, s24, 3
	s_lshl_b32 s74, s25, 6
	v_and_b32_e32 v2, 48, v0
	s_lshl_b32 s24, s25, 13
	v_lshlrev_b32_e32 v3, 6, v0
	s_movk_i32 s25, 0x3c0
	v_lshlrev_b32_e32 v0, 2, v0
	v_and_or_b32 v2, v3, s25, v2
	v_and_b32_e32 v0, 32, v0
	v_bitop3_b32 v3, v2, s24, v0 bitop3:0xde
	s_lshl_b32 s24, s26, 12
	v_bitop3_b32 v0, v2, s24, v0 bitop3:0xde
	s_add_u32 s24, s48, 0x80
	s_addc_u32 s25, s49, 0
	s_add_i32 s75, s29, 0x18000
	s_add_i32 s80, s29, 0x1a000
	s_waitcnt vmcnt(2)
	s_barrier
	s_mov_b32 m0, s75
	s_nop 0
	global_load_lds_dwordx4 v165, s[24:25]
	s_mov_b32 m0, s80
	s_nop 0
	global_load_lds_dwordx4 v167, s[24:25]
	s_add_u32 s24, s54, 0x80
	s_addc_u32 s25, s55, 0
	s_add_i32 s81, s29, 0x8000
	s_add_i32 s82, s29, 0xa000
	s_mov_b32 m0, s81
	s_nop 0
	global_load_lds_dwordx4 v164, s[24:25]
	s_mov_b32 m0, s82
	s_nop 0
	global_load_lds_dwordx4 v166, s[24:25]
	s_add_u32 s24, s38, 0x80
	s_addc_u32 s25, s39, 0
	s_add_i32 s83, s29, 0x1c000
	s_add_i32 s84, s29, 0x1e000
	s_mov_b32 m0, s83
	s_nop 0
	global_load_lds_dwordx4 v165, s[24:25]
	s_mov_b32 m0, s84
	s_nop 0
	global_load_lds_dwordx4 v167, s[24:25]
	s_waitcnt vmcnt(6)
	s_add_i32 s85, s29, 0xc000
	s_add_i32 s86, s29, 0xe000
	s_cmpk_lt_u32 s3, 0x100
	v_readlane_b32 s3, v254, 55
	v_mov_b32_e32 v2, 0
	s_cselect_b64 s[46:47], -1, 0
	s_lshl_b32 s87, s26, 6
	s_ashr_i32 s88, s74, 31
	s_ashr_i32 s89, s3, 31
	s_mov_b32 s3, 0
	v_add_u32_e32 v168, 0, v0
	v_add_u32_e32 v169, 0, v3
	v_mov_b32_e32 v3, v2
	v_mov_b32_e32 v4, v2
	v_mov_b32_e32 v5, v2
	v_mov_b32_e32 v6, v2
	v_mov_b32_e32 v7, v2
	v_mov_b32_e32 v8, v2
	v_mov_b32_e32 v9, v2
	v_mov_b32_e32 v10, v2
	v_mov_b32_e32 v11, v2
	v_mov_b32_e32 v12, v2
	v_mov_b32_e32 v13, v2
	v_mov_b32_e32 v14, v2
	v_mov_b32_e32 v15, v2
	v_mov_b32_e32 v16, v2
	v_mov_b32_e32 v17, v2
	v_mov_b32_e32 v18, v2
	v_mov_b32_e32 v19, v2
	v_mov_b32_e32 v20, v2
	v_mov_b32_e32 v21, v2
	v_mov_b32_e32 v22, v2
	v_mov_b32_e32 v23, v2
	v_mov_b32_e32 v24, v2
	v_mov_b32_e32 v25, v2
	v_mov_b32_e32 v26, v2
	v_mov_b32_e32 v27, v2
	v_mov_b32_e32 v28, v2
	v_mov_b32_e32 v29, v2
	v_mov_b32_e32 v30, v2
	v_mov_b32_e32 v31, v2
	v_mov_b32_e32 v32, v2
	v_mov_b32_e32 v33, v2
	v_mov_b32_e32 v34, v2
	v_mov_b32_e32 v35, v2
	v_mov_b32_e32 v36, v2
	v_mov_b32_e32 v37, v2
	v_mov_b32_e32 v38, v2
	v_mov_b32_e32 v39, v2
	v_mov_b32_e32 v40, v2
	v_mov_b32_e32 v41, v2
	v_mov_b32_e32 v42, v2
	v_mov_b32_e32 v43, v2
	v_mov_b32_e32 v44, v2
	v_mov_b32_e32 v45, v2
	v_mov_b32_e32 v46, v2
	v_mov_b32_e32 v47, v2
	v_mov_b32_e32 v48, v2
	v_mov_b32_e32 v49, v2
	v_mov_b32_e32 v50, v2
	v_mov_b32_e32 v51, v2
	v_mov_b32_e32 v52, v2
	v_mov_b32_e32 v53, v2
	v_mov_b32_e32 v54, v2
	v_mov_b32_e32 v55, v2
	v_mov_b32_e32 v56, v2
	v_mov_b32_e32 v57, v2
	v_mov_b32_e32 v58, v2
	v_mov_b32_e32 v59, v2
	v_mov_b32_e32 v60, v2
	v_mov_b32_e32 v61, v2
	s_waitcnt vmcnt(0)
	v_mov_b32_e32 v62, v2
	v_mov_b32_e32 v63, v2
	v_mov_b32_e32 v64, v2
	v_mov_b32_e32 v65, v2
	v_mov_b32_e32 v66, v2
	v_mov_b32_e32 v67, v2
	v_mov_b32_e32 v68, v2
	v_mov_b32_e32 v69, v2
	v_mov_b32_e32 v70, v2
	v_mov_b32_e32 v71, v2
	v_mov_b32_e32 v72, v2
	v_mov_b32_e32 v73, v2
	v_mov_b32_e32 v74, v2
	v_mov_b32_e32 v75, v2
	v_mov_b32_e32 v76, v2
	v_mov_b32_e32 v77, v2
	v_mov_b32_e32 v78, v2
	v_mov_b32_e32 v79, v2
	v_mov_b32_e32 v80, v2
	v_mov_b32_e32 v81, v2
	v_mov_b32_e32 v82, v2
	v_mov_b32_e32 v83, v2
	v_mov_b32_e32 v84, v2
	v_mov_b32_e32 v85, v2
	v_mov_b32_e32 v86, v2
	v_mov_b32_e32 v87, v2
	v_mov_b32_e32 v88, v2
	v_mov_b32_e32 v89, v2
	v_mov_b32_e32 v90, v2
	v_mov_b32_e32 v91, v2
	v_mov_b32_e32 v92, v2
	v_mov_b32_e32 v93, v2
	v_mov_b32_e32 v94, v2
	v_mov_b32_e32 v95, v2
	v_mov_b32_e32 v96, v2
	v_mov_b32_e32 v97, v2
	v_mov_b32_e32 v98, v2
	v_mov_b32_e32 v99, v2
	v_mov_b32_e32 v100, v2
	v_mov_b32_e32 v101, v2
	v_mov_b32_e32 v102, v2
	v_mov_b32_e32 v103, v2
	v_mov_b32_e32 v104, v2
	v_mov_b32_e32 v105, v2
	v_mov_b32_e32 v106, v2
	v_mov_b32_e32 v107, v2
	v_mov_b32_e32 v108, v2
	v_mov_b32_e32 v109, v2
	v_mov_b32_e32 v110, v2
	v_mov_b32_e32 v111, v2
	v_mov_b32_e32 v112, v2
	v_mov_b32_e32 v113, v2
	v_mov_b32_e32 v114, v2
	v_mov_b32_e32 v115, v2
	v_mov_b32_e32 v116, v2
	v_mov_b32_e32 v117, v2
	v_mov_b32_e32 v118, v2
	v_mov_b32_e32 v119, v2
	v_mov_b32_e32 v120, v2
	v_mov_b32_e32 v121, v2
	v_mov_b32_e32 v122, v2
	v_mov_b32_e32 v123, v2
	v_mov_b32_e32 v124, v2
	v_mov_b32_e32 v125, v2
	v_mov_b32_e32 v126, v2
	v_mov_b32_e32 v127, v2
	v_mov_b32_e32 v128, v2
	v_mov_b32_e32 v129, v2
	s_mov_b64 s[50:51], s[54:55]
	s_barrier
	s_branch .LBB0_117

.LBB0_122:
	s_add_u32 s56, s27, s54
	v_add_u32_e32 v0, 0x10000, v168
	s_addc_u32 s57, s53, s55
	ds_read_b128 v[130:133], v0
	ds_read_b128 v[134:137], v0 offset:1024
	ds_read_b128 v[138:141], v0 offset:2048
	ds_read_b128 v[142:145], v0 offset:3072
	v_add_u32_e32 v0, 0x14000, v168
	s_add_u32 s58, s48, s54
	ds_read_b128 v[146:149], v0
	ds_read_b128 v[150:153], v0 offset:1024
	ds_read_b128 v[154:157], v0 offset:2048
	ds_read_b128 v[158:161], v0 offset:3072
	s_addc_u32 s59, s49, s55
	s_add_u32 s58, s58, 0x100
	s_addc_u32 s59, s59, 0
	s_cmp_eq_u32 s91, 12
	s_cselect_b32 s60, s50, s56
	s_cselect_b32 s61, s51, s57
	s_cselect_b32 s58, s42, s58
	s_cselect_b32 s59, s43, s59
	s_add_u32 s56, s60, 0x80
	s_addc_u32 s57, s61, 0
	ds_read_b128 v[170:173], v169
	ds_read_b128 v[174:177], v169 offset:1024
	ds_read_b128 v[178:181], v169 offset:2048
	ds_read_b128 v[182:185], v169 offset:3072
	ds_read_b128 v[186:189], v169 offset:4096
	ds_read_b128 v[190:193], v169 offset:5120
	ds_read_b128 v[194:197], v169 offset:6144
	ds_read_b128 v[198:201], v169 offset:7168
	s_add_u32 s62, s76, s54
	s_addc_u32 s63, s90, s55
	s_mov_b32 m0, s85
	s_nop 0
	global_load_lds_dwordx4 v164, s[62:63]
	s_mov_b32 m0, s86
	s_nop 0
	global_load_lds_dwordx4 v166, s[62:63]
	s_waitcnt vmcnt(8) lgkmcnt(0)
	s_barrier
	s_setprio 1
	v_mfma_f32_16x16x32_bf16 v[126:129], v[130:133], v[170:173], v[126:129]
	v_mfma_f32_16x16x32_bf16 v[122:125], v[138:141], v[170:173], v[122:125]
	v_mfma_f32_16x16x32_bf16 v[118:121], v[130:133], v[178:181], v[118:121]
	v_mfma_f32_16x16x32_bf16 v[114:117], v[138:141], v[178:181], v[114:117]
	v_mfma_f32_16x16x32_bf16 v[110:113], v[130:133], v[186:189], v[110:113]
	v_mfma_f32_16x16x32_bf16 v[106:109], v[138:141], v[186:189], v[106:109]
	v_mfma_f32_16x16x32_bf16 v[102:105], v[130:133], v[194:197], v[102:105]
	v_mfma_f32_16x16x32_bf16 v[98:101], v[138:141], v[194:197], v[98:101]
	v_mfma_f32_16x16x32_bf16 v[126:129], v[134:137], v[174:177], v[126:129]
	v_mfma_f32_16x16x32_bf16 v[122:125], v[142:145], v[174:177], v[122:125]
	v_mfma_f32_16x16x32_bf16 v[118:121], v[134:137], v[182:185], v[118:121]
	v_mfma_f32_16x16x32_bf16 v[114:117], v[142:145], v[182:185], v[114:117]
	v_mfma_f32_16x16x32_bf16 v[110:113], v[134:137], v[190:193], v[110:113]
	v_mfma_f32_16x16x32_bf16 v[106:109], v[142:145], v[190:193], v[106:109]
	v_mfma_f32_16x16x32_bf16 v[102:105], v[134:137], v[198:201], v[102:105]
	v_mfma_f32_16x16x32_bf16 v[98:101], v[142:145], v[198:201], v[98:101]
	v_mfma_f32_16x16x32_bf16 v[94:97], v[146:149], v[170:173], v[94:97]
	v_mfma_f32_16x16x32_bf16 v[90:93], v[154:157], v[170:173], v[90:93]
	v_mfma_f32_16x16x32_bf16 v[86:89], v[146:149], v[178:181], v[86:89]
	v_mfma_f32_16x16x32_bf16 v[82:85], v[154:157], v[178:181], v[82:85]
	v_mfma_f32_16x16x32_bf16 v[78:81], v[146:149], v[186:189], v[78:81]
	v_mfma_f32_16x16x32_bf16 v[74:77], v[154:157], v[186:189], v[74:77]
	v_mfma_f32_16x16x32_bf16 v[70:73], v[146:149], v[194:197], v[70:73]
	v_mfma_f32_16x16x32_bf16 v[66:69], v[154:157], v[194:197], v[66:69]
	v_mfma_f32_16x16x32_bf16 v[94:97], v[150:153], v[174:177], v[94:97]
	v_mfma_f32_16x16x32_bf16 v[90:93], v[158:161], v[174:177], v[90:93]
	v_mfma_f32_16x16x32_bf16 v[86:89], v[150:153], v[182:185], v[86:89]
	v_mfma_f32_16x16x32_bf16 v[82:85], v[158:161], v[182:185], v[82:85]
	v_mfma_f32_16x16x32_bf16 v[78:81], v[150:153], v[190:193], v[78:81]
	v_mfma_f32_16x16x32_bf16 v[74:77], v[158:161], v[190:193], v[74:77]
	v_mfma_f32_16x16x32_bf16 v[70:73], v[150:153], v[198:201], v[70:73]
	v_mfma_f32_16x16x32_bf16 v[66:69], v[158:161], v[198:201], v[66:69]
	s_setprio 0
	s_barrier
	ds_read_b128 v[170:173], v169 offset:16384
	ds_read_b128 v[174:177], v169 offset:17408
	ds_read_b128 v[178:181], v169 offset:18432
	ds_read_b128 v[182:185], v169 offset:19456
	ds_read_b128 v[186:189], v169 offset:20480
	ds_read_b128 v[190:193], v169 offset:21504
	ds_read_b128 v[194:197], v169 offset:22528
	ds_read_b128 v[198:201], v169 offset:23552
	s_mov_b32 m0, s30
	s_nop 0
	global_load_lds_dwordx4 v165, s[58:59]
	s_mov_b32 m0, s31
	s_nop 0
	global_load_lds_dwordx4 v167, s[58:59]
	s_add_u32 s62, s58, s20
	s_addc_u32 s63, s59, s21
	s_mov_b32 m0, s64
	s_nop 0
	global_load_lds_dwordx4 v165, s[62:63]
	s_mov_b32 m0, s65
	s_nop 0
	global_load_lds_dwordx4 v167, s[62:63]
	s_nop 0
	s_mov_b32 m0, s29
	s_nop 0
	global_load_lds_dwordx4 v164, s[60:61]
	s_mov_b32 m0, s66
	s_nop 0
	global_load_lds_dwordx4 v166, s[60:61]
	s_waitcnt vmcnt(8) lgkmcnt(0)
	s_barrier
	s_setprio 1
	v_mfma_f32_16x16x32_bf16 v[62:65], v[130:133], v[170:173], v[62:65]
	v_mfma_f32_16x16x32_bf16 v[58:61], v[138:141], v[170:173], v[58:61]
	v_mfma_f32_16x16x32_bf16 v[54:57], v[130:133], v[178:181], v[54:57]
	v_mfma_f32_16x16x32_bf16 v[50:53], v[138:141], v[178:181], v[50:53]
	v_mfma_f32_16x16x32_bf16 v[46:49], v[130:133], v[186:189], v[46:49]
	v_mfma_f32_16x16x32_bf16 v[42:45], v[138:141], v[186:189], v[42:45]
	v_mfma_f32_16x16x32_bf16 v[38:41], v[130:133], v[194:197], v[38:41]
	v_mfma_f32_16x16x32_bf16 v[34:37], v[138:141], v[194:197], v[34:37]
	v_mfma_f32_16x16x32_bf16 v[62:65], v[134:137], v[174:177], v[62:65]
	v_mfma_f32_16x16x32_bf16 v[58:61], v[142:145], v[174:177], v[58:61]
	v_mfma_f32_16x16x32_bf16 v[54:57], v[134:137], v[182:185], v[54:57]
	v_mfma_f32_16x16x32_bf16 v[50:53], v[142:145], v[182:185], v[50:53]
	v_mfma_f32_16x16x32_bf16 v[46:49], v[134:137], v[190:193], v[46:49]
	v_mfma_f32_16x16x32_bf16 v[42:45], v[142:145], v[190:193], v[42:45]
	v_mfma_f32_16x16x32_bf16 v[38:41], v[134:137], v[198:201], v[38:41]
	v_mfma_f32_16x16x32_bf16 v[34:37], v[142:145], v[198:201], v[34:37]
	v_mfma_f32_16x16x32_bf16 v[30:33], v[146:149], v[170:173], v[30:33]
	v_mfma_f32_16x16x32_bf16 v[26:29], v[154:157], v[170:173], v[26:29]
	v_mfma_f32_16x16x32_bf16 v[22:25], v[146:149], v[178:181], v[22:25]
	v_mfma_f32_16x16x32_bf16 v[18:21], v[154:157], v[178:181], v[18:21]
	v_mfma_f32_16x16x32_bf16 v[14:17], v[146:149], v[186:189], v[14:17]
	v_mfma_f32_16x16x32_bf16 v[10:13], v[154:157], v[186:189], v[10:13]
	v_mfma_f32_16x16x32_bf16 v[6:9], v[146:149], v[194:197], v[6:9]
	v_mfma_f32_16x16x32_bf16 v[2:5], v[154:157], v[194:197], v[2:5]
	v_mfma_f32_16x16x32_bf16 v[30:33], v[150:153], v[174:177], v[30:33]
	v_mfma_f32_16x16x32_bf16 v[26:29], v[158:161], v[174:177], v[26:29]
	v_mfma_f32_16x16x32_bf16 v[22:25], v[150:153], v[182:185], v[22:25]
	v_mfma_f32_16x16x32_bf16 v[18:21], v[158:161], v[182:185], v[18:21]
	v_mfma_f32_16x16x32_bf16 v[14:17], v[150:153], v[190:193], v[14:17]
	v_mfma_f32_16x16x32_bf16 v[10:13], v[158:161], v[190:193], v[10:13]
	v_mfma_f32_16x16x32_bf16 v[6:9], v[150:153], v[198:201], v[6:9]
	v_mfma_f32_16x16x32_bf16 v[2:5], v[158:161], v[198:201], v[2:5]
	s_setprio 0
	s_barrier
	v_add_u32_e32 v0, 0x18000, v168
	ds_read_b128 v[130:133], v0
	ds_read_b128 v[134:137], v0 offset:1024
	ds_read_b128 v[138:141], v0 offset:2048
	ds_read_b128 v[142:145], v0 offset:3072
	v_add_u32_e32 v0, 0x1c000, v168
	ds_read_b128 v[146:149], v0
	ds_read_b128 v[150:153], v0 offset:1024
	ds_read_b128 v[154:157], v0 offset:2048
	ds_read_b128 v[158:161], v0 offset:3072
	ds_read_b128 v[170:173], v169 offset:32768
	ds_read_b128 v[174:177], v169 offset:33792
	ds_read_b128 v[178:181], v169 offset:34816
	ds_read_b128 v[182:185], v169 offset:35840
	ds_read_b128 v[186:189], v169 offset:36864
	ds_read_b128 v[190:193], v169 offset:37888
	ds_read_b128 v[194:197], v169 offset:38912
	ds_read_b128 v[198:201], v169 offset:39936
	s_add_u32 s60, s60, s4
	s_addc_u32 s61, s61, s5
	s_mov_b32 m0, s68
	s_nop 0
	global_load_lds_dwordx4 v164, s[60:61]
	s_mov_b32 m0, s69
	s_nop 0
	global_load_lds_dwordx4 v166, s[60:61]
	s_waitcnt vmcnt(8) lgkmcnt(0)
	s_barrier
	s_setprio 1
	v_mfma_f32_16x16x32_bf16 v[126:129], v[130:133], v[170:173], v[126:129]
	v_mfma_f32_16x16x32_bf16 v[122:125], v[138:141], v[170:173], v[122:125]
	v_mfma_f32_16x16x32_bf16 v[118:121], v[130:133], v[178:181], v[118:121]
	v_mfma_f32_16x16x32_bf16 v[114:117], v[138:141], v[178:181], v[114:117]
	v_mfma_f32_16x16x32_bf16 v[110:113], v[130:133], v[186:189], v[110:113]
	v_mfma_f32_16x16x32_bf16 v[106:109], v[138:141], v[186:189], v[106:109]
	v_mfma_f32_16x16x32_bf16 v[102:105], v[130:133], v[194:197], v[102:105]
	v_mfma_f32_16x16x32_bf16 v[98:101], v[138:141], v[194:197], v[98:101]
	v_mfma_f32_16x16x32_bf16 v[126:129], v[134:137], v[174:177], v[126:129]
	v_mfma_f32_16x16x32_bf16 v[122:125], v[142:145], v[174:177], v[122:125]
	v_mfma_f32_16x16x32_bf16 v[118:121], v[134:137], v[182:185], v[118:121]
	v_mfma_f32_16x16x32_bf16 v[114:117], v[142:145], v[182:185], v[114:117]
	v_mfma_f32_16x16x32_bf16 v[110:113], v[134:137], v[190:193], v[110:113]
	v_mfma_f32_16x16x32_bf16 v[106:109], v[142:145], v[190:193], v[106:109]
	v_mfma_f32_16x16x32_bf16 v[102:105], v[134:137], v[198:201], v[102:105]
	v_mfma_f32_16x16x32_bf16 v[98:101], v[142:145], v[198:201], v[98:101]
	v_mfma_f32_16x16x32_bf16 v[94:97], v[146:149], v[170:173], v[94:97]
	v_mfma_f32_16x16x32_bf16 v[90:93], v[154:157], v[170:173], v[90:93]
	v_mfma_f32_16x16x32_bf16 v[86:89], v[146:149], v[178:181], v[86:89]
	v_mfma_f32_16x16x32_bf16 v[82:85], v[154:157], v[178:181], v[82:85]
	v_mfma_f32_16x16x32_bf16 v[78:81], v[146:149], v[186:189], v[78:81]
	v_mfma_f32_16x16x32_bf16 v[74:77], v[154:157], v[186:189], v[74:77]
	v_mfma_f32_16x16x32_bf16 v[70:73], v[146:149], v[194:197], v[70:73]
	v_mfma_f32_16x16x32_bf16 v[66:69], v[154:157], v[194:197], v[66:69]
	v_mfma_f32_16x16x32_bf16 v[94:97], v[150:153], v[174:177], v[94:97]
	v_mfma_f32_16x16x32_bf16 v[90:93], v[158:161], v[174:177], v[90:93]
	v_mfma_f32_16x16x32_bf16 v[86:89], v[150:153], v[182:185], v[86:89]
	v_mfma_f32_16x16x32_bf16 v[82:85], v[158:161], v[182:185], v[82:85]
	v_mfma_f32_16x16x32_bf16 v[78:81], v[150:153], v[190:193], v[78:81]
	v_mfma_f32_16x16x32_bf16 v[74:77], v[158:161], v[190:193], v[74:77]
	v_mfma_f32_16x16x32_bf16 v[70:73], v[150:153], v[198:201], v[70:73]
	v_mfma_f32_16x16x32_bf16 v[66:69], v[158:161], v[198:201], v[66:69]
	s_setprio 0
	s_barrier
	ds_read_b128 v[170:173], v169 offset:49152
	ds_read_b128 v[174:177], v169 offset:50176
	ds_read_b128 v[178:181], v169 offset:51200
	ds_read_b128 v[182:185], v169 offset:52224
	ds_read_b128 v[186:189], v169 offset:53248
	ds_read_b128 v[190:193], v169 offset:54272
	ds_read_b128 v[194:197], v169 offset:55296
	ds_read_b128 v[198:201], v169 offset:56320
	s_add_u32 s58, s58, 0x80
	s_addc_u32 s59, s59, 0
	s_mov_b32 m0, s75
	s_nop 0
	global_load_lds_dwordx4 v165, s[58:59]
	s_mov_b32 m0, s80
	s_nop 0
	global_load_lds_dwordx4 v167, s[58:59]
	s_add_u32 s58, s62, 0x80
	s_addc_u32 s59, s63, 0
	s_mov_b32 m0, s83
	s_nop 0
	global_load_lds_dwordx4 v165, s[58:59]
	s_mov_b32 m0, s84
	s_nop 0
	global_load_lds_dwordx4 v167, s[58:59]
	s_mov_b32 m0, s81
	s_nop 0
	global_load_lds_dwordx4 v164, s[56:57]
	s_mov_b32 m0, s82
	s_nop 0
	global_load_lds_dwordx4 v166, s[56:57]
	s_waitcnt vmcnt(8) lgkmcnt(0)
	s_barrier
	s_setprio 1
	v_mfma_f32_16x16x32_bf16 v[62:65], v[130:133], v[170:173], v[62:65]
	v_mfma_f32_16x16x32_bf16 v[58:61], v[138:141], v[170:173], v[58:61]
	v_mfma_f32_16x16x32_bf16 v[54:57], v[130:133], v[178:181], v[54:57]
	v_mfma_f32_16x16x32_bf16 v[50:53], v[138:141], v[178:181], v[50:53]
	v_mfma_f32_16x16x32_bf16 v[46:49], v[130:133], v[186:189], v[46:49]
	v_mfma_f32_16x16x32_bf16 v[42:45], v[138:141], v[186:189], v[42:45]
	v_mfma_f32_16x16x32_bf16 v[38:41], v[130:133], v[194:197], v[38:41]
	v_mfma_f32_16x16x32_bf16 v[34:37], v[138:141], v[194:197], v[34:37]
	v_mfma_f32_16x16x32_bf16 v[62:65], v[134:137], v[174:177], v[62:65]
	v_mfma_f32_16x16x32_bf16 v[58:61], v[142:145], v[174:177], v[58:61]
	v_mfma_f32_16x16x32_bf16 v[54:57], v[134:137], v[182:185], v[54:57]
	v_mfma_f32_16x16x32_bf16 v[50:53], v[142:145], v[182:185], v[50:53]
	v_mfma_f32_16x16x32_bf16 v[46:49], v[134:137], v[190:193], v[46:49]
	v_mfma_f32_16x16x32_bf16 v[42:45], v[142:145], v[190:193], v[42:45]
	v_mfma_f32_16x16x32_bf16 v[38:41], v[134:137], v[198:201], v[38:41]
	v_mfma_f32_16x16x32_bf16 v[34:37], v[142:145], v[198:201], v[34:37]
	v_mfma_f32_16x16x32_bf16 v[30:33], v[146:149], v[170:173], v[30:33]
	v_mfma_f32_16x16x32_bf16 v[26:29], v[154:157], v[170:173], v[26:29]
	v_mfma_f32_16x16x32_bf16 v[22:25], v[146:149], v[178:181], v[22:25]
	v_mfma_f32_16x16x32_bf16 v[18:21], v[154:157], v[178:181], v[18:21]
	v_mfma_f32_16x16x32_bf16 v[14:17], v[146:149], v[186:189], v[14:17]
	v_mfma_f32_16x16x32_bf16 v[10:13], v[154:157], v[186:189], v[10:13]
	v_mfma_f32_16x16x32_bf16 v[6:9], v[146:149], v[194:197], v[6:9]
	v_mfma_f32_16x16x32_bf16 v[2:5], v[154:157], v[194:197], v[2:5]
	v_mfma_f32_16x16x32_bf16 v[30:33], v[150:153], v[174:177], v[30:33]
	v_mfma_f32_16x16x32_bf16 v[26:29], v[158:161], v[174:177], v[26:29]
	v_mfma_f32_16x16x32_bf16 v[22:25], v[150:153], v[182:185], v[22:25]
	v_mfma_f32_16x16x32_bf16 v[18:21], v[158:161], v[182:185], v[18:21]
	v_mfma_f32_16x16x32_bf16 v[14:17], v[150:153], v[190:193], v[14:17]
	v_mfma_f32_16x16x32_bf16 v[10:13], v[158:161], v[190:193], v[10:13]
	v_mfma_f32_16x16x32_bf16 v[6:9], v[150:153], v[198:201], v[6:9]
	v_mfma_f32_16x16x32_bf16 v[2:5], v[158:161], v[198:201], v[2:5]
	s_setprio 0
	s_barrier
	s_add_i32 s91, s91, 2
	s_add_u32 s54, s54, 0x100
	s_addc_u32 s55, s55, 0
	s_cmp_gt_u32 s91, 13
	s_cbranch_scc0 .LBB0_122
	s_and_b64 vcc, exec, s[46:47]
	s_cbranch_vccz .LBB0_125
	s_barrier

.LBB0_360:
	s_or_b64 exec, exec, s[4:5]
	v_readlane_b32 s0, v254, 58
	s_cmp_gt_i32 s0, 2
	s_mov_b64 s[6:7], -1
	s_waitcnt lgkmcnt(0)
	s_barrier
	s_cbranch_scc0 .LBB0_470
	v_readlane_b32 s22, v254, 55
	s_cmpk_lt_i32 s22, 0x240
	s_cselect_b32 s0, s22, 0
	s_ashr_i32 s3, s0, 31
	s_lshr_b32 s3, s3, 29
	s_add_i32 s3, s0, s3
	s_ashr_i32 s4, s3, 3
	s_and_b32 s3, s3, -8
	s_sub_i32 s0, s0, s3
	s_cmp_lt_i32 s0, 0
	s_movk_i32 s2, 0x49
	s_cselect_b32 s3, s2, 0x48
	s_mul_i32 s0, s0, s3
	s_add_i32 s3, s0, s4
	s_mul_hi_i32 s0, s3, 0x2aaaaaab
	s_lshr_b32 s4, s0, 31
	s_ashr_i32 s0, s0, 3
	s_add_i32 s4, s0, s4
	s_lshl_b32 s5, s4, 3
	s_sub_i32 s0, 0x60, s5
	s_min_i32 s6, s0, 8
	s_abs_i32 s7, s6
	v_cvt_f32_u32_e32 v2, s7
	s_sub_i32 s11, 0, s7
	s_mul_i32 s4, s4, 48
	s_sub_i32 s4, s3, s4
	v_rcp_iflag_f32_e32 v2, v2
	s_abs_i32 s10, s4
	s_xor_b32 s3, s4, s6
	s_ashr_i32 s3, s3, 31
	v_mul_f32_e32 v2, 0x4f7ffffe, v2
	v_cvt_u32_f32_e32 v2, v2
	v_mov_b32_e32 v0, v249
	v_writelane_b32 v254, s52, 61
	v_readfirstlane_b32 s20, v2
	s_mul_i32 s11, s11, s20
	s_mul_hi_u32 s11, s20, s11
	s_add_i32 s20, s20, s11
	s_mul_hi_u32 s11, s10, s20
	s_mul_i32 s20, s11, s7
	s_sub_i32 s10, s10, s20
	s_add_i32 s20, s11, 1
	s_sub_i32 s21, s10, s7
	s_cmp_ge_u32 s10, s7
	s_cselect_b32 s11, s20, s11
	s_cselect_b32 s10, s21, s10
	s_add_i32 s20, s11, 1
	s_cmp_ge_u32 s10, s7
	s_cselect_b32 s7, s20, s11
	s_xor_b32 s7, s7, s3
	s_sub_i32 s3, s7, s3
	s_mul_i32 s6, s3, s6
	s_sub_i32 s4, s4, s6
	s_add_i32 s11, s5, s4
	v_readfirstlane_b32 s0, v0
	s_movk_i32 s38, 0x100
	s_movk_i32 s40, 0x100
	s_cmpk_gt_i32 s22, 0x23f
	v_writelane_b32 v254, s53, 62
	s_cbranch_scc1 .LBB0_429
	v_bfe_i32 v4, v0, 27, 1
	v_lshlrev_b32_e32 v2, 4, v0
	v_lshrrev_b32_e32 v4, 22, v4
	v_add_u32_e32 v4, v2, v4
	v_and_b32_e32 v4, 0xfffffc00, v4
	v_sub_u32_e32 v4, v2, v4
	v_lshrrev_b32_e32 v5, 4, v4
	v_ashrrev_i32_e32 v3, 31, v0
	v_bitop3_b32 v4, v5, v4, 32 bitop3:0x6c
	v_lshrrev_b32_e32 v3, 26, v3
	v_ashrrev_i32_e32 v6, 31, v4
	v_add_u32_e32 v3, v0, v3
	v_lshrrev_b32_e32 v6, 26, v6
	v_ashrrev_i32_e32 v3, 6, v3
	v_add_u32_e32 v6, v4, v6
	v_lshlrev_b32_e32 v5, 3, v3
	v_ashrrev_i32_e32 v7, 6, v6
	v_and_b32_e32 v6, 0xc0, v6
	v_and_b32_e32 v5, -16, v5
	v_lshlrev_b32_e32 v3, 5, v3
	v_sub_u32_e32 v4, v4, v6
	v_add_u32_e32 v5, v7, v5
	v_and_b32_e32 v3, 32, v3
	v_ashrrev_i16_sdwa v4, v214, sext(v4) dst_sel:DWORD dst_unused:UNUSED_PAD src0_sel:DWORD src1_sel:BYTE_0
	v_add_u32_sdwa v3, v3, sext(v4) dst_sel:DWORD dst_unused:UNUSED_PAD src0_sel:DWORD src1_sel:WORD_0
	v_mul_lo_u32 v4, v5, s40
	v_add_lshl_u32 v150, v3, v4, 1
	v_lshlrev_b32_e32 v4, 1, v5
	v_and_b32_e32 v5, 31, v5
	s_mov_b32 s2, 0x7fffffc0
	v_and_or_b32 v4, v4, s2, v5
	s_add_u32 s94, s52, 0x15928000
	v_mul_lo_u32 v4, v4, s38
	v_add_u32_e32 v2, 0x2000, v2
	s_addc_u32 s95, s53, 0
	v_add_lshl_u32 v151, v4, v3, 1
	v_ashrrev_i32_e32 v3, 31, v2
	s_add_u32 s29, s52, 0xee8000
	v_lshrrev_b32_e32 v3, 22, v3
	s_addc_u32 s30, s53, 0
	v_add_u32_e32 v3, v2, v3
	s_ashr_i32 s41, s40, 31
	v_ashrrev_i32_e32 v3, 10, v3
	s_lshl_b64 s[6:7], s[40:41], 9
	s_ashr_i32 s26, s11, 31
	v_mul_i32_i24_e32 v4, 0x400, v3
	s_mul_i32 s26, s6, s26
	s_mul_hi_u32 s27, s6, s11
	v_sub_u32_e32 v2, v2, v4
	s_add_i32 s28, s27, s26
	s_lshr_b64 s[26:27], s[40:41], 23
	s_ashr_i32 s10, s0, 6
	v_lshrrev_b32_e32 v4, 4, v2
	s_ashr_i32 s39, s38, 31
	s_mul_i32 s26, s26, s11
	v_bitop3_b32 v2, v4, v2, 32 bitop3:0x6c
	s_ashr_i32 s24, s0, 8
	s_lshl_b64 s[4:5], s[40:41], 8
	s_lshl_b64 s[20:21], s[38:39], 6
	s_lshl_b64 s[22:23], s[38:39], 9
	s_lshl_b32 s25, s10, 10
	s_add_i32 s28, s28, s26
	s_mul_i32 s26, s6, s11
	v_ashrrev_i32_e32 v5, 31, v2
	s_add_u32 s42, s94, s26
	v_lshrrev_b32_e32 v5, 26, v5
	s_addc_u32 s43, s95, s28
	s_ashr_i32 s26, s3, 31
	v_add_u32_e32 v5, v2, v5
	s_mul_i32 s26, s22, s26
	s_mul_hi_u32 s27, s22, s3
	v_lshlrev_b32_e32 v4, 3, v3
	v_ashrrev_i32_e32 v6, 6, v5
	v_and_b32_e32 v5, 0xc0, v5
	s_add_i32 s28, s27, s26
	s_lshr_b64 s[26:27], s[38:39], 23
	v_and_b32_e32 v4, -16, v4
	v_lshlrev_b32_e32 v3, 5, v3
	v_sub_u32_e32 v2, v2, v5
	s_mul_i32 s26, s26, s3
	v_add_u32_e32 v4, v6, v4
	v_and_b32_e32 v3, 32, v3
	v_ashrrev_i16_sdwa v2, v214, sext(v2) dst_sel:DWORD dst_unused:UNUSED_PAD src0_sel:DWORD src1_sel:BYTE_0
	s_add_i32 s28, s28, s26
	s_mul_i32 s26, s22, s3
	v_add_u32_sdwa v2, v3, sext(v2) dst_sel:DWORD dst_unused:UNUSED_PAD src0_sel:DWORD src1_sel:WORD_0
	v_mul_lo_u32 v3, v4, s40
	s_add_u32 s44, s29, s26
	v_add_lshl_u32 v152, v2, v3, 1
	v_lshlrev_b32_e32 v3, 1, v4
	v_and_b32_e32 v4, 31, v4
	s_addc_u32 s45, s30, s28
	s_add_i32 s75, s25, 0
	v_and_or_b32 v3, v3, s2, v4
	s_add_i32 s78, s75, 0x10000
	s_add_i32 s79, s75, 0x12000
	v_mul_lo_u32 v3, v3, s38
	s_add_u32 s38, s44, s20
	v_add_lshl_u32 v153, v3, v2, 1
	s_mov_b32 m0, s78
	s_nop 0
	global_load_lds_dwordx4 v151, s[44:45]
	s_mov_b32 m0, s79
	s_nop 0
	global_load_lds_dwordx4 v153, s[44:45]
	s_addc_u32 s39, s45, s21
	s_add_i32 s80, s75, 0x14000
	s_add_i32 s81, s75, 0x16000
	s_add_i32 s82, s75, 0x2000
	s_mov_b32 m0, s80
	s_nop 0
	global_load_lds_dwordx4 v151, s[38:39]
	s_mov_b32 m0, s81
	s_nop 0
	global_load_lds_dwordx4 v153, s[38:39]
	s_add_u32 s26, s42, s4
	s_mov_b32 m0, s75
	s_nop 0
	global_load_lds_dwordx4 v150, s[42:43]
	s_mov_b32 m0, s82
	s_nop 0
	global_load_lds_dwordx4 v152, s[42:43]
	s_addc_u32 s27, s43, s5
	s_add_i32 s83, s75, 0x4000
	s_add_i32 s84, s75, 0x6000
	s_mov_b32 m0, s83
	s_nop 0
	global_load_lds_dwordx4 v150, s[26:27]
	s_mov_b32 m0, s84
	s_nop 0
	global_load_lds_dwordx4 v152, s[26:27]
	s_cmp_eq_u32 s24, 1
	v_writelane_b32 v255, s85, 1
	s_cselect_b64 s[26:27], -1, 0
	s_mov_b32 s76, s29
	s_mov_b32 s93, s30
	v_writelane_b32 v254, s26, 63
	s_cmp_lg_u32 s24, 1
	s_nop 0
	v_writelane_b32 v255, s27, 0
	s_cbranch_scc1 .LBB0_364
	s_barrier
.LBB0_364:
	s_add_u32 s48, s52, 0x11128000
	v_and_b32_e32 v2, 48, v0
	v_lshlrev_b32_e32 v3, 6, v0
	s_movk_i32 s2, 0x3c0
	v_lshlrev_b32_e32 v0, 2, v0
	s_addc_u32 s49, s53, 0
	s_and_b32 s10, s10, 3
	s_lshl_b32 s86, s24, 6
	s_lshl_b32 s24, s24, 13
	v_and_or_b32 v2, v3, s2, v2
	v_and_b32_e32 v0, 32, v0
	v_bitop3_b32 v3, v2, s24, v0 bitop3:0xde
	s_lshl_b32 s24, s10, 12
	v_bitop3_b32 v0, v2, s24, v0 bitop3:0xde
	s_add_u32 s24, s44, 0x80
	s_addc_u32 s25, s45, 0
	s_add_i32 s87, s75, 0x18000
	s_add_i32 s88, s75, 0x1a000
	s_waitcnt vmcnt(2)
	s_barrier
	s_mov_b32 m0, s87
	s_nop 0
	global_load_lds_dwordx4 v151, s[24:25]
	s_mov_b32 m0, s88
	s_nop 0
	global_load_lds_dwordx4 v153, s[24:25]
	s_add_u32 s24, s42, 0x80
	s_addc_u32 s25, s43, 0
	s_add_i32 s89, s75, 0x8000
	s_add_i32 s90, s75, 0xa000
	s_mov_b32 m0, s89
	s_nop 0
	global_load_lds_dwordx4 v150, s[24:25]
	s_mov_b32 m0, s90
	s_nop 0
	global_load_lds_dwordx4 v152, s[24:25]
	s_add_u32 s24, s38, 0x80
	s_addc_u32 s25, s39, 0
	s_add_i32 s91, s75, 0x1c000
	s_add_i32 s97, s75, 0x1e000
	s_mov_b32 m0, s91
	s_nop 0
	global_load_lds_dwordx4 v151, s[24:25]
	s_mov_b32 m0, s97
	s_nop 0
	global_load_lds_dwordx4 v153, s[24:25]
	s_waitcnt vmcnt(6)
	s_add_i32 s46, s75, 0xc000
	s_add_i32 s47, s75, 0xe000
	s_cmpk_lt_u32 s0, 0x100
	v_readlane_b32 s2, v254, 55
	s_cselect_b64 s[50:51], -1, 0
	s_lshl_b32 s0, s10, 6
	s_ashr_i32 s72, s96, 31
	s_ashr_i32 s73, s2, 31
	s_xor_b32 s74, s10, 15
	s_mov_b32 s85, 0
	v_add_u32_e32 v154, 0, v0
	v_add_u32_e32 v155, 0, v3
	s_mov_b64 s[52:53], s[42:43]
	s_barrier
	s_branch .LBB0_367

.LBB0_372:
	s_add_u32 s26, s42, s25
	s_addc_u32 s27, s43, 0
	s_add_u32 s30, s26, 0x100
	s_addc_u32 s31, s27, 0
	s_and_b64 s[26:27], s[56:57], exec
	s_cselect_b32 s65, s53, s31
	s_cselect_b32 s64, s52, s30
	s_add_u32 s26, s44, s25
	s_addc_u32 s27, s45, 0
	s_add_u32 s30, s26, 0x100
	s_addc_u32 s31, s27, 0
	s_add_u32 s58, s64, 0x80
	s_addc_u32 s59, s65, 0
	s_and_b64 s[26:27], s[56:57], exec
	s_cselect_b32 s67, s55, s31
	s_cselect_b32 s66, s54, s30
	s_add_u32 s25, s10, s25
	s_addc_u32 s26, s24, 0
	s_add_u32 s70, s25, 0x80
	s_addc_u32 s71, s26, 0
	v_add_u32_e32 v0, 0x10000, v154
	s_add_u32 s68, s66, s20
	ds_read_b128 v[38:41], v0
	ds_read_b128 v[42:45], v0 offset:1024
	ds_read_b128 v[50:53], v0 offset:2048
	ds_read_b128 v[54:57], v0 offset:3072
	v_add_u32_e32 v0, 0x14000, v154
	s_addc_u32 s69, s67, s21
	ds_read_b128 v[146:149], v0
	ds_read_b128 v[156:159], v0 offset:1024
	ds_read_b128 v[160:163], v0 offset:2048
	ds_read_b128 v[164:167], v0 offset:3072
	s_add_u32 s62, s64, s4
	s_addc_u32 s63, s65, s5
	s_add_u32 s60, s66, 0x80
	s_addc_u32 s61, s67, 0
	s_add_u32 s56, s68, 0x80
	s_addc_u32 s57, s69, 0
	ds_read_b128 v[168:171], v155
	ds_read_b128 v[172:175], v155 offset:1024
	ds_read_b128 v[176:179], v155 offset:2048
	ds_read_b128 v[202:205], v155 offset:3072
	ds_read_b128 v[206:209], v155 offset:4096
	ds_read_b128 v[216:219], v155 offset:5120
	ds_read_b128 v[220:223], v155 offset:6144
	ds_read_b128 v[224:227], v155 offset:7168
	s_mov_b32 m0, s46
	s_nop 0
	global_load_lds_dwordx4 v150, s[70:71]
	s_mov_b32 m0, s47
	s_nop 0
	global_load_lds_dwordx4 v152, s[70:71]
	s_waitcnt vmcnt(8) lgkmcnt(0)
	s_barrier
	s_setprio 1
	v_mfma_f32_16x16x32_bf16 v[142:145], v[38:41], v[168:171], v[142:145]
	v_mfma_f32_16x16x32_bf16 v[138:141], v[50:53], v[168:171], v[138:141]
	v_mfma_f32_16x16x32_bf16 v[126:129], v[38:41], v[176:179], v[126:129]
	v_mfma_f32_16x16x32_bf16 v[122:125], v[50:53], v[176:179], v[122:125]
	v_mfma_f32_16x16x32_bf16 v[110:113], v[38:41], v[206:209], v[110:113]
	v_mfma_f32_16x16x32_bf16 v[106:109], v[50:53], v[206:209], v[106:109]
	v_mfma_f32_16x16x32_bf16 v[94:97], v[38:41], v[220:223], v[94:97]
	v_mfma_f32_16x16x32_bf16 v[90:93], v[50:53], v[220:223], v[90:93]
	v_mfma_f32_16x16x32_bf16 v[142:145], v[42:45], v[172:175], v[142:145]
	v_mfma_f32_16x16x32_bf16 v[138:141], v[54:57], v[172:175], v[138:141]
	v_mfma_f32_16x16x32_bf16 v[126:129], v[42:45], v[202:205], v[126:129]
	v_mfma_f32_16x16x32_bf16 v[122:125], v[54:57], v[202:205], v[122:125]
	v_mfma_f32_16x16x32_bf16 v[110:113], v[42:45], v[216:219], v[110:113]
	v_mfma_f32_16x16x32_bf16 v[106:109], v[54:57], v[216:219], v[106:109]
	v_mfma_f32_16x16x32_bf16 v[94:97], v[42:45], v[224:227], v[94:97]
	v_mfma_f32_16x16x32_bf16 v[90:93], v[54:57], v[224:227], v[90:93]
	v_mfma_f32_16x16x32_bf16 v[134:137], v[146:149], v[168:171], v[134:137]
	v_mfma_f32_16x16x32_bf16 v[130:133], v[160:163], v[168:171], v[130:133]
	v_mfma_f32_16x16x32_bf16 v[118:121], v[146:149], v[176:179], v[118:121]
	v_mfma_f32_16x16x32_bf16 v[114:117], v[160:163], v[176:179], v[114:117]
	v_mfma_f32_16x16x32_bf16 v[102:105], v[146:149], v[206:209], v[102:105]
	v_mfma_f32_16x16x32_bf16 v[98:101], v[160:163], v[206:209], v[98:101]
	v_mfma_f32_16x16x32_bf16 v[86:89], v[146:149], v[220:223], v[86:89]
	v_mfma_f32_16x16x32_bf16 v[82:85], v[160:163], v[220:223], v[82:85]
	v_mfma_f32_16x16x32_bf16 v[134:137], v[156:159], v[172:175], v[134:137]
	v_mfma_f32_16x16x32_bf16 v[130:133], v[164:167], v[172:175], v[130:133]
	v_mfma_f32_16x16x32_bf16 v[118:121], v[156:159], v[202:205], v[118:121]
	v_mfma_f32_16x16x32_bf16 v[114:117], v[164:167], v[202:205], v[114:117]
	v_mfma_f32_16x16x32_bf16 v[102:105], v[156:159], v[216:219], v[102:105]
	v_mfma_f32_16x16x32_bf16 v[98:101], v[164:167], v[216:219], v[98:101]
	v_mfma_f32_16x16x32_bf16 v[86:89], v[156:159], v[224:227], v[86:89]
	v_mfma_f32_16x16x32_bf16 v[82:85], v[164:167], v[224:227], v[82:85]
	s_setprio 0
	s_barrier
	ds_read_b128 v[168:171], v155 offset:16384
	ds_read_b128 v[172:175], v155 offset:17408
	ds_read_b128 v[176:179], v155 offset:18432
	ds_read_b128 v[202:205], v155 offset:19456
	ds_read_b128 v[206:209], v155 offset:20480
	ds_read_b128 v[216:219], v155 offset:21504
	ds_read_b128 v[220:223], v155 offset:22528
	ds_read_b128 v[224:227], v155 offset:23552
	s_mov_b32 m0, s78
	s_nop 0
	global_load_lds_dwordx4 v151, s[66:67]
	s_mov_b32 m0, s79
	s_nop 0
	global_load_lds_dwordx4 v153, s[66:67]
	s_nop 0
	s_mov_b32 m0, s80
	s_nop 0
	global_load_lds_dwordx4 v151, s[68:69]
	s_mov_b32 m0, s81
	s_nop 0
	global_load_lds_dwordx4 v153, s[68:69]
	s_nop 0
	s_mov_b32 m0, s75
	s_nop 0
	global_load_lds_dwordx4 v150, s[64:65]
	s_mov_b32 m0, s82
	s_nop 0
	global_load_lds_dwordx4 v152, s[64:65]
	s_waitcnt vmcnt(8) lgkmcnt(0)
	s_barrier
	s_setprio 1
	v_mfma_f32_16x16x32_bf16 v[78:81], v[38:41], v[168:171], v[78:81]
	v_mfma_f32_16x16x32_bf16 v[74:77], v[50:53], v[168:171], v[74:77]
	v_mfma_f32_16x16x32_bf16 v[62:65], v[38:41], v[176:179], v[62:65]
	v_mfma_f32_16x16x32_bf16 v[58:61], v[50:53], v[176:179], v[58:61]
	v_mfma_f32_16x16x32_bf16 v[30:33], v[38:41], v[206:209], v[30:33]
	v_mfma_f32_16x16x32_bf16 v[26:29], v[50:53], v[206:209], v[26:29]
	v_mfma_f32_16x16x32_bf16 v[14:17], v[38:41], v[220:223], v[14:17]
	v_mfma_f32_16x16x32_bf16 v[10:13], v[50:53], v[220:223], v[10:13]
	v_mfma_f32_16x16x32_bf16 v[78:81], v[42:45], v[172:175], v[78:81]
	v_mfma_f32_16x16x32_bf16 v[74:77], v[54:57], v[172:175], v[74:77]
	v_mfma_f32_16x16x32_bf16 v[62:65], v[42:45], v[202:205], v[62:65]
	v_mfma_f32_16x16x32_bf16 v[58:61], v[54:57], v[202:205], v[58:61]
	v_mfma_f32_16x16x32_bf16 v[30:33], v[42:45], v[216:219], v[30:33]
	v_mfma_f32_16x16x32_bf16 v[26:29], v[54:57], v[216:219], v[26:29]
	v_mfma_f32_16x16x32_bf16 v[14:17], v[42:45], v[224:227], v[14:17]
	v_mfma_f32_16x16x32_bf16 v[10:13], v[54:57], v[224:227], v[10:13]
	v_mfma_f32_16x16x32_bf16 v[46:49], v[146:149], v[176:179], v[46:49]
	v_mfma_f32_16x16x32_bf16 v[34:37], v[160:163], v[176:179], v[34:37]
	v_mfma_f32_16x16x32_bf16 v[22:25], v[146:149], v[206:209], v[22:25]
	v_mfma_f32_16x16x32_bf16 v[18:21], v[160:163], v[206:209], v[18:21]
	v_mfma_f32_16x16x32_bf16 v[6:9], v[146:149], v[220:223], v[6:9]
	v_mfma_f32_16x16x32_bf16 v[2:5], v[160:163], v[220:223], v[2:5]
	v_mfma_f32_16x16x32_bf16 v[38:41], v[146:149], v[168:171], v[70:73]
	v_mfma_f32_16x16x32_bf16 v[42:45], v[160:163], v[168:171], v[66:69]
	v_mfma_f32_16x16x32_bf16 v[46:49], v[156:159], v[202:205], v[46:49]
	v_mfma_f32_16x16x32_bf16 v[34:37], v[164:167], v[202:205], v[34:37]
	v_mfma_f32_16x16x32_bf16 v[22:25], v[156:159], v[216:219], v[22:25]
	v_mfma_f32_16x16x32_bf16 v[18:21], v[164:167], v[216:219], v[18:21]
	v_mfma_f32_16x16x32_bf16 v[6:9], v[156:159], v[224:227], v[6:9]
	v_mfma_f32_16x16x32_bf16 v[2:5], v[164:167], v[224:227], v[2:5]
	v_mfma_f32_16x16x32_bf16 v[38:41], v[156:159], v[172:175], v[38:41]
	v_mfma_f32_16x16x32_bf16 v[42:45], v[164:167], v[172:175], v[42:45]
	s_setprio 0
	s_barrier
	v_add_u32_e32 v0, 0x18000, v154
	ds_read_b128 v[50:53], v0
	ds_read_b128 v[54:57], v0 offset:1024
	ds_read_b128 v[66:69], v0 offset:2048
	ds_read_b128 v[70:73], v0 offset:3072
	v_add_u32_e32 v0, 0x1c000, v154
	ds_read_b128 v[146:149], v0
	ds_read_b128 v[156:159], v0 offset:1024
	ds_read_b128 v[160:163], v0 offset:2048
	ds_read_b128 v[164:167], v0 offset:3072
	ds_read_b128 v[168:171], v155 offset:32768
	ds_read_b128 v[172:175], v155 offset:33792
	ds_read_b128 v[176:179], v155 offset:34816
	ds_read_b128 v[202:205], v155 offset:35840
	ds_read_b128 v[206:209], v155 offset:36864
	ds_read_b128 v[216:219], v155 offset:37888
	ds_read_b128 v[220:223], v155 offset:38912
	ds_read_b128 v[224:227], v155 offset:39936
	s_mov_b32 m0, s83
	s_nop 0
	global_load_lds_dwordx4 v150, s[62:63]
	s_mov_b32 m0, s84
	s_nop 0
	global_load_lds_dwordx4 v152, s[62:63]
	s_waitcnt vmcnt(8) lgkmcnt(0)
	s_barrier
	s_setprio 1
	v_mfma_f32_16x16x32_bf16 v[142:145], v[50:53], v[168:171], v[142:145]
	v_mfma_f32_16x16x32_bf16 v[138:141], v[66:69], v[168:171], v[138:141]
	v_mfma_f32_16x16x32_bf16 v[126:129], v[50:53], v[176:179], v[126:129]
	v_mfma_f32_16x16x32_bf16 v[122:125], v[66:69], v[176:179], v[122:125]
	v_mfma_f32_16x16x32_bf16 v[110:113], v[50:53], v[206:209], v[110:113]
	v_mfma_f32_16x16x32_bf16 v[106:109], v[66:69], v[206:209], v[106:109]
	v_mfma_f32_16x16x32_bf16 v[94:97], v[50:53], v[220:223], v[94:97]
	v_mfma_f32_16x16x32_bf16 v[90:93], v[66:69], v[220:223], v[90:93]
	v_mfma_f32_16x16x32_bf16 v[142:145], v[54:57], v[172:175], v[142:145]
	v_mfma_f32_16x16x32_bf16 v[138:141], v[70:73], v[172:175], v[138:141]
	v_mfma_f32_16x16x32_bf16 v[126:129], v[54:57], v[202:205], v[126:129]
	v_mfma_f32_16x16x32_bf16 v[122:125], v[70:73], v[202:205], v[122:125]
	v_mfma_f32_16x16x32_bf16 v[110:113], v[54:57], v[216:219], v[110:113]
	v_mfma_f32_16x16x32_bf16 v[106:109], v[70:73], v[216:219], v[106:109]
	v_mfma_f32_16x16x32_bf16 v[94:97], v[54:57], v[224:227], v[94:97]
	v_mfma_f32_16x16x32_bf16 v[90:93], v[70:73], v[224:227], v[90:93]
	v_mfma_f32_16x16x32_bf16 v[134:137], v[146:149], v[168:171], v[134:137]
	v_mfma_f32_16x16x32_bf16 v[130:133], v[160:163], v[168:171], v[130:133]
	v_mfma_f32_16x16x32_bf16 v[118:121], v[146:149], v[176:179], v[118:121]
	v_mfma_f32_16x16x32_bf16 v[114:117], v[160:163], v[176:179], v[114:117]
	v_mfma_f32_16x16x32_bf16 v[102:105], v[146:149], v[206:209], v[102:105]
	v_mfma_f32_16x16x32_bf16 v[98:101], v[160:163], v[206:209], v[98:101]
	v_mfma_f32_16x16x32_bf16 v[86:89], v[146:149], v[220:223], v[86:89]
	v_mfma_f32_16x16x32_bf16 v[82:85], v[160:163], v[220:223], v[82:85]
	v_mfma_f32_16x16x32_bf16 v[134:137], v[156:159], v[172:175], v[134:137]
	v_mfma_f32_16x16x32_bf16 v[130:133], v[164:167], v[172:175], v[130:133]
	v_mfma_f32_16x16x32_bf16 v[118:121], v[156:159], v[202:205], v[118:121]
	v_mfma_f32_16x16x32_bf16 v[114:117], v[164:167], v[202:205], v[114:117]
	v_mfma_f32_16x16x32_bf16 v[102:105], v[156:159], v[216:219], v[102:105]
	v_mfma_f32_16x16x32_bf16 v[98:101], v[164:167], v[216:219], v[98:101]
	v_mfma_f32_16x16x32_bf16 v[86:89], v[156:159], v[224:227], v[86:89]
	v_mfma_f32_16x16x32_bf16 v[82:85], v[164:167], v[224:227], v[82:85]
	s_setprio 0
	s_barrier
	ds_read_b128 v[168:171], v155 offset:49152
	ds_read_b128 v[172:175], v155 offset:50176
	ds_read_b128 v[176:179], v155 offset:51200
	ds_read_b128 v[202:205], v155 offset:52224
	ds_read_b128 v[206:209], v155 offset:53248
	ds_read_b128 v[216:219], v155 offset:54272
	ds_read_b128 v[220:223], v155 offset:55296
	ds_read_b128 v[224:227], v155 offset:56320
	s_mov_b32 m0, s87
	s_nop 0
	global_load_lds_dwordx4 v151, s[60:61]
	s_mov_b32 m0, s88
	s_nop 0
	global_load_lds_dwordx4 v153, s[60:61]
	s_nop 0
	s_mov_b32 m0, s91
	s_nop 0
	global_load_lds_dwordx4 v151, s[56:57]
	s_mov_b32 m0, s97
	s_nop 0
	global_load_lds_dwordx4 v153, s[56:57]
	s_nop 0
	s_mov_b32 m0, s89
	s_nop 0
	global_load_lds_dwordx4 v150, s[58:59]
	s_mov_b32 m0, s90
	s_nop 0
	global_load_lds_dwordx4 v152, s[58:59]
	s_waitcnt vmcnt(8) lgkmcnt(0)
	s_barrier
	s_setprio 1
	v_mfma_f32_16x16x32_bf16 v[78:81], v[50:53], v[168:171], v[78:81]
	v_mfma_f32_16x16x32_bf16 v[74:77], v[66:69], v[168:171], v[74:77]
	v_mfma_f32_16x16x32_bf16 v[62:65], v[50:53], v[176:179], v[62:65]
	v_mfma_f32_16x16x32_bf16 v[58:61], v[66:69], v[176:179], v[58:61]
	v_mfma_f32_16x16x32_bf16 v[30:33], v[50:53], v[206:209], v[30:33]
	v_mfma_f32_16x16x32_bf16 v[26:29], v[66:69], v[206:209], v[26:29]
	v_mfma_f32_16x16x32_bf16 v[14:17], v[50:53], v[220:223], v[14:17]
	v_mfma_f32_16x16x32_bf16 v[10:13], v[66:69], v[220:223], v[10:13]
	v_mfma_f32_16x16x32_bf16 v[78:81], v[54:57], v[172:175], v[78:81]
	v_mfma_f32_16x16x32_bf16 v[74:77], v[70:73], v[172:175], v[74:77]
	v_mfma_f32_16x16x32_bf16 v[62:65], v[54:57], v[202:205], v[62:65]
	v_mfma_f32_16x16x32_bf16 v[58:61], v[70:73], v[202:205], v[58:61]
	v_mfma_f32_16x16x32_bf16 v[30:33], v[54:57], v[216:219], v[30:33]
	v_mfma_f32_16x16x32_bf16 v[26:29], v[70:73], v[216:219], v[26:29]
	v_mfma_f32_16x16x32_bf16 v[14:17], v[54:57], v[224:227], v[14:17]
	v_mfma_f32_16x16x32_bf16 v[10:13], v[70:73], v[224:227], v[10:13]
	v_mfma_f32_16x16x32_bf16 v[38:41], v[146:149], v[168:171], v[38:41]
	v_mfma_f32_16x16x32_bf16 v[70:73], v[156:159], v[172:175], v[38:41]
	v_mfma_f32_16x16x32_bf16 v[38:41], v[160:163], v[168:171], v[42:45]
	v_mfma_f32_16x16x32_bf16 v[66:69], v[164:167], v[172:175], v[38:41]
	v_mfma_f32_16x16x32_bf16 v[38:41], v[146:149], v[176:179], v[46:49]
	v_mfma_f32_16x16x32_bf16 v[34:37], v[160:163], v[176:179], v[34:37]
	v_mfma_f32_16x16x32_bf16 v[22:25], v[146:149], v[206:209], v[22:25]
	v_mfma_f32_16x16x32_bf16 v[18:21], v[160:163], v[206:209], v[18:21]
	v_mfma_f32_16x16x32_bf16 v[6:9], v[146:149], v[220:223], v[6:9]
	v_mfma_f32_16x16x32_bf16 v[2:5], v[160:163], v[220:223], v[2:5]
	v_mfma_f32_16x16x32_bf16 v[46:49], v[156:159], v[202:205], v[38:41]
	v_mfma_f32_16x16x32_bf16 v[34:37], v[164:167], v[202:205], v[34:37]
	v_mfma_f32_16x16x32_bf16 v[22:25], v[156:159], v[216:219], v[22:25]
	v_mfma_f32_16x16x32_bf16 v[18:21], v[164:167], v[216:219], v[18:21]
	v_mfma_f32_16x16x32_bf16 v[6:9], v[156:159], v[224:227], v[6:9]
	v_mfma_f32_16x16x32_bf16 v[2:5], v[164:167], v[224:227], v[2:5]
	s_setprio 0
	s_barrier
	s_movk_i32 s25, 0x100
	s_andn2_b64 vcc, exec, s[40:41]
	s_mov_b64 s[56:57], -1
	s_mov_b64 s[40:41], 0
	s_cbranch_vccz .LBB0_372
	s_and_b64 vcc, exec, s[50:51]
	s_cbranch_vccz .LBB0_375
	s_barrier

.LBB0_429:
	v_readlane_b32 s21, v254, 55
	s_cmpk_lt_i32 s21, 0x380
	s_cselect_b32 s0, s21, 0
	s_ashr_i32 s3, s0, 31
	s_lshr_b32 s3, s3, 29
	s_add_i32 s3, s0, s3
	s_ashr_i32 s4, s3, 3
	s_and_b32 s3, s3, -8
	s_sub_i32 s0, s0, s3
	s_cmp_lt_i32 s0, 0
	s_movk_i32 s2, 0x71
	s_cselect_b32 s3, s2, 0x70
	s_mul_i32 s0, s0, s3
	s_add_i32 s0, s0, s4
	s_ashr_i32 s3, s0, 31
	s_lshr_b32 s3, s3, 26
	s_add_i32 s3, s0, s3
	s_ashr_i32 s4, s3, 6
	s_lshl_b32 s4, s4, 3
	s_sub_i32 s5, 0x70, s4
	s_min_i32 s5, s5, 8
	s_abs_i32 s6, s5
	v_cvt_f32_u32_e32 v2, s6
	s_sub_i32 s10, 0, s6
	s_andn2_b32 s3, s3, 63
	s_sub_i32 s0, s0, s3
	v_rcp_iflag_f32_e32 v2, v2
	s_abs_i32 s7, s0
	s_xor_b32 s3, s0, s5
	s_ashr_i32 s3, s3, 31
	v_mul_f32_e32 v2, 0x4f7ffffe, v2
	v_cvt_u32_f32_e32 v2, v2
	v_mov_b32_e32 v0, v249
	s_movk_i32 s38, 0x80
	v_readfirstlane_b32 s11, v2
	s_mul_i32 s10, s10, s11
	s_mul_hi_u32 s10, s11, s10
	s_add_i32 s11, s11, s10
	s_mul_hi_u32 s10, s7, s11
	s_mul_i32 s11, s10, s6
	s_sub_i32 s7, s7, s11
	s_add_i32 s11, s10, 1
	s_sub_i32 s20, s7, s6
	s_cmp_ge_u32 s7, s6
	s_cselect_b32 s10, s11, s10
	s_cselect_b32 s7, s20, s7
	s_add_i32 s11, s10, 1
	s_cmp_ge_u32 s7, s6
	s_cselect_b32 s6, s11, s10
	s_xor_b32 s6, s6, s3
	s_sub_i32 s73, s6, s3
	s_mul_i32 s3, s73, s5
	s_sub_i32 s0, s0, s3
	s_add_i32 s74, s4, s0
	v_readfirstlane_b32 s50, v0
	s_movk_i32 s40, 0x80
	s_cmpk_gt_i32 s21, 0x37f
	s_cbranch_scc1 .LBB0_469
	v_bfe_i32 v4, v0, 27, 1
	v_lshlrev_b32_e32 v2, 4, v0
	v_lshrrev_b32_e32 v4, 22, v4
	v_add_u32_e32 v4, v2, v4
	v_and_b32_e32 v4, 0xfffffc00, v4
	v_sub_u32_e32 v4, v2, v4
	v_lshrrev_b32_e32 v5, 4, v4
	v_ashrrev_i32_e32 v3, 31, v0
	v_bitop3_b32 v4, v5, v4, 32 bitop3:0x6c
	v_lshrrev_b32_e32 v3, 26, v3
	v_ashrrev_i32_e32 v6, 31, v4
	v_add_u32_e32 v3, v0, v3
	v_lshrrev_b32_e32 v6, 26, v6
	v_ashrrev_i32_e32 v3, 6, v3
	v_add_u32_e32 v6, v4, v6
	v_lshlrev_b32_e32 v5, 3, v3
	v_ashrrev_i32_e32 v7, 6, v6
	v_and_b32_e32 v6, 0xc0, v6
	v_and_b32_e32 v5, -16, v5
	v_lshlrev_b32_e32 v3, 5, v3
	v_sub_u32_e32 v4, v4, v6
	v_add_u32_e32 v5, v7, v5
	v_and_b32_e32 v3, 32, v3
	v_ashrrev_i16_sdwa v4, v214, sext(v4) dst_sel:DWORD dst_unused:UNUSED_PAD src0_sel:DWORD src1_sel:BYTE_0
	v_add_u32_sdwa v3, v3, sext(v4) dst_sel:DWORD dst_unused:UNUSED_PAD src0_sel:DWORD src1_sel:WORD_0
	v_mul_lo_u32 v4, v5, s40
	v_add_lshl_u32 v148, v3, v4, 1
	v_lshlrev_b32_e32 v4, 1, v5
	v_and_b32_e32 v5, 31, v5
	s_mov_b32 s2, 0x7fffffc0
	v_and_or_b32 v4, v4, s2, v5
	v_mul_lo_u32 v4, v4, s38
	v_add_u32_e32 v2, 0x2000, v2
	s_add_u32 s0, s52, 0x16528000
	v_add_lshl_u32 v149, v4, v3, 1
	v_ashrrev_i32_e32 v3, 31, v2
	s_addc_u32 s3, s53, 0
	v_lshrrev_b32_e32 v3, 22, v3
	s_add_u32 s10, s52, 0xfa8000
	v_add_u32_e32 v3, v2, v3
	s_addc_u32 s11, s53, 0
	v_ashrrev_i32_e32 v3, 10, v3
	s_ashr_i32 s41, s40, 31
	v_mul_i32_i24_e32 v4, 0x400, v3
	s_lshl_b64 s[6:7], s[40:41], 9
	s_ashr_i32 s24, s74, 31
	v_sub_u32_e32 v2, v2, v4
	s_mul_i32 s24, s6, s24
	s_mul_hi_u32 s25, s6, s74
	v_lshrrev_b32_e32 v4, 4, v2
	s_add_i32 s27, s25, s24
	s_lshr_b64 s[24:25], s[40:41], 23
	s_ashr_i32 s48, s50, 6
	v_bitop3_b32 v2, v4, v2, 32 bitop3:0x6c
	s_ashr_i32 s39, s38, 31
	s_mul_i32 s24, s24, s74
	v_ashrrev_i32_e32 v5, 31, v2
	s_ashr_i32 s49, s50, 8
	s_lshl_b64 s[4:5], s[40:41], 8
	s_lshl_b64 s[20:21], s[38:39], 6
	s_lshl_b64 s[22:23], s[38:39], 9
	s_lshl_b32 s26, s48, 10
	s_add_i32 s27, s27, s24
	s_mul_i32 s24, s6, s74
	v_lshrrev_b32_e32 v5, 26, v5
	s_add_u32 s58, s0, s24
	v_add_u32_e32 v5, v2, v5
	s_addc_u32 s59, s3, s27
	s_ashr_i32 s24, s73, 31
	v_lshlrev_b32_e32 v4, 3, v3
	v_ashrrev_i32_e32 v6, 6, v5
	v_and_b32_e32 v5, 0xc0, v5
	s_mul_i32 s24, s22, s24
	s_mul_hi_u32 s25, s22, s73
	v_and_b32_e32 v4, -16, v4
	v_lshlrev_b32_e32 v3, 5, v3
	v_sub_u32_e32 v2, v2, v5
	s_add_i32 s27, s25, s24
	s_lshr_b64 s[24:25], s[38:39], 23
	v_add_u32_e32 v4, v6, v4
	v_and_b32_e32 v3, 32, v3
	v_ashrrev_i16_sdwa v2, v214, sext(v2) dst_sel:DWORD dst_unused:UNUSED_PAD src0_sel:DWORD src1_sel:BYTE_0
	s_mul_i32 s24, s24, s73
	v_add_u32_sdwa v2, v3, sext(v2) dst_sel:DWORD dst_unused:UNUSED_PAD src0_sel:DWORD src1_sel:WORD_0
	v_mul_lo_u32 v3, v4, s40
	s_add_i32 s27, s27, s24
	s_mul_i32 s24, s22, s73
	v_add_lshl_u32 v150, v2, v3, 1
	v_lshlrev_b32_e32 v3, 1, v4
	v_and_b32_e32 v4, 31, v4
	s_add_u32 s42, s10, s24
	v_and_or_b32 v3, v3, s2, v4
	s_addc_u32 s43, s11, s27
	s_add_i32 s24, s26, 0
	v_mul_lo_u32 v3, v3, s38
	s_add_i32 s25, s24, 0x10000
	s_add_i32 s26, s24, 0x12000
	v_add_lshl_u32 v151, v3, v2, 1
	s_mov_b32 m0, s25
	s_nop 0
	global_load_lds_dwordx4 v149, s[42:43]
	s_mov_b32 m0, s26
	s_nop 0
	global_load_lds_dwordx4 v151, s[42:43]
	s_add_u32 s38, s42, s20
	s_addc_u32 s39, s43, s21
	s_add_i32 s27, s24, 0x14000
	s_add_i32 s28, s24, 0x16000
	s_mov_b32 m0, s27
	s_nop 0
	global_load_lds_dwordx4 v149, s[38:39]
	s_mov_b32 m0, s28
	s_nop 0
	global_load_lds_dwordx4 v151, s[38:39]
	s_add_i32 s29, s24, 0x2000
	s_mov_b32 m0, s24
	s_nop 0
	global_load_lds_dwordx4 v148, s[58:59]
	s_mov_b32 m0, s29
	s_nop 0
	global_load_lds_dwordx4 v150, s[58:59]
	s_add_u32 s40, s58, s4
	s_addc_u32 s41, s59, s5
	s_add_i32 s30, s24, 0x4000
	s_add_i32 s31, s24, 0x6000
	s_mov_b32 m0, s30
	s_nop 0
	global_load_lds_dwordx4 v148, s[40:41]
	s_mov_b32 m0, s31
	s_nop 0
	global_load_lds_dwordx4 v150, s[40:41]
	s_cmp_eq_u32 s49, 1
	s_mov_b32 s71, s77
	v_mov_b32_e32 v250, 1
	s_cselect_b64 s[44:45], -1, 0
	s_cmp_lg_u32 s49, 1
	s_cbranch_scc1 .LBB0_432
	s_barrier
.LBB0_432:
	s_add_u32 s46, s52, 0xa128000
	v_and_b32_e32 v2, 48, v0
	v_lshlrev_b32_e32 v3, 6, v0
	s_movk_i32 s2, 0x3c0
	v_lshlrev_b32_e32 v0, 2, v0
	s_addc_u32 s47, s53, 0
	s_and_b32 s51, s48, 3
	s_lshl_b32 s40, s49, 13
	v_and_or_b32 v2, v3, s2, v2
	v_and_b32_e32 v0, 32, v0
	s_lshl_b32 s60, s49, 6
	v_bitop3_b32 v3, v2, s40, v0 bitop3:0xde
	s_lshl_b32 s40, s51, 12
	v_bitop3_b32 v0, v2, s40, v0 bitop3:0xde
	s_add_u32 s40, s42, 0x80
	s_addc_u32 s41, s43, 0
	s_add_i32 s61, s24, 0x18000
	s_add_i32 s62, s24, 0x1a000
	s_waitcnt vmcnt(2)
	s_barrier
	s_mov_b32 m0, s61
	s_nop 0
	global_load_lds_dwordx4 v149, s[40:41]
	s_mov_b32 m0, s62
	s_nop 0
	global_load_lds_dwordx4 v151, s[40:41]
	s_add_u32 s40, s58, 0x80
	s_addc_u32 s41, s59, 0
	s_add_i32 s63, s24, 0x8000
	s_add_i32 s64, s24, 0xa000
	s_add_u32 s38, s38, 0x80
	s_mov_b32 m0, s63
	s_nop 0
	global_load_lds_dwordx4 v148, s[40:41]
	s_mov_b32 m0, s64
	s_nop 0
	global_load_lds_dwordx4 v150, s[40:41]
	s_addc_u32 s39, s39, 0
	s_add_i32 s65, s24, 0x1c000
	s_add_i32 s66, s24, 0x1e000
	s_add_i32 s67, s24, 0xc000
	s_add_i32 s68, s24, 0xe000
	s_mov_b32 m0, s65
	s_nop 0
	global_load_lds_dwordx4 v149, s[38:39]
	s_mov_b32 m0, s66
	s_nop 0
	global_load_lds_dwordx4 v151, s[38:39]
	s_cmpk_lt_u32 s50, 0x100
	v_readlane_b32 s2, v254, 55
	s_cselect_b64 s[48:49], -1, 0
	s_and_b32 s38, s50, 64
	s_lshl_b32 s69, s51, 6
	s_ashr_i32 s70, s96, 31
	s_ashr_i32 s40, s2, 31
	s_cmp_eq_u32 s38, 0
	s_cselect_b64 s[50:51], -1, 0
	v_readlane_b32 s76, v254, 10
	s_waitcnt vmcnt(6)
	s_and_b64 s[38:39], s[50:51], exec
	v_readlane_b32 s82, v254, 16
	v_readlane_b32 s83, v254, 17
	v_readlane_b32 s77, v254, 11
	s_cselect_b32 s53, s83, 0
	s_cselect_b32 s52, s82, 0
	s_add_u32 s54, s96, s2
	s_addc_u32 s55, s70, s40
	v_add_u32_e32 v152, 0, v0
	v_add_u32_e32 v153, 0, v3
	s_mov_b64 s[56:57], s[58:59]
	s_mov_b32 s77, s71
	s_barrier
	v_readlane_b32 s78, v254, 12
	v_readlane_b32 s79, v254, 13
	v_readlane_b32 s80, v254, 14
	v_readlane_b32 s81, v254, 15
	s_branch .LBB0_435

.LBB0_439:
	v_add_u32_e32 v0, 0x10000, v152
	ds_read_b128 v[2:5], v0
	ds_read_b128 v[6:9], v0 offset:1024
	ds_read_b128 v[10:13], v0 offset:2048
	ds_read_b128 v[14:17], v0 offset:3072
	v_add_u32_e32 v0, 0x14000, v152
	ds_read_b128 v[18:21], v0
	ds_read_b128 v[22:25], v0 offset:1024
	ds_read_b128 v[26:29], v0 offset:2048
	ds_read_b128 v[30:33], v0 offset:3072
	s_add_u32 s58, s58, s4
	s_addc_u32 s59, s59, s5
	s_add_u32 s40, s56, 0x80
	s_addc_u32 s41, s57, 0
	ds_read_b128 v[34:37], v153
	ds_read_b128 v[38:41], v153 offset:1024
	ds_read_b128 v[42:45], v153 offset:2048
	ds_read_b128 v[46:49], v153 offset:3072
	ds_read_b128 v[50:53], v153 offset:4096
	ds_read_b128 v[54:57], v153 offset:5120
	ds_read_b128 v[58:61], v153 offset:6144
	s_waitcnt vmcnt(0)
	ds_read_b128 v[62:65], v153 offset:7168
	s_add_u32 s58, s58, 0x80
	s_addc_u32 s59, s59, 0
	s_mov_b32 m0, s67
	s_nop 0
	global_load_lds_dwordx4 v148, s[58:59]
	s_mov_b32 m0, s68
	s_nop 0
	global_load_lds_dwordx4 v150, s[58:59]
	s_waitcnt vmcnt(8) lgkmcnt(0)
	s_barrier
	s_setprio 1
	s_waitcnt lgkmcnt(0)
	v_mfma_f32_16x16x32_bf16 v[66:69], v[2:5], v[34:37], 0
	v_mfma_f32_16x16x32_bf16 v[70:73], v[10:13], v[34:37], 0
	v_mfma_f32_16x16x32_bf16 v[74:77], v[2:5], v[42:45], 0
	v_mfma_f32_16x16x32_bf16 v[78:81], v[10:13], v[42:45], 0
	s_waitcnt vmcnt(0)
	v_mfma_f32_16x16x32_bf16 v[82:85], v[2:5], v[50:53], 0
	v_mfma_f32_16x16x32_bf16 v[86:89], v[10:13], v[50:53], 0
	v_mfma_f32_16x16x32_bf16 v[90:93], v[2:5], v[58:61], 0
	v_mfma_f32_16x16x32_bf16 v[94:97], v[10:13], v[58:61], 0
	v_mfma_f32_16x16x32_bf16 v[66:69], v[6:9], v[38:41], v[66:69]
	v_mfma_f32_16x16x32_bf16 v[70:73], v[14:17], v[38:41], v[70:73]
	v_mfma_f32_16x16x32_bf16 v[74:77], v[6:9], v[46:49], v[74:77]
	v_mfma_f32_16x16x32_bf16 v[78:81], v[14:17], v[46:49], v[78:81]
	v_mfma_f32_16x16x32_bf16 v[82:85], v[6:9], v[54:57], v[82:85]
	v_mfma_f32_16x16x32_bf16 v[86:89], v[14:17], v[54:57], v[86:89]
	v_mfma_f32_16x16x32_bf16 v[90:93], v[6:9], v[62:65], v[90:93]
	v_mfma_f32_16x16x32_bf16 v[98:101], v[14:17], v[62:65], v[94:97]
	v_mfma_f32_16x16x32_bf16 v[94:97], v[18:21], v[34:37], 0
	v_mfma_f32_16x16x32_bf16 v[34:37], v[26:29], v[34:37], 0
	v_mfma_f32_16x16x32_bf16 v[102:105], v[22:25], v[38:41], v[94:97]
	v_mfma_f32_16x16x32_bf16 v[34:37], v[30:33], v[38:41], v[34:37]
	v_mfma_f32_16x16x32_bf16 v[38:41], v[18:21], v[42:45], 0
	v_mfma_f32_16x16x32_bf16 v[42:45], v[26:29], v[42:45], 0
	v_mfma_f32_16x16x32_bf16 v[38:41], v[22:25], v[46:49], v[38:41]
	v_mfma_f32_16x16x32_bf16 v[42:45], v[30:33], v[46:49], v[42:45]
	v_mfma_f32_16x16x32_bf16 v[46:49], v[18:21], v[50:53], 0
	v_mfma_f32_16x16x32_bf16 v[50:53], v[26:29], v[50:53], 0
	v_mfma_f32_16x16x32_bf16 v[46:49], v[22:25], v[54:57], v[46:49]
	v_mfma_f32_16x16x32_bf16 v[50:53], v[30:33], v[54:57], v[50:53]
	v_mfma_f32_16x16x32_bf16 v[54:57], v[18:21], v[58:61], 0
	v_mfma_f32_16x16x32_bf16 v[58:61], v[26:29], v[58:61], 0
	v_mfma_f32_16x16x32_bf16 v[54:57], v[22:25], v[62:65], v[54:57]
	v_mfma_f32_16x16x32_bf16 v[58:61], v[30:33], v[62:65], v[58:61]
	s_setprio 0
	s_barrier
	ds_read_b128 v[62:65], v153 offset:16384
	ds_read_b128 v[94:97], v153 offset:17408
	ds_read_b128 v[106:109], v153 offset:18432
	ds_read_b128 v[110:113], v153 offset:19456
	ds_read_b128 v[114:117], v153 offset:20480
	ds_read_b128 v[118:121], v153 offset:21504
	ds_read_b128 v[122:125], v153 offset:22528
	ds_read_b128 v[126:129], v153 offset:23552
	s_mov_b32 m0, s25
	s_nop 0
	global_load_lds_dwordx4 v149, s[42:43]
	s_mov_b32 m0, s26
	s_nop 0
	global_load_lds_dwordx4 v151, s[42:43]
	s_add_u32 s58, s42, s20
	s_addc_u32 s59, s43, s21
	s_mov_b32 m0, s27
	s_nop 0
	global_load_lds_dwordx4 v149, s[58:59]
	s_mov_b32 m0, s28
	s_nop 0
	global_load_lds_dwordx4 v151, s[58:59]
	s_nop 0
	s_mov_b32 m0, s24
	s_nop 0
	global_load_lds_dwordx4 v148, s[56:57]
	s_mov_b32 m0, s29
	s_nop 0
	global_load_lds_dwordx4 v150, s[56:57]
	s_waitcnt vmcnt(8) lgkmcnt(0)
	s_barrier
	s_setprio 1
	v_mfma_f32_16x16x32_bf16 v[130:133], v[2:5], v[62:65], 0
	v_mfma_f32_16x16x32_bf16 v[154:157], v[6:9], v[94:97], v[130:133]
	v_mfma_f32_16x16x32_bf16 v[130:133], v[10:13], v[62:65], 0
	v_mfma_f32_16x16x32_bf16 v[158:161], v[14:17], v[94:97], v[130:133]
	v_mfma_f32_16x16x32_bf16 v[130:133], v[2:5], v[106:109], 0
	v_mfma_f32_16x16x32_bf16 v[162:165], v[6:9], v[110:113], v[130:133]
	v_mfma_f32_16x16x32_bf16 v[130:133], v[10:13], v[106:109], 0
	v_mfma_f32_16x16x32_bf16 v[166:169], v[14:17], v[110:113], v[130:133]
	v_mfma_f32_16x16x32_bf16 v[130:133], v[2:5], v[114:117], 0
	v_mfma_f32_16x16x32_bf16 v[2:5], v[2:5], v[122:125], 0
	v_mfma_f32_16x16x32_bf16 v[170:173], v[6:9], v[118:121], v[130:133]
	v_mfma_f32_16x16x32_bf16 v[2:5], v[6:9], v[126:129], v[2:5]
	v_mfma_f32_16x16x32_bf16 v[6:9], v[10:13], v[122:125], 0
	v_mfma_f32_16x16x32_bf16 v[130:133], v[10:13], v[114:117], 0
	v_mfma_f32_16x16x32_bf16 v[6:9], v[14:17], v[126:129], v[6:9]
	v_mfma_f32_16x16x32_bf16 v[174:177], v[14:17], v[118:121], v[130:133]
	v_mfma_f32_16x16x32_bf16 v[10:13], v[18:21], v[62:65], 0
	v_mfma_f32_16x16x32_bf16 v[202:205], v[22:25], v[94:97], v[10:13]
	v_mfma_f32_16x16x32_bf16 v[10:13], v[26:29], v[62:65], 0
	v_mfma_f32_16x16x32_bf16 v[206:209], v[30:33], v[94:97], v[10:13]
	v_mfma_f32_16x16x32_bf16 v[10:13], v[18:21], v[106:109], 0
	v_mfma_f32_16x16x32_bf16 v[216:219], v[22:25], v[110:113], v[10:13]
	v_mfma_f32_16x16x32_bf16 v[10:13], v[26:29], v[106:109], 0
	v_mfma_f32_16x16x32_bf16 v[220:223], v[30:33], v[110:113], v[10:13]
	v_mfma_f32_16x16x32_bf16 v[10:13], v[18:21], v[114:117], 0
	v_mfma_f32_16x16x32_bf16 v[224:227], v[22:25], v[118:121], v[10:13]
	v_mfma_f32_16x16x32_bf16 v[10:13], v[26:29], v[114:117], 0
	v_mfma_f32_16x16x32_bf16 v[228:231], v[30:33], v[118:121], v[10:13]
	v_mfma_f32_16x16x32_bf16 v[10:13], v[18:21], v[122:125], 0
	v_mfma_f32_16x16x32_bf16 v[18:21], v[22:25], v[126:129], v[10:13]
	v_mfma_f32_16x16x32_bf16 v[10:13], v[26:29], v[122:125], 0
	v_mfma_f32_16x16x32_bf16 v[22:25], v[30:33], v[126:129], v[10:13]
	s_setprio 0
	s_barrier
	v_add_u32_e32 v0, 0x18000, v152
	s_nop 3
	ds_read_b128 v[10:13], v0
	ds_read_b128 v[14:17], v0 offset:1024
	ds_read_b128 v[26:29], v0 offset:2048
	ds_read_b128 v[30:33], v0 offset:3072
	v_add_u32_e32 v0, 0x1c000, v152
	ds_read_b128 v[232:235], v0
	ds_read_b128 v[236:239], v0 offset:1024
	ds_read_b128 v[240:243], v0 offset:2048
	ds_read_b128 v[244:247], v0 offset:3072
	ds_read_b128 v[62:65], v153 offset:32768
	ds_read_b128 v[114:117], v153 offset:33792
	ds_read_b128 v[198:201], v153 offset:34816
	ds_read_b128 v[182:185], v153 offset:35840
	ds_read_b128 v[190:193], v153 offset:36864
	ds_read_b128 v[194:197], v153 offset:37888
	ds_read_b128 v[186:189], v153 offset:38912
	ds_read_b128 v[178:181], v153 offset:39936
	s_add_u32 s78, s56, s4
	s_addc_u32 s79, s57, s5
	s_mov_b32 m0, s30
	s_nop 0
	global_load_lds_dwordx4 v148, s[78:79]
	s_mov_b32 m0, s31
	s_nop 0
	global_load_lds_dwordx4 v150, s[78:79]
	s_waitcnt vmcnt(8) lgkmcnt(0)
	s_barrier
	s_setprio 1
	v_mfma_f32_16x16x32_bf16 v[66:69], v[10:13], v[62:65], v[66:69]
	v_mfma_f32_16x16x32_bf16 v[142:145], v[14:17], v[114:117], v[66:69]
	v_mfma_f32_16x16x32_bf16 v[66:69], v[26:29], v[62:65], v[70:73]
	v_mfma_f32_16x16x32_bf16 v[138:141], v[30:33], v[114:117], v[66:69]
	v_mfma_f32_16x16x32_bf16 v[66:69], v[10:13], v[198:201], v[74:77]
	v_mfma_f32_16x16x32_bf16 v[126:129], v[14:17], v[182:185], v[66:69]
	v_mfma_f32_16x16x32_bf16 v[66:69], v[26:29], v[198:201], v[78:81]
	v_mfma_f32_16x16x32_bf16 v[122:125], v[30:33], v[182:185], v[66:69]
	v_mfma_f32_16x16x32_bf16 v[66:69], v[10:13], v[190:193], v[82:85]
	v_mfma_f32_16x16x32_bf16 v[110:113], v[14:17], v[194:197], v[66:69]
	v_mfma_f32_16x16x32_bf16 v[66:69], v[26:29], v[190:193], v[86:89]
	v_mfma_f32_16x16x32_bf16 v[106:109], v[30:33], v[194:197], v[66:69]
	v_mfma_f32_16x16x32_bf16 v[66:69], v[10:13], v[186:189], v[90:93]
	v_mfma_f32_16x16x32_bf16 v[94:97], v[14:17], v[178:181], v[66:69]
	v_mfma_f32_16x16x32_bf16 v[66:69], v[26:29], v[186:189], v[98:101]
	v_mfma_f32_16x16x32_bf16 v[90:93], v[30:33], v[178:181], v[66:69]
	v_mfma_f32_16x16x32_bf16 v[34:37], v[240:243], v[62:65], v[34:37]
	v_mfma_f32_16x16x32_bf16 v[130:133], v[244:247], v[114:117], v[34:37]
	v_mfma_f32_16x16x32_bf16 v[34:37], v[232:235], v[198:201], v[38:41]
	v_mfma_f32_16x16x32_bf16 v[66:69], v[232:235], v[62:65], v[102:105]
	v_mfma_f32_16x16x32_bf16 v[118:121], v[236:239], v[182:185], v[34:37]
	v_mfma_f32_16x16x32_bf16 v[34:37], v[240:243], v[198:201], v[42:45]
	v_mfma_f32_16x16x32_bf16 v[134:137], v[236:239], v[114:117], v[66:69]
	v_mfma_f32_16x16x32_bf16 v[114:117], v[244:247], v[182:185], v[34:37]
	v_mfma_f32_16x16x32_bf16 v[34:37], v[232:235], v[190:193], v[46:49]
	v_mfma_f32_16x16x32_bf16 v[102:105], v[236:239], v[194:197], v[34:37]
	v_mfma_f32_16x16x32_bf16 v[34:37], v[240:243], v[190:193], v[50:53]
	v_mfma_f32_16x16x32_bf16 v[98:101], v[244:247], v[194:197], v[34:37]
	v_mfma_f32_16x16x32_bf16 v[34:37], v[232:235], v[186:189], v[54:57]
	v_mfma_f32_16x16x32_bf16 v[86:89], v[236:239], v[178:181], v[34:37]
	v_mfma_f32_16x16x32_bf16 v[34:37], v[240:243], v[186:189], v[58:61]
	v_mfma_f32_16x16x32_bf16 v[82:85], v[244:247], v[178:181], v[34:37]
	s_setprio 0
	s_barrier
	s_nop 4
	ds_read_b128 v[34:37], v153 offset:49152
	ds_read_b128 v[38:41], v153 offset:50176
	ds_read_b128 v[50:53], v153 offset:51200
	ds_read_b128 v[178:181], v153 offset:52224
	ds_read_b128 v[182:185], v153 offset:53248
	ds_read_b128 v[186:189], v153 offset:54272
	ds_read_b128 v[190:193], v153 offset:55296
	ds_read_b128 v[194:197], v153 offset:56320
	s_add_u32 s78, s42, 0x80
	s_addc_u32 s79, s43, 0
	s_mov_b32 m0, s61
	s_nop 0
	global_load_lds_dwordx4 v149, s[78:79]
	s_mov_b32 m0, s62
	s_nop 0
	global_load_lds_dwordx4 v151, s[78:79]
	s_add_u32 s58, s58, 0x80
	s_addc_u32 s59, s59, 0
	s_mov_b32 m0, s65
	s_nop 0
	global_load_lds_dwordx4 v149, s[58:59]
	s_mov_b32 m0, s66
	s_nop 0
	global_load_lds_dwordx4 v151, s[58:59]
	s_mov_b32 m0, s63
	s_nop 0
	global_load_lds_dwordx4 v148, s[40:41]
	s_mov_b32 m0, s64
	s_nop 0
	global_load_lds_dwordx4 v150, s[40:41]
	s_waitcnt vmcnt(8) lgkmcnt(0)
	s_barrier
	s_setprio 1
	v_mfma_f32_16x16x32_bf16 v[42:45], v[10:13], v[34:37], v[154:157]
	v_mfma_f32_16x16x32_bf16 v[78:81], v[14:17], v[38:41], v[42:45]
	v_mfma_f32_16x16x32_bf16 v[42:45], v[26:29], v[34:37], v[158:161]
	v_mfma_f32_16x16x32_bf16 v[74:77], v[30:33], v[38:41], v[42:45]
	v_mfma_f32_16x16x32_bf16 v[42:45], v[10:13], v[50:53], v[162:165]
	v_mfma_f32_16x16x32_bf16 v[62:65], v[14:17], v[178:181], v[42:45]
	v_mfma_f32_16x16x32_bf16 v[42:45], v[26:29], v[50:53], v[166:169]
	v_mfma_f32_16x16x32_bf16 v[58:61], v[30:33], v[178:181], v[42:45]
	v_mfma_f32_16x16x32_bf16 v[42:45], v[10:13], v[182:185], v[170:173]
	v_mfma_f32_16x16x32_bf16 v[2:5], v[10:13], v[190:193], v[2:5]
	v_mfma_f32_16x16x32_bf16 v[46:49], v[14:17], v[186:189], v[42:45]
	v_mfma_f32_16x16x32_bf16 v[42:45], v[26:29], v[182:185], v[174:177]
	v_mfma_f32_16x16x32_bf16 v[14:17], v[14:17], v[194:197], v[2:5]
	v_mfma_f32_16x16x32_bf16 v[2:5], v[26:29], v[190:193], v[6:9]
	v_mfma_f32_16x16x32_bf16 v[42:45], v[30:33], v[186:189], v[42:45]
	v_mfma_f32_16x16x32_bf16 v[10:13], v[30:33], v[194:197], v[2:5]
	v_mfma_f32_16x16x32_bf16 v[2:5], v[232:235], v[34:37], v[202:205]
	v_mfma_f32_16x16x32_bf16 v[70:73], v[236:239], v[38:41], v[2:5]
	v_mfma_f32_16x16x32_bf16 v[2:5], v[240:243], v[34:37], v[206:209]
	v_mfma_f32_16x16x32_bf16 v[66:69], v[244:247], v[38:41], v[2:5]
	v_mfma_f32_16x16x32_bf16 v[2:5], v[232:235], v[50:53], v[216:219]
	v_mfma_f32_16x16x32_bf16 v[54:57], v[236:239], v[178:181], v[2:5]
	v_mfma_f32_16x16x32_bf16 v[2:5], v[240:243], v[50:53], v[220:223]
	v_mfma_f32_16x16x32_bf16 v[50:53], v[244:247], v[178:181], v[2:5]
	v_mfma_f32_16x16x32_bf16 v[2:5], v[232:235], v[182:185], v[224:227]
	v_mfma_f32_16x16x32_bf16 v[38:41], v[236:239], v[186:189], v[2:5]
	v_mfma_f32_16x16x32_bf16 v[2:5], v[240:243], v[182:185], v[228:231]
	v_mfma_f32_16x16x32_bf16 v[34:37], v[244:247], v[186:189], v[2:5]
	v_mfma_f32_16x16x32_bf16 v[2:5], v[232:235], v[190:193], v[18:21]
	v_mfma_f32_16x16x32_bf16 v[6:9], v[236:239], v[194:197], v[2:5]
	v_mfma_f32_16x16x32_bf16 v[2:5], v[240:243], v[190:193], v[22:25]
	v_mfma_f32_16x16x32_bf16 v[2:5], v[244:247], v[194:197], v[2:5]
	s_setprio 0
	s_barrier
	s_andn2_b64 vcc, exec, s[48:49]
	s_cbranch_vccnz .LBB0_441
	s_barrier

.LBB0_470:
	s_mov_b64 s[4:5], 0
	s_and_b64 vcc, exec, s[6:7]
	s_mov_b64 s[6:7], 0
	s_cbranch_vccz .LBB0_616
	v_readlane_b32 s0, v254, 58
	s_cmp_lg_u32 s0, 2
	s_mov_b64 s[6:7], -1
	s_cbranch_scc0 .LBB0_616
	s_sub_i32 s0, s85, 19
	s_cmp_gt_u32 s0, 8
	s_cbranch_scc0 .LBB0_596
	s_add_i32 s6, s85, -10
	s_cmp_gt_u32 s6, 0xffffffee
	s_cselect_b64 s[2:3], -1, 0
	s_cmp_lt_u32 s6, 0xffffffef
	s_cselect_b64 s[38:39], -1, 0
	s_and_b64 s[10:11], s[38:39], exec
	s_movk_i32 s0, 0xc00
	s_cselect_b32 s84, 0x600, s0
	v_writelane_b32 v254, s2, 63
	s_lshr_b32 s86, s84, 8
	s_mul_i32 s20, s86, 0x60
	v_writelane_b32 v255, s3, 0
	v_readlane_b32 s2, v254, 55
	s_cmp_lt_i32 s2, s20
	s_cselect_b32 s0, s2, 0
	s_ashr_i32 s3, s0, 31
	s_lshr_b32 s3, s3, 29
	s_add_i32 s3, s0, s3
	s_mul_i32 s86, s86, 12
	s_ashr_i32 s7, s3, 3
	s_and_b32 s3, s3, -8
	s_sub_i32 s0, s0, s3
	s_or_b32 s76, s86, 1
	s_cmp_lt_i32 s0, 0
	s_cselect_b32 s3, s76, s86
	s_lshr_b32 s88, s84, 5
	v_cvt_f32_u32_e32 v2, s88
	s_sub_i32 s10, 0, s88
	s_mul_i32 s0, s3, s0
	s_add_i32 s3, s0, s7
	v_rcp_iflag_f32_e32 v2, v2
	s_abs_i32 s7, s3
	s_ashr_i32 s0, s3, 31
	v_mov_b32_e32 v0, v249
	v_mul_f32_e32 v2, 0x4f7ffffe, v2
	v_cvt_u32_f32_e32 v2, v2
	s_movk_i32 s44, 0x400
	s_movk_i32 s42, 0x400
	v_readfirstlane_b32 s11, v2
	s_mul_i32 s10, s10, s11
	s_mul_hi_u32 s10, s11, s10
	s_add_i32 s10, s11, s10
	s_mov_b32 s31, s10
	s_mul_hi_u32 s10, s7, s10
	s_mul_i32 s11, s10, s88
	s_sub_i32 s7, s7, s11
	s_add_i32 s11, s10, 1
	s_sub_i32 s21, s7, s88
	s_cmp_ge_u32 s7, s88
	s_cselect_b32 s10, s11, s10
	s_cselect_b32 s7, s21, s7
	s_add_i32 s11, s10, 1
	s_cmp_ge_u32 s7, s88
	s_cselect_b32 s7, s11, s10
	s_xor_b32 s7, s7, s0
	s_sub_i32 s7, s7, s0
	s_lshl_b32 s10, s7, 3
	s_sub_i32 s0, 0x60, s10
	s_min_i32 s11, s0, 8
	s_abs_i32 s21, s11
	v_cvt_f32_u32_e32 v2, s21
	s_sub_i32 s23, 0, s21
	s_mul_i32 s7, s7, s88
	s_sub_i32 s7, s3, s7
	v_rcp_iflag_f32_e32 v2, v2
	s_abs_i32 s22, s7
	s_xor_b32 s3, s7, s11
	s_ashr_i32 s3, s3, 31
	v_mul_f32_e32 v2, 0x4f7ffffe, v2
	v_cvt_u32_f32_e32 v2, v2
	v_readfirstlane_b32 s0, v0
	v_readfirstlane_b32 s24, v2
	s_mul_i32 s23, s23, s24
	s_mul_hi_u32 s23, s24, s23
	s_add_i32 s24, s24, s23
	s_mul_hi_u32 s23, s22, s24
	s_mul_i32 s24, s23, s21
	s_sub_i32 s22, s22, s24
	s_add_i32 s24, s23, 1
	s_sub_i32 s25, s22, s21
	s_cmp_ge_u32 s22, s21
	s_cselect_b32 s23, s24, s23
	s_cselect_b32 s22, s25, s22
	s_add_i32 s24, s23, 1
	s_cmp_ge_u32 s22, s21
	s_cselect_b32 s21, s24, s23
	s_xor_b32 s21, s21, s3
	s_sub_i32 s3, s21, s3
	s_mul_i32 s11, s3, s11
	s_sub_i32 s7, s7, s11
	s_add_i32 s10, s7, s10
	s_cmp_ge_i32 s2, s20
	s_cbranch_scc1 .LBB0_595
	v_bfe_i32 v4, v0, 27, 1
	v_lshlrev_b32_e32 v2, 4, v0
	v_lshrrev_b32_e32 v4, 22, v4
	v_add_u32_e32 v4, v2, v4
	v_and_b32_e32 v4, 0xfffffc00, v4
	v_sub_u32_e32 v4, v2, v4
	v_lshrrev_b32_e32 v5, 4, v4
	s_cmp_lt_u32 s6, 9
	v_ashrrev_i32_e32 v3, 31, v0
	v_bitop3_b32 v4, v5, v4, 32 bitop3:0x6c
	s_cselect_b64 s[40:41], -1, 0
	v_lshrrev_b32_e32 v3, 26, v3
	v_ashrrev_i32_e32 v6, 31, v4
	s_and_b64 s[6:7], s[40:41], exec
	v_add_u32_e32 v3, v0, v3
	v_lshrrev_b32_e32 v6, 26, v6
	s_mov_b32 s6, 0x8e8000
	v_ashrrev_i32_e32 v3, 6, v3
	v_add_u32_e32 v6, v4, v6
	s_cselect_b32 s11, s6, 0x1228000
	s_cselect_b32 s21, 22, 38
	s_cselect_b32 s22, 23, 39
	s_and_b64 s[6:7], s[38:39], exec
	v_lshlrev_b32_e32 v5, 3, v3
	v_ashrrev_i32_e32 v7, 6, v6
	v_and_b32_e32 v6, 0xc0, v6
	s_cselect_b32 s6, s11, 0xe8000
	v_and_b32_e32 v5, -16, v5
	v_lshlrev_b32_e32 v3, 5, v3
	v_sub_u32_e32 v4, v4, v6
	s_add_u32 s26, s52, s6
	v_add_u32_e32 v5, v7, v5
	v_and_b32_e32 v3, 32, v3
	v_ashrrev_i16_sdwa v4, v214, sext(v4) dst_sel:DWORD dst_unused:UNUSED_PAD src0_sel:DWORD src1_sel:BYTE_0
	v_writelane_b32 v254, s52, 61
	s_addc_u32 s27, s53, 0
	v_add_u32_sdwa v3, v3, sext(v4) dst_sel:DWORD dst_unused:UNUSED_PAD src0_sel:DWORD src1_sel:WORD_0
	v_mul_lo_u32 v4, v5, s42
	s_and_b64 s[6:7], s[38:39], exec
	v_add_lshl_u32 v152, v3, v4, 1
	v_lshlrev_b32_e32 v4, 1, v5
	v_and_b32_e32 v5, 31, v5
	s_mov_b32 s2, 0x7fffffc0
	s_cselect_b32 s6, s21, 17
	v_readlane_b32 s24, v251, 2
	v_and_or_b32 v4, v4, s2, v5
	s_lshl_b32 s6, s6, 3
	v_readlane_b32 s25, v251, 3
	v_mul_lo_u32 v4, v4, s44
	v_add_u32_e32 v2, 0x2000, v2
	s_load_dwordx2 s[6:7], s[24:25], s6 offset:0x0
	v_add_lshl_u32 v153, v4, v3, 1
	v_ashrrev_i32_e32 v3, 31, v2
	v_lshrrev_b32_e32 v3, 22, v3
	v_add_u32_e32 v3, v2, v3
	v_ashrrev_i32_e32 v3, 10, v3
	v_writelane_b32 v255, s85, 1
	v_mul_i32_i24_e32 v4, 0x400, v3
	s_waitcnt lgkmcnt(0)
	v_writelane_b32 v255, s6, 2
	v_sub_u32_e32 v2, v2, v4
	v_lshrrev_b32_e32 v4, 4, v2
	v_writelane_b32 v255, s7, 3
	s_and_b64 s[6:7], s[38:39], exec
	s_cselect_b32 s6, s22, 18
	v_bitop3_b32 v2, v4, v2, 32 bitop3:0x6c
	s_lshl_b32 s6, s6, 3
	v_ashrrev_i32_e32 v5, 31, v2
	s_load_dwordx2 s[6:7], s[24:25], s6 offset:0x0
	v_lshrrev_b32_e32 v5, 26, v5
	v_add_u32_e32 v5, v2, v5
	v_lshlrev_b32_e32 v4, 3, v3
	v_ashrrev_i32_e32 v6, 6, v5
	v_and_b32_e32 v5, 0xc0, v5
	v_and_b32_e32 v4, -16, v4
	v_lshlrev_b32_e32 v3, 5, v3
	v_sub_u32_e32 v2, v2, v5
	s_ashr_i32 s43, s42, 31
	v_add_u32_e32 v4, v6, v4
	v_and_b32_e32 v3, 32, v3
	v_ashrrev_i16_sdwa v2, v214, sext(v2) dst_sel:DWORD dst_unused:UNUSED_PAD src0_sel:DWORD src1_sel:BYTE_0
	s_lshl_b64 s[54:55], s[42:43], 9
	s_ashr_i32 s11, s10, 31
	s_waitcnt lgkmcnt(0)
	v_writelane_b32 v255, s6, 4
	v_add_u32_sdwa v2, v3, sext(v2) dst_sel:DWORD dst_unused:UNUSED_PAD src0_sel:DWORD src1_sel:WORD_0
	v_mul_lo_u32 v3, v4, s42
	s_mul_i32 s11, s54, s11
	s_mul_hi_u32 s21, s54, s10
	s_lshr_b64 s[22:23], s[42:43], 23
	v_writelane_b32 v254, s53, 62
	v_writelane_b32 v255, s7, 5
	s_ashr_i32 s6, s0, 6
	v_add_lshl_u32 v154, v2, v3, 1
	v_lshlrev_b32_e32 v3, 1, v4
	v_and_b32_e32 v4, 31, v4
	s_ashr_i32 s45, s44, 31
	s_add_i32 s11, s21, s11
	s_mul_i32 s21, s22, s10
	v_and_or_b32 v3, v3, s2, v4
	s_ashr_i32 s7, s0, 8
	s_lshl_b64 s[52:53], s[42:43], 8
	s_lshl_b64 s[56:57], s[44:45], 6
	s_lshl_b64 s[58:59], s[44:45], 9
	s_lshl_b32 s64, s6, 10
	s_add_i32 s11, s11, s21
	s_mul_i32 s21, s54, s10
	v_readlane_b32 s2, v254, 56
	s_add_u32 s42, s2, s21
	v_readlane_b32 s2, v254, 57
	s_addc_u32 s43, s2, s11
	s_ashr_i32 s11, s3, 31
	s_mul_i32 s11, s58, s11
	s_mul_hi_u32 s21, s58, s3
	s_lshr_b64 s[22:23], s[44:45], 23
	s_add_i32 s11, s21, s11
	s_mul_i32 s21, s22, s3
	s_add_i32 s11, s11, s21
	s_mul_i32 s21, s58, s3
	v_mul_lo_u32 v3, v3, s44
	s_add_u32 s44, s26, s21
	s_addc_u32 s45, s27, s11
	s_add_i32 s64, s64, 0
	s_add_i32 s65, s64, 0x10000
	s_add_i32 s22, s64, 0x12000
	s_add_u32 s46, s44, s56
	s_addc_u32 s47, s45, s57
	s_add_i32 s23, s64, 0x14000
	s_add_i32 s50, s64, 0x16000
	s_add_i32 s51, s64, 0x2000
	v_add_lshl_u32 v155, v3, v2, 1
	s_mov_b32 m0, s65
	s_nop 0
	global_load_lds_dwordx4 v153, s[44:45]
	s_mov_b32 m0, s22
	s_nop 0
	global_load_lds_dwordx4 v155, s[44:45]
	s_add_u32 s24, s42, s52
	s_mov_b32 m0, s23
	s_nop 0
	global_load_lds_dwordx4 v153, s[46:47]
	s_mov_b32 m0, s50
	s_nop 0
	global_load_lds_dwordx4 v155, s[46:47]
	s_addc_u32 s25, s43, s53
	s_add_i32 s60, s64, 0x4000
	s_add_i32 s61, s64, 0x6000
	v_writelane_b32 v255, s26, 6
	s_mov_b32 m0, s64
	s_nop 0
	global_load_lds_dwordx4 v152, s[42:43]
	s_mov_b32 m0, s51
	s_nop 0
	global_load_lds_dwordx4 v154, s[42:43]
	s_cmp_eq_u32 s7, 1
	v_writelane_b32 v255, s27, 7
	s_mov_b32 m0, s60
	s_nop 0
	global_load_lds_dwordx4 v152, s[24:25]
	s_mov_b32 m0, s61
	s_nop 0
	global_load_lds_dwordx4 v154, s[24:25]
	s_cselect_b64 s[24:25], -1, 0
	v_writelane_b32 v255, s24, 8
	s_cmp_lg_u32 s7, 1
	s_nop 0
	v_writelane_b32 v255, s25, 9
	s_cbranch_scc1 .LBB0_476
	s_barrier
.LBB0_476:
	v_readlane_b32 s24, v254, 61
	v_readlane_b32 s25, v254, 62
	s_add_u32 s62, s24, 0xa128000
	s_addc_u32 s63, s25, 0
	s_and_b64 s[24:25], s[40:41], exec
	s_mov_b32 s11, 0x2800000
	s_cselect_b32 s11, s11, 0x2d40000
	s_and_b64 s[24:25], s[38:39], exec
	s_cselect_b32 s11, s11, 0x1800000
	s_lshl_b32 s11, s11, 2
	v_readlane_b32 s68, v254, 51
	v_readlane_b32 s69, v254, 52
	s_add_u32 s24, s68, s11
	s_addc_u32 s25, s69, 0
	v_writelane_b32 v255, s24, 10
	s_mov_b32 s11, 0x2a00000
	v_and_b32_e32 v2, 48, v0
	v_writelane_b32 v255, s25, 11
	s_and_b64 s[24:25], s[40:41], exec
	s_cselect_b32 s11, s11, 0x2f40000
	s_and_b64 s[24:25], s[38:39], exec
	s_cselect_b32 s11, s11, 0x2000000
	s_lshl_b32 s11, s11, 2
	s_add_u32 s24, s68, s11
	v_lshlrev_b32_e32 v3, 6, v0
	s_movk_i32 s2, 0x3c0
	v_lshlrev_b32_e32 v0, 2, v0
	s_addc_u32 s25, s69, 0
	s_and_b32 s90, s6, 3
	s_lshl_b32 s6, s7, 13
	v_and_or_b32 v2, v3, s2, v2
	v_and_b32_e32 v0, 32, v0
	s_lshl_b32 s93, s7, 6
	v_bitop3_b32 v3, v2, s6, v0 bitop3:0xde
	s_lshl_b32 s6, s90, 12
	v_bitop3_b32 v0, v2, s6, v0 bitop3:0xde
	s_add_u32 s6, s44, 0x80
	v_writelane_b32 v255, s24, 12
	s_addc_u32 s7, s45, 0
	s_add_i32 s66, s64, 0x18000
	s_add_i32 s67, s64, 0x1a000
	v_writelane_b32 v255, s25, 13
	s_add_u32 s24, s42, 0x80
	s_waitcnt vmcnt(2)
	s_barrier
	s_mov_b32 m0, s66
	s_nop 0
	global_load_lds_dwordx4 v153, s[6:7]
	s_mov_b32 m0, s67
	s_nop 0
	global_load_lds_dwordx4 v155, s[6:7]
	s_addc_u32 s25, s43, 0
	s_add_i32 s97, s64, 0x8000
	s_add_i32 s6, s64, 0xa000
	s_mov_b32 m0, s97
	s_nop 0
	global_load_lds_dwordx4 v152, s[24:25]
	s_mov_b32 m0, s6
	s_nop 0
	global_load_lds_dwordx4 v154, s[24:25]
	s_add_u32 s24, s46, 0x80
	s_addc_u32 s25, s47, 0
	s_add_i32 s7, s64, 0x1c000
	s_add_i32 s91, s64, 0x1e000
	s_add_i32 s68, s64, 0xc000
	s_add_i32 s69, s64, 0xe000
	s_cmpk_lt_u32 s0, 0x100
	s_mov_b32 m0, s7
	s_nop 0
	global_load_lds_dwordx4 v153, s[24:25]
	s_mov_b32 m0, s91
	s_nop 0
	global_load_lds_dwordx4 v155, s[24:25]
	s_cselect_b64 s[24:25], -1, 0
	v_writelane_b32 v255, s24, 14
	s_lshl_b32 s0, s90, 6
	s_waitcnt vmcnt(6)
	v_readlane_b32 s70, v254, 53
	v_writelane_b32 v255, s25, 15
	v_writelane_b32 v255, s0, 16
	s_ashr_i32 s0, s96, 31
	v_writelane_b32 v255, s0, 18
	v_readlane_b32 s0, v254, 55
	v_readlane_b32 s71, v254, 54
	s_ashr_i32 s0, s0, 31
	v_writelane_b32 v255, s0, 19
	s_mov_b32 s21, s1
	s_mov_b32 s87, 0
	v_add_u32_e32 v156, 0, v0
	v_add_u32_e32 v157, 0, v3
	s_mov_b64 s[70:71], s[42:43]
	s_barrier
	s_branch .LBB0_479

.LBB0_484:
	v_add_u32_e32 v0, 0x10000, v156
	ds_read_b128 v[62:65], v0
	ds_read_b128 v[66:69], v0 offset:1024
	ds_read_b128 v[70:73], v0 offset:2048
	ds_read_b128 v[74:77], v0 offset:3072
	v_add_u32_e32 v0, 0x14000, v156
	ds_read_b128 v[146:149], v0
	ds_read_b128 v[158:161], v0 offset:1024
	ds_read_b128 v[162:165], v0 offset:2048
	ds_read_b128 v[166:169], v0 offset:3072
	s_cmp_eq_u32 s26, 12
	s_cselect_b32 s44, s70, s24
	s_cselect_b32 s45, s71, s25
	s_cselect_b32 s42, s72, s0
	s_cselect_b32 s43, s73, s11
	s_add_u32 s40, s44, 0x80
	s_addc_u32 s41, s45, 0
	ds_read_b128 v[170:173], v157
	ds_read_b128 v[174:177], v157 offset:1024
	ds_read_b128 v[202:205], v157 offset:2048
	ds_read_b128 v[206:209], v157 offset:3072
	ds_read_b128 v[216:219], v157 offset:4096
	ds_read_b128 v[220:223], v157 offset:5120
	ds_read_b128 v[224:227], v157 offset:6144
	ds_read_b128 v[228:231], v157 offset:7168
	s_add_u32 s27, s24, s52
	s_addc_u32 s29, s25, s53
	s_add_u32 s28, s27, 0xffffff80
	s_addc_u32 s29, s29, -1
	s_mov_b32 m0, s68
	s_nop 0
	global_load_lds_dwordx4 v152, s[28:29]
	s_mov_b32 m0, s69
	s_nop 0
	global_load_lds_dwordx4 v154, s[28:29]
	s_waitcnt vmcnt(8) lgkmcnt(0)
	s_barrier
	s_setprio 1
	v_mfma_f32_16x16x32_bf16 v[142:145], v[62:65], v[170:173], v[142:145]
	v_mfma_f32_16x16x32_bf16 v[138:141], v[70:73], v[170:173], v[138:141]
	v_mfma_f32_16x16x32_bf16 v[126:129], v[62:65], v[202:205], v[126:129]
	v_mfma_f32_16x16x32_bf16 v[122:125], v[70:73], v[202:205], v[122:125]
	v_mfma_f32_16x16x32_bf16 v[110:113], v[62:65], v[216:219], v[110:113]
	v_mfma_f32_16x16x32_bf16 v[106:109], v[70:73], v[216:219], v[106:109]
	v_mfma_f32_16x16x32_bf16 v[94:97], v[62:65], v[224:227], v[94:97]
	v_mfma_f32_16x16x32_bf16 v[90:93], v[70:73], v[224:227], v[90:93]
	v_mfma_f32_16x16x32_bf16 v[142:145], v[66:69], v[174:177], v[142:145]
	v_mfma_f32_16x16x32_bf16 v[138:141], v[74:77], v[174:177], v[138:141]
	v_mfma_f32_16x16x32_bf16 v[126:129], v[66:69], v[206:209], v[126:129]
	v_mfma_f32_16x16x32_bf16 v[122:125], v[74:77], v[206:209], v[122:125]
	v_mfma_f32_16x16x32_bf16 v[110:113], v[66:69], v[220:223], v[110:113]
	v_mfma_f32_16x16x32_bf16 v[106:109], v[74:77], v[220:223], v[106:109]
	v_mfma_f32_16x16x32_bf16 v[94:97], v[66:69], v[228:231], v[94:97]
	v_mfma_f32_16x16x32_bf16 v[90:93], v[74:77], v[228:231], v[90:93]
	v_mfma_f32_16x16x32_bf16 v[134:137], v[146:149], v[170:173], v[134:137]
	v_mfma_f32_16x16x32_bf16 v[130:133], v[162:165], v[170:173], v[130:133]
	v_mfma_f32_16x16x32_bf16 v[118:121], v[146:149], v[202:205], v[118:121]
	v_mfma_f32_16x16x32_bf16 v[114:117], v[162:165], v[202:205], v[114:117]
	v_mfma_f32_16x16x32_bf16 v[102:105], v[146:149], v[216:219], v[102:105]
	v_mfma_f32_16x16x32_bf16 v[98:101], v[162:165], v[216:219], v[98:101]
	v_mfma_f32_16x16x32_bf16 v[86:89], v[146:149], v[224:227], v[86:89]
	v_mfma_f32_16x16x32_bf16 v[82:85], v[162:165], v[224:227], v[82:85]
	v_mfma_f32_16x16x32_bf16 v[134:137], v[158:161], v[174:177], v[134:137]
	v_mfma_f32_16x16x32_bf16 v[130:133], v[166:169], v[174:177], v[130:133]
	v_mfma_f32_16x16x32_bf16 v[118:121], v[158:161], v[206:209], v[118:121]
	v_mfma_f32_16x16x32_bf16 v[114:117], v[166:169], v[206:209], v[114:117]
	v_mfma_f32_16x16x32_bf16 v[102:105], v[158:161], v[220:223], v[102:105]
	v_mfma_f32_16x16x32_bf16 v[98:101], v[166:169], v[220:223], v[98:101]
	v_mfma_f32_16x16x32_bf16 v[86:89], v[158:161], v[228:231], v[86:89]
	v_mfma_f32_16x16x32_bf16 v[82:85], v[166:169], v[228:231], v[82:85]
	s_setprio 0
	s_barrier
	ds_read_b128 v[170:173], v157 offset:16384
	ds_read_b128 v[174:177], v157 offset:17408
	ds_read_b128 v[202:205], v157 offset:18432
	ds_read_b128 v[206:209], v157 offset:19456
	ds_read_b128 v[216:219], v157 offset:20480
	ds_read_b128 v[220:223], v157 offset:21504
	ds_read_b128 v[224:227], v157 offset:22528
	ds_read_b128 v[228:231], v157 offset:23552
	s_mov_b32 m0, s65
	s_nop 0
	global_load_lds_dwordx4 v153, s[42:43]
	s_mov_b32 m0, s22
	s_nop 0
	global_load_lds_dwordx4 v155, s[42:43]
	s_add_u32 s46, s42, s56
	s_addc_u32 s47, s43, s57
	s_mov_b32 m0, s23
	s_nop 0
	global_load_lds_dwordx4 v153, s[46:47]
	s_mov_b32 m0, s50
	s_nop 0
	global_load_lds_dwordx4 v155, s[46:47]
	s_nop 0
	s_mov_b32 m0, s64
	s_nop 0
	global_load_lds_dwordx4 v152, s[44:45]
	s_mov_b32 m0, s51
	s_nop 0
	global_load_lds_dwordx4 v154, s[44:45]
	s_waitcnt vmcnt(8) lgkmcnt(0)
	s_barrier
	s_setprio 1
	v_mfma_f32_16x16x32_bf16 v[78:81], v[62:65], v[170:173], v[78:81]
	v_mfma_f32_16x16x32_bf16 v[58:61], v[70:73], v[170:173], v[58:61]
	v_mfma_f32_16x16x32_bf16 v[46:49], v[62:65], v[202:205], v[46:49]
	v_mfma_f32_16x16x32_bf16 v[42:45], v[70:73], v[202:205], v[42:45]
	v_mfma_f32_16x16x32_bf16 v[30:33], v[62:65], v[216:219], v[30:33]
	v_mfma_f32_16x16x32_bf16 v[26:29], v[70:73], v[216:219], v[26:29]
	v_mfma_f32_16x16x32_bf16 v[14:17], v[62:65], v[224:227], v[14:17]
	v_mfma_f32_16x16x32_bf16 v[10:13], v[70:73], v[224:227], v[10:13]
	v_mfma_f32_16x16x32_bf16 v[78:81], v[66:69], v[174:177], v[78:81]
	v_mfma_f32_16x16x32_bf16 v[58:61], v[74:77], v[174:177], v[58:61]
	v_mfma_f32_16x16x32_bf16 v[46:49], v[66:69], v[206:209], v[46:49]
	v_mfma_f32_16x16x32_bf16 v[42:45], v[74:77], v[206:209], v[42:45]
	v_mfma_f32_16x16x32_bf16 v[30:33], v[66:69], v[220:223], v[30:33]
	v_mfma_f32_16x16x32_bf16 v[26:29], v[74:77], v[220:223], v[26:29]
	v_mfma_f32_16x16x32_bf16 v[14:17], v[66:69], v[228:231], v[14:17]
	v_mfma_f32_16x16x32_bf16 v[10:13], v[74:77], v[228:231], v[10:13]
	v_mfma_f32_16x16x32_bf16 v[54:57], v[146:149], v[170:173], v[54:57]
	v_mfma_f32_16x16x32_bf16 v[50:53], v[162:165], v[170:173], v[50:53]
	v_mfma_f32_16x16x32_bf16 v[38:41], v[146:149], v[202:205], v[38:41]
	v_mfma_f32_16x16x32_bf16 v[34:37], v[162:165], v[202:205], v[34:37]
	v_mfma_f32_16x16x32_bf16 v[22:25], v[146:149], v[216:219], v[22:25]
	v_mfma_f32_16x16x32_bf16 v[18:21], v[162:165], v[216:219], v[18:21]
	v_mfma_f32_16x16x32_bf16 v[6:9], v[146:149], v[224:227], v[6:9]
	v_mfma_f32_16x16x32_bf16 v[2:5], v[162:165], v[224:227], v[2:5]
	v_mfma_f32_16x16x32_bf16 v[54:57], v[158:161], v[174:177], v[54:57]
	v_mfma_f32_16x16x32_bf16 v[50:53], v[166:169], v[174:177], v[50:53]
	v_mfma_f32_16x16x32_bf16 v[38:41], v[158:161], v[206:209], v[38:41]
	v_mfma_f32_16x16x32_bf16 v[34:37], v[166:169], v[206:209], v[34:37]
	v_mfma_f32_16x16x32_bf16 v[22:25], v[158:161], v[220:223], v[22:25]
	v_mfma_f32_16x16x32_bf16 v[18:21], v[166:169], v[220:223], v[18:21]
	v_mfma_f32_16x16x32_bf16 v[6:9], v[158:161], v[228:231], v[6:9]
	v_mfma_f32_16x16x32_bf16 v[2:5], v[166:169], v[228:231], v[2:5]
	s_setprio 0
	s_barrier
	v_add_u32_e32 v0, 0x18000, v156
	ds_read_b128 v[62:65], v0
	ds_read_b128 v[66:69], v0 offset:1024
	ds_read_b128 v[70:73], v0 offset:2048
	ds_read_b128 v[74:77], v0 offset:3072
	v_add_u32_e32 v0, 0x1c000, v156
	ds_read_b128 v[146:149], v0
	ds_read_b128 v[158:161], v0 offset:1024
	ds_read_b128 v[162:165], v0 offset:2048
	ds_read_b128 v[166:169], v0 offset:3072
	ds_read_b128 v[170:173], v157 offset:32768
	ds_read_b128 v[174:177], v157 offset:33792
	ds_read_b128 v[202:205], v157 offset:34816
	ds_read_b128 v[206:209], v157 offset:35840
	ds_read_b128 v[216:219], v157 offset:36864
	ds_read_b128 v[220:223], v157 offset:37888
	ds_read_b128 v[224:227], v157 offset:38912
	ds_read_b128 v[228:231], v157 offset:39936
	s_add_u32 s28, s44, s52
	s_addc_u32 s29, s45, s53
	s_mov_b32 m0, s60
	s_nop 0
	global_load_lds_dwordx4 v152, s[28:29]
	s_mov_b32 m0, s61
	s_nop 0
	global_load_lds_dwordx4 v154, s[28:29]
	s_waitcnt vmcnt(8) lgkmcnt(0)
	s_barrier
	s_setprio 1
	v_mfma_f32_16x16x32_bf16 v[142:145], v[62:65], v[170:173], v[142:145]
	v_mfma_f32_16x16x32_bf16 v[138:141], v[70:73], v[170:173], v[138:141]
	v_mfma_f32_16x16x32_bf16 v[126:129], v[62:65], v[202:205], v[126:129]
	v_mfma_f32_16x16x32_bf16 v[122:125], v[70:73], v[202:205], v[122:125]
	v_mfma_f32_16x16x32_bf16 v[110:113], v[62:65], v[216:219], v[110:113]
	v_mfma_f32_16x16x32_bf16 v[106:109], v[70:73], v[216:219], v[106:109]
	v_mfma_f32_16x16x32_bf16 v[94:97], v[62:65], v[224:227], v[94:97]
	v_mfma_f32_16x16x32_bf16 v[90:93], v[70:73], v[224:227], v[90:93]
	v_mfma_f32_16x16x32_bf16 v[142:145], v[66:69], v[174:177], v[142:145]
	v_mfma_f32_16x16x32_bf16 v[138:141], v[74:77], v[174:177], v[138:141]
	v_mfma_f32_16x16x32_bf16 v[126:129], v[66:69], v[206:209], v[126:129]
	v_mfma_f32_16x16x32_bf16 v[122:125], v[74:77], v[206:209], v[122:125]
	v_mfma_f32_16x16x32_bf16 v[110:113], v[66:69], v[220:223], v[110:113]
	v_mfma_f32_16x16x32_bf16 v[106:109], v[74:77], v[220:223], v[106:109]
	v_mfma_f32_16x16x32_bf16 v[94:97], v[66:69], v[228:231], v[94:97]
	v_mfma_f32_16x16x32_bf16 v[90:93], v[74:77], v[228:231], v[90:93]
	v_mfma_f32_16x16x32_bf16 v[134:137], v[146:149], v[170:173], v[134:137]
	v_mfma_f32_16x16x32_bf16 v[130:133], v[162:165], v[170:173], v[130:133]
	v_mfma_f32_16x16x32_bf16 v[118:121], v[146:149], v[202:205], v[118:121]
	v_mfma_f32_16x16x32_bf16 v[114:117], v[162:165], v[202:205], v[114:117]
	v_mfma_f32_16x16x32_bf16 v[102:105], v[146:149], v[216:219], v[102:105]
	v_mfma_f32_16x16x32_bf16 v[98:101], v[162:165], v[216:219], v[98:101]
	v_mfma_f32_16x16x32_bf16 v[86:89], v[146:149], v[224:227], v[86:89]
	v_mfma_f32_16x16x32_bf16 v[82:85], v[162:165], v[224:227], v[82:85]
	v_mfma_f32_16x16x32_bf16 v[134:137], v[158:161], v[174:177], v[134:137]
	v_mfma_f32_16x16x32_bf16 v[130:133], v[166:169], v[174:177], v[130:133]
	v_mfma_f32_16x16x32_bf16 v[118:121], v[158:161], v[206:209], v[118:121]
	v_mfma_f32_16x16x32_bf16 v[114:117], v[166:169], v[206:209], v[114:117]
	v_mfma_f32_16x16x32_bf16 v[102:105], v[158:161], v[220:223], v[102:105]
	v_mfma_f32_16x16x32_bf16 v[98:101], v[166:169], v[220:223], v[98:101]
	v_mfma_f32_16x16x32_bf16 v[86:89], v[158:161], v[228:231], v[86:89]
	v_mfma_f32_16x16x32_bf16 v[82:85], v[166:169], v[228:231], v[82:85]
	s_setprio 0
	s_barrier
	ds_read_b128 v[170:173], v157 offset:49152
	ds_read_b128 v[174:177], v157 offset:50176
	ds_read_b128 v[202:205], v157 offset:51200
	ds_read_b128 v[206:209], v157 offset:52224
	ds_read_b128 v[216:219], v157 offset:53248
	ds_read_b128 v[220:223], v157 offset:54272
	ds_read_b128 v[224:227], v157 offset:55296
	ds_read_b128 v[228:231], v157 offset:56320
	s_add_u32 s28, s42, 0x80
	s_addc_u32 s29, s43, 0
	s_mov_b32 m0, s66
	s_nop 0
	global_load_lds_dwordx4 v153, s[28:29]
	s_mov_b32 m0, s67
	s_nop 0
	global_load_lds_dwordx4 v155, s[28:29]
	s_add_u32 s28, s46, 0x80
	s_addc_u32 s29, s47, 0
	s_mov_b32 m0, s7
	s_nop 0
	global_load_lds_dwordx4 v153, s[28:29]
	s_mov_b32 m0, s91
	s_nop 0
	global_load_lds_dwordx4 v155, s[28:29]
	s_nop 0
	s_mov_b32 m0, s97
	s_nop 0
	global_load_lds_dwordx4 v152, s[40:41]
	s_mov_b32 m0, s6
	s_nop 0
	global_load_lds_dwordx4 v154, s[40:41]
	s_waitcnt vmcnt(8) lgkmcnt(0)
	s_barrier
	s_setprio 1
	v_mfma_f32_16x16x32_bf16 v[78:81], v[62:65], v[170:173], v[78:81]
	v_mfma_f32_16x16x32_bf16 v[58:61], v[70:73], v[170:173], v[58:61]
	v_mfma_f32_16x16x32_bf16 v[46:49], v[62:65], v[202:205], v[46:49]
	v_mfma_f32_16x16x32_bf16 v[42:45], v[70:73], v[202:205], v[42:45]
	v_mfma_f32_16x16x32_bf16 v[30:33], v[62:65], v[216:219], v[30:33]
	v_mfma_f32_16x16x32_bf16 v[26:29], v[70:73], v[216:219], v[26:29]
	v_mfma_f32_16x16x32_bf16 v[14:17], v[62:65], v[224:227], v[14:17]
	v_mfma_f32_16x16x32_bf16 v[10:13], v[70:73], v[224:227], v[10:13]
	v_mfma_f32_16x16x32_bf16 v[78:81], v[66:69], v[174:177], v[78:81]
	v_mfma_f32_16x16x32_bf16 v[58:61], v[74:77], v[174:177], v[58:61]
	v_mfma_f32_16x16x32_bf16 v[46:49], v[66:69], v[206:209], v[46:49]
	v_mfma_f32_16x16x32_bf16 v[42:45], v[74:77], v[206:209], v[42:45]
	v_mfma_f32_16x16x32_bf16 v[30:33], v[66:69], v[220:223], v[30:33]
	v_mfma_f32_16x16x32_bf16 v[26:29], v[74:77], v[220:223], v[26:29]
	v_mfma_f32_16x16x32_bf16 v[14:17], v[66:69], v[228:231], v[14:17]
	v_mfma_f32_16x16x32_bf16 v[10:13], v[74:77], v[228:231], v[10:13]
	v_mfma_f32_16x16x32_bf16 v[54:57], v[146:149], v[170:173], v[54:57]
	v_mfma_f32_16x16x32_bf16 v[50:53], v[162:165], v[170:173], v[50:53]
	v_mfma_f32_16x16x32_bf16 v[38:41], v[146:149], v[202:205], v[38:41]
	v_mfma_f32_16x16x32_bf16 v[34:37], v[162:165], v[202:205], v[34:37]
	v_mfma_f32_16x16x32_bf16 v[22:25], v[146:149], v[216:219], v[22:25]
	v_mfma_f32_16x16x32_bf16 v[18:21], v[162:165], v[216:219], v[18:21]
	v_mfma_f32_16x16x32_bf16 v[6:9], v[146:149], v[224:227], v[6:9]
	v_mfma_f32_16x16x32_bf16 v[2:5], v[162:165], v[224:227], v[2:5]
	v_mfma_f32_16x16x32_bf16 v[54:57], v[158:161], v[174:177], v[54:57]
	v_mfma_f32_16x16x32_bf16 v[50:53], v[166:169], v[174:177], v[50:53]
	v_mfma_f32_16x16x32_bf16 v[38:41], v[158:161], v[206:209], v[38:41]
	v_mfma_f32_16x16x32_bf16 v[34:37], v[166:169], v[206:209], v[34:37]
	v_mfma_f32_16x16x32_bf16 v[22:25], v[158:161], v[220:223], v[22:25]
	v_mfma_f32_16x16x32_bf16 v[18:21], v[166:169], v[220:223], v[18:21]
	v_mfma_f32_16x16x32_bf16 v[6:9], v[158:161], v[228:231], v[6:9]
	v_mfma_f32_16x16x32_bf16 v[2:5], v[166:169], v[228:231], v[2:5]
	s_setprio 0
	s_barrier
	s_add_i32 s26, s26, 2
	s_add_u32 s0, s0, 0x100
	s_addc_u32 s11, s11, 0
	s_add_u32 s24, s24, 0x100
	s_addc_u32 s25, s25, 0
	s_cmp_gt_u32 s26, 13
	s_cbranch_scc0 .LBB0_484
	v_readlane_b32 s24, v255, 14
	v_readlane_b32 s25, v255, 15
	s_and_b64 vcc, exec, s[24:25]
	s_cbranch_vccz .LBB0_487
	s_barrier

.LBB0_596:
	s_andn2_b64 vcc, exec, s[6:7]
	s_cbranch_vccnz .LBB0_615
	v_readlane_b32 s2, v254, 55
	s_cmpk_lt_i32 s2, 0xc0
	s_cselect_b32 s0, s2, 0
	s_ashr_i32 s3, s0, 31
	s_lshr_b32 s3, s3, 29
	s_add_i32 s3, s0, s3
	s_ashr_i32 s6, s3, 3
	s_and_b32 s3, s3, -8
	s_sub_i32 s0, s0, s3
	s_cmp_lt_i32 s0, 0
	s_cselect_b32 s3, 25, 24
	s_mul_i32 s0, s0, s3
	s_add_i32 s0, s0, s6
	s_ashr_i32 s3, s0, 31
	s_lshr_b32 s3, s3, 28
	s_add_i32 s3, s0, s3
	s_ashr_i32 s6, s3, 4
	s_lshl_b32 s6, s6, 3
	s_sub_i32 s7, 0x60, s6
	s_min_i32 s7, s7, 8
	s_abs_i32 s10, s7
	v_cvt_f32_u32_e32 v0, s10
	s_sub_i32 s21, 0, s10
	s_and_b32 s3, s3, -16
	s_sub_i32 s0, s0, s3
	v_rcp_iflag_f32_e32 v0, v0
	s_abs_i32 s20, s0
	s_xor_b32 s3, s0, s7
	s_ashr_i32 s3, s3, 31
	v_mul_f32_e32 v0, 0x4f7ffffe, v0
	v_cvt_u32_f32_e32 v0, v0
	v_mov_b32_e32 v2, v249
	s_movk_i32 s38, 0x400
	v_readfirstlane_b32 s22, v0
	s_mul_i32 s21, s21, s22
	s_mul_hi_u32 s21, s22, s21
	s_add_i32 s22, s22, s21
	s_mul_hi_u32 s21, s20, s22
	s_mul_i32 s22, s21, s10
	s_sub_i32 s20, s20, s22
	s_add_i32 s22, s21, 1
	s_sub_i32 s23, s20, s10
	s_cmp_ge_u32 s20, s10
	s_cselect_b32 s21, s22, s21
	s_cselect_b32 s20, s23, s20
	s_add_i32 s22, s21, 1
	s_cmp_ge_u32 s20, s10
	s_cselect_b32 s10, s22, s21
	s_xor_b32 s10, s10, s3
	s_sub_i32 s10, s10, s3
	s_mul_i32 s3, s10, s7
	s_sub_i32 s0, s0, s3
	s_add_i32 s44, s6, s0
	v_readfirstlane_b32 s11, v2
	s_movk_i32 s40, 0x400
	s_cmpk_gt_i32 s2, 0xbf
	s_cbranch_scc1 .LBB0_615
	v_bfe_i32 v4, v2, 27, 1
	v_lshlrev_b32_e32 v3, 4, v2
	v_lshrrev_b32_e32 v4, 22, v4
	v_add_u32_e32 v4, v3, v4
	v_and_b32_e32 v4, 0xfffffc00, v4
	v_sub_u32_e32 v4, v3, v4
	v_lshrrev_b32_e32 v5, 4, v4
	v_ashrrev_i32_e32 v0, 31, v2
	v_bitop3_b32 v4, v5, v4, 32 bitop3:0x6c
	v_lshrrev_b32_e32 v0, 26, v0
	v_ashrrev_i32_e32 v6, 31, v4
	v_add_u32_e32 v0, v2, v0
	v_lshrrev_b32_e32 v6, 26, v6
	v_ashrrev_i32_e32 v0, 6, v0
	v_add_u32_e32 v6, v4, v6
	v_lshlrev_b32_e32 v5, 3, v0
	v_ashrrev_i32_e32 v7, 6, v6
	v_and_b32_e32 v6, 0xc0, v6
	v_and_b32_e32 v5, -16, v5
	v_lshlrev_b32_e32 v0, 5, v0
	v_sub_u32_e32 v4, v4, v6
	v_add_u32_e32 v5, v7, v5
	v_and_b32_e32 v0, 32, v0
	v_ashrrev_i16_sdwa v4, v214, sext(v4) dst_sel:DWORD dst_unused:UNUSED_PAD src0_sel:DWORD src1_sel:BYTE_0
	v_add_u32_sdwa v4, v0, sext(v4) dst_sel:DWORD dst_unused:UNUSED_PAD src0_sel:DWORD src1_sel:WORD_0
	v_mul_lo_u32 v0, v5, s40
	v_lshlrev_b32_e32 v6, 1, v5
	v_and_b32_e32 v5, 31, v5
	s_mov_b32 s2, 0x7fffffc0
	v_and_or_b32 v5, v6, s2, v5
	v_mul_lo_u32 v5, v5, s38
	v_add_u32_e32 v3, 0x2000, v3
	v_add_lshl_u32 v0, v4, v0, 1
	v_add_lshl_u32 v130, v5, v4, 1
	v_ashrrev_i32_e32 v4, 31, v3
	v_lshrrev_b32_e32 v4, 22, v4
	v_add_u32_e32 v4, v3, v4
	v_ashrrev_i32_e32 v4, 10, v4
	v_mul_i32_i24_e32 v5, 0x400, v4
	v_sub_u32_e32 v3, v3, v5
	v_lshrrev_b32_e32 v5, 4, v3
	v_bitop3_b32 v3, v5, v3, 32 bitop3:0x6c
	v_ashrrev_i32_e32 v6, 31, v3
	v_lshrrev_b32_e32 v6, 26, v6
	s_add_u32 s0, s52, 0xde8000
	v_add_u32_e32 v6, v3, v6
	s_addc_u32 s3, s53, 0
	v_lshlrev_b32_e32 v5, 3, v4
	v_ashrrev_i32_e32 v7, 6, v6
	v_and_b32_e32 v6, 0xc0, v6
	s_ashr_i32 s41, s40, 31
	v_and_b32_e32 v5, -16, v5
	v_lshlrev_b32_e32 v4, 5, v4
	v_sub_u32_e32 v3, v3, v6
	s_lshl_b64 s[20:21], s[40:41], 9
	s_ashr_i32 s24, s44, 31
	v_add_u32_e32 v5, v7, v5
	v_and_b32_e32 v4, 32, v4
	v_ashrrev_i16_sdwa v3, v214, sext(v3) dst_sel:DWORD dst_unused:UNUSED_PAD src0_sel:DWORD src1_sel:BYTE_0
	s_mul_i32 s24, s20, s24
	s_mul_hi_u32 s25, s20, s44
	v_add_u32_sdwa v3, v4, sext(v3) dst_sel:DWORD dst_unused:UNUSED_PAD src0_sel:DWORD src1_sel:WORD_0
	v_mul_lo_u32 v4, v5, s40
	s_add_i32 s27, s25, s24
	s_lshr_b64 s[24:25], s[40:41], 23
	s_ashr_i32 s45, s11, 6
	v_add_lshl_u32 v131, v3, v4, 1
	v_lshlrev_b32_e32 v4, 1, v5
	v_and_b32_e32 v5, 31, v5
	s_ashr_i32 s39, s38, 31
	s_mul_i32 s24, s24, s44
	v_and_or_b32 v4, v4, s2, v5
	s_ashr_i32 s50, s11, 8
	s_lshl_b64 s[6:7], s[40:41], 8
	s_lshl_b64 s[22:23], s[38:39], 6
	s_lshl_b64 s[42:43], s[38:39], 9
	s_lshl_b32 s26, s45, 10
	s_add_i32 s27, s27, s24
	s_mul_i32 s24, s20, s44
	v_readlane_b32 s2, v254, 56
	s_add_u32 s54, s2, s24
	v_readlane_b32 s2, v254, 57
	s_addc_u32 s55, s2, s27
	s_ashr_i32 s24, s10, 31
	s_mul_i32 s24, s42, s24
	s_mul_hi_u32 s25, s42, s10
	s_add_i32 s27, s25, s24
	s_lshr_b64 s[24:25], s[38:39], 23
	s_mul_i32 s24, s24, s10
	s_add_i32 s27, s27, s24
	s_mul_i32 s24, s42, s10
	s_add_u32 s56, s0, s24
	s_addc_u32 s57, s3, s27
	s_add_i32 s24, s26, 0
	v_mul_lo_u32 v4, v4, s38
	s_add_i32 s25, s24, 0x10000
	s_add_i32 s26, s24, 0x12000
	v_add_lshl_u32 v132, v4, v3, 1
	s_mov_b32 m0, s25
	s_nop 0
	global_load_lds_dwordx4 v130, s[56:57]
	s_mov_b32 m0, s26
	s_nop 0
	global_load_lds_dwordx4 v132, s[56:57]
	s_add_u32 s38, s56, s22
	s_addc_u32 s39, s57, s23
	s_add_i32 s27, s24, 0x14000
	s_add_i32 s28, s24, 0x16000
	s_mov_b32 m0, s27
	s_nop 0
	global_load_lds_dwordx4 v130, s[38:39]
	s_mov_b32 m0, s28
	s_nop 0
	global_load_lds_dwordx4 v132, s[38:39]
	s_add_i32 s29, s24, 0x2000
	s_mov_b32 m0, s24
	s_nop 0
	global_load_lds_dwordx4 v0, s[54:55]
	s_mov_b32 m0, s29
	s_nop 0
	global_load_lds_dwordx4 v131, s[54:55]
	s_add_u32 s40, s54, s6
	s_addc_u32 s41, s55, s7
	s_add_i32 s30, s24, 0x4000
	s_add_i32 s31, s24, 0x6000
	s_mov_b32 m0, s30
	s_nop 0
	global_load_lds_dwordx4 v0, s[40:41]
	s_mov_b32 m0, s31
	s_nop 0
	global_load_lds_dwordx4 v131, s[40:41]
	s_cmp_eq_u32 s50, 1
	s_cselect_b64 s[46:47], -1, 0
	s_cmp_lg_u32 s50, 1
	s_cbranch_scc1 .LBB0_600
	s_barrier
.LBB0_600:
	s_add_u32 s48, s52, 0xa128000
	v_and_b32_e32 v3, 48, v2
	v_lshlrev_b32_e32 v4, 6, v2
	s_movk_i32 s2, 0x3c0
	v_lshlrev_b32_e32 v2, 2, v2
	v_writelane_b32 v254, s52, 61
	s_addc_u32 s49, s53, 0
	s_and_b32 s45, s45, 3
	s_lshl_b32 s40, s50, 13
	v_and_or_b32 v3, v4, s2, v3
	v_and_b32_e32 v2, 32, v2
	s_lshl_b32 s62, s50, 6
	v_bitop3_b32 v4, v3, s40, v2 bitop3:0xde
	s_lshl_b32 s40, s45, 12
	v_bitop3_b32 v2, v3, s40, v2 bitop3:0xde
	s_add_u32 s40, s56, 0x80
	s_addc_u32 s41, s57, 0
	s_add_i32 s63, s24, 0x18000
	s_add_i32 s64, s24, 0x1a000
	s_waitcnt vmcnt(2)
	s_barrier
	s_mov_b32 m0, s63
	s_nop 0
	global_load_lds_dwordx4 v130, s[40:41]
	s_mov_b32 m0, s64
	s_nop 0
	global_load_lds_dwordx4 v132, s[40:41]
	s_add_u32 s40, s54, 0x80
	s_addc_u32 s41, s55, 0
	s_add_i32 s65, s24, 0x8000
	s_add_i32 s66, s24, 0xa000
	s_mov_b32 m0, s65
	s_nop 0
	global_load_lds_dwordx4 v0, s[40:41]
	s_mov_b32 m0, s66
	s_nop 0
	global_load_lds_dwordx4 v131, s[40:41]
	s_add_u32 s38, s38, 0x80
	s_addc_u32 s39, s39, 0
	s_add_i32 s67, s24, 0x1c000
	s_add_i32 s68, s24, 0x1e000
	s_mov_b32 m0, s67
	s_nop 0
	global_load_lds_dwordx4 v130, s[38:39]
	s_mov_b32 m0, s68
	s_nop 0
	global_load_lds_dwordx4 v132, s[38:39]
	v_writelane_b32 v254, s53, 62
	s_waitcnt vmcnt(6)
	s_add_i32 s69, s24, 0xc000
	s_add_i32 s70, s24, 0xe000
	s_cmpk_lt_u32 s11, 0x100
	v_readlane_b32 s2, v254, 55
	s_cselect_b64 s[50:51], -1, 0
	s_lshl_b32 s71, s45, 6
	s_ashr_i32 s72, s62, 31
	s_ashr_i32 s73, s96, 31
	s_ashr_i32 s74, s2, 31
	s_mov_b32 s75, 0
	v_add_u32_e32 v133, 0, v2
	v_add_u32_e32 v134, 0, v4
	s_mov_b64 s[52:53], s[54:55]
	s_barrier
	s_waitcnt vmcnt(0)
	s_branch .LBB0_603

.LBB0_608:
	v_add_u32_e32 v135, 0x10000, v133
	ds_read_b128 v[136:139], v135
	ds_read_b128 v[140:143], v135 offset:1024
	ds_read_b128 v[144:147], v135 offset:2048
	ds_read_b128 v[148:151], v135 offset:3072
	v_add_u32_e32 v135, 0x14000, v133
	ds_read_b128 v[152:155], v135
	ds_read_b128 v[156:159], v135 offset:1024
	ds_read_b128 v[160:163], v135 offset:2048
	ds_read_b128 v[164:167], v135 offset:3072
	s_cmp_eq_u32 s81, 12
	s_cselect_b32 s58, s52, s79
	s_cselect_b32 s59, s53, s80
	s_cselect_b32 s56, s40, s11
	s_cselect_b32 s57, s41, s45
	s_add_u32 s54, s58, 0x80
	s_addc_u32 s55, s59, 0
	ds_read_b128 v[168:171], v134
	ds_read_b128 v[172:175], v134 offset:1024
	ds_read_b128 v[176:179], v134 offset:2048
	ds_read_b128 v[202:205], v134 offset:3072
	ds_read_b128 v[206:209], v134 offset:4096
	ds_read_b128 v[216:219], v134 offset:5120
	ds_read_b128 v[220:223], v134 offset:6144
	ds_read_b128 v[224:227], v134 offset:7168
	s_add_u32 s60, s79, s6
	s_addc_u32 s61, s80, s7
	s_add_u32 s60, s60, 0xffffff80
	s_addc_u32 s61, s61, -1
	s_mov_b32 m0, s69
	s_nop 0
	global_load_lds_dwordx4 v0, s[60:61]
	s_mov_b32 m0, s70
	s_nop 0
	global_load_lds_dwordx4 v131, s[60:61]
	s_waitcnt vmcnt(8) lgkmcnt(0)
	s_barrier
	s_setprio 1
	v_mfma_f32_16x16x32_bf16 v[126:129], v[136:139], v[168:171], v[126:129]
	v_mfma_f32_16x16x32_bf16 v[122:125], v[144:147], v[168:171], v[122:125]
	v_mfma_f32_16x16x32_bf16 v[118:121], v[136:139], v[176:179], v[118:121]
	v_mfma_f32_16x16x32_bf16 v[114:117], v[144:147], v[176:179], v[114:117]
	v_mfma_f32_16x16x32_bf16 v[106:109], v[136:139], v[206:209], v[106:109]
	v_mfma_f32_16x16x32_bf16 v[98:101], v[144:147], v[206:209], v[98:101]
	v_mfma_f32_16x16x32_bf16 v[90:93], v[136:139], v[220:223], v[90:93]
	v_mfma_f32_16x16x32_bf16 v[82:85], v[144:147], v[220:223], v[82:85]
	v_mfma_f32_16x16x32_bf16 v[126:129], v[140:143], v[172:175], v[126:129]
	v_mfma_f32_16x16x32_bf16 v[122:125], v[148:151], v[172:175], v[122:125]
	v_mfma_f32_16x16x32_bf16 v[118:121], v[140:143], v[202:205], v[118:121]
	v_mfma_f32_16x16x32_bf16 v[114:117], v[148:151], v[202:205], v[114:117]
	v_mfma_f32_16x16x32_bf16 v[106:109], v[140:143], v[216:219], v[106:109]
	v_mfma_f32_16x16x32_bf16 v[98:101], v[148:151], v[216:219], v[98:101]
	v_mfma_f32_16x16x32_bf16 v[90:93], v[140:143], v[224:227], v[90:93]
	v_mfma_f32_16x16x32_bf16 v[82:85], v[148:151], v[224:227], v[82:85]
	v_mfma_f32_16x16x32_bf16 v[110:113], v[152:155], v[168:171], v[110:113]
	v_mfma_f32_16x16x32_bf16 v[102:105], v[160:163], v[168:171], v[102:105]
	v_mfma_f32_16x16x32_bf16 v[94:97], v[152:155], v[176:179], v[94:97]
	v_mfma_f32_16x16x32_bf16 v[86:89], v[160:163], v[176:179], v[86:89]
	v_mfma_f32_16x16x32_bf16 v[78:81], v[152:155], v[206:209], v[78:81]
	v_mfma_f32_16x16x32_bf16 v[74:77], v[160:163], v[206:209], v[74:77]
	v_mfma_f32_16x16x32_bf16 v[70:73], v[152:155], v[220:223], v[70:73]
	v_mfma_f32_16x16x32_bf16 v[66:69], v[160:163], v[220:223], v[66:69]
	v_mfma_f32_16x16x32_bf16 v[110:113], v[156:159], v[172:175], v[110:113]
	v_mfma_f32_16x16x32_bf16 v[102:105], v[164:167], v[172:175], v[102:105]
	v_mfma_f32_16x16x32_bf16 v[94:97], v[156:159], v[202:205], v[94:97]
	v_mfma_f32_16x16x32_bf16 v[86:89], v[164:167], v[202:205], v[86:89]
	v_mfma_f32_16x16x32_bf16 v[78:81], v[156:159], v[216:219], v[78:81]
	v_mfma_f32_16x16x32_bf16 v[74:77], v[164:167], v[216:219], v[74:77]
	v_mfma_f32_16x16x32_bf16 v[70:73], v[156:159], v[224:227], v[70:73]
	v_mfma_f32_16x16x32_bf16 v[66:69], v[164:167], v[224:227], v[66:69]
	s_setprio 0
	s_barrier
	ds_read_b128 v[168:171], v134 offset:16384
	ds_read_b128 v[172:175], v134 offset:17408
	ds_read_b128 v[176:179], v134 offset:18432
	ds_read_b128 v[202:205], v134 offset:19456
	ds_read_b128 v[206:209], v134 offset:20480
	ds_read_b128 v[216:219], v134 offset:21504
	ds_read_b128 v[220:223], v134 offset:22528
	ds_read_b128 v[224:227], v134 offset:23552
	s_mov_b32 m0, s25
	s_nop 0
	global_load_lds_dwordx4 v130, s[56:57]
	s_mov_b32 m0, s26
	s_nop 0
	global_load_lds_dwordx4 v132, s[56:57]
	s_add_u32 s60, s56, s22
	s_addc_u32 s61, s57, s23
	s_mov_b32 m0, s27
	s_nop 0
	global_load_lds_dwordx4 v130, s[60:61]
	s_mov_b32 m0, s28
	s_nop 0
	global_load_lds_dwordx4 v132, s[60:61]
	s_nop 0
	s_mov_b32 m0, s24
	s_nop 0
	global_load_lds_dwordx4 v0, s[58:59]
	s_mov_b32 m0, s29
	s_nop 0
	global_load_lds_dwordx4 v131, s[58:59]
	s_waitcnt vmcnt(8) lgkmcnt(0)
	s_barrier
	s_setprio 1
	v_mfma_f32_16x16x32_bf16 v[62:65], v[136:139], v[168:171], v[62:65]
	v_mfma_f32_16x16x32_bf16 v[58:61], v[144:147], v[168:171], v[58:61]
	v_mfma_f32_16x16x32_bf16 v[54:57], v[136:139], v[176:179], v[54:57]
	v_mfma_f32_16x16x32_bf16 v[50:53], v[144:147], v[176:179], v[50:53]
	v_mfma_f32_16x16x32_bf16 v[38:41], v[136:139], v[206:209], v[38:41]
	v_mfma_f32_16x16x32_bf16 v[34:37], v[144:147], v[206:209], v[34:37]
	v_mfma_f32_16x16x32_bf16 v[22:25], v[136:139], v[220:223], v[22:25]
	v_mfma_f32_16x16x32_bf16 v[18:21], v[144:147], v[220:223], v[18:21]
	v_mfma_f32_16x16x32_bf16 v[62:65], v[140:143], v[172:175], v[62:65]
	v_mfma_f32_16x16x32_bf16 v[58:61], v[148:151], v[172:175], v[58:61]
	v_mfma_f32_16x16x32_bf16 v[54:57], v[140:143], v[202:205], v[54:57]
	v_mfma_f32_16x16x32_bf16 v[50:53], v[148:151], v[202:205], v[50:53]
	v_mfma_f32_16x16x32_bf16 v[38:41], v[140:143], v[216:219], v[38:41]
	v_mfma_f32_16x16x32_bf16 v[34:37], v[148:151], v[216:219], v[34:37]
	v_mfma_f32_16x16x32_bf16 v[22:25], v[140:143], v[224:227], v[22:25]
	v_mfma_f32_16x16x32_bf16 v[18:21], v[148:151], v[224:227], v[18:21]
	v_mfma_f32_16x16x32_bf16 v[46:49], v[152:155], v[168:171], v[46:49]
	v_mfma_f32_16x16x32_bf16 v[42:45], v[160:163], v[168:171], v[42:45]
	v_mfma_f32_16x16x32_bf16 v[30:33], v[152:155], v[176:179], v[30:33]
	v_mfma_f32_16x16x32_bf16 v[26:29], v[160:163], v[176:179], v[26:29]
	v_mfma_f32_16x16x32_bf16 v[14:17], v[152:155], v[206:209], v[14:17]
	v_mfma_f32_16x16x32_bf16 v[10:13], v[160:163], v[206:209], v[10:13]
	v_mfma_f32_16x16x32_bf16 v[6:9], v[152:155], v[220:223], v[6:9]
	v_mfma_f32_16x16x32_bf16 v[2:5], v[160:163], v[220:223], v[2:5]
	v_mfma_f32_16x16x32_bf16 v[46:49], v[156:159], v[172:175], v[46:49]
	v_mfma_f32_16x16x32_bf16 v[42:45], v[164:167], v[172:175], v[42:45]
	v_mfma_f32_16x16x32_bf16 v[30:33], v[156:159], v[202:205], v[30:33]
	v_mfma_f32_16x16x32_bf16 v[26:29], v[164:167], v[202:205], v[26:29]
	v_mfma_f32_16x16x32_bf16 v[14:17], v[156:159], v[216:219], v[14:17]
	v_mfma_f32_16x16x32_bf16 v[10:13], v[164:167], v[216:219], v[10:13]
	v_mfma_f32_16x16x32_bf16 v[6:9], v[156:159], v[224:227], v[6:9]
	v_mfma_f32_16x16x32_bf16 v[2:5], v[164:167], v[224:227], v[2:5]
	s_setprio 0
	s_barrier
	v_add_u32_e32 v135, 0x18000, v133
	ds_read_b128 v[136:139], v135
	ds_read_b128 v[140:143], v135 offset:1024
	ds_read_b128 v[144:147], v135 offset:2048
	ds_read_b128 v[148:151], v135 offset:3072
	v_add_u32_e32 v135, 0x1c000, v133
	ds_read_b128 v[152:155], v135
	ds_read_b128 v[156:159], v135 offset:1024
	ds_read_b128 v[160:163], v135 offset:2048
	ds_read_b128 v[164:167], v135 offset:3072
	ds_read_b128 v[168:171], v134 offset:32768
	ds_read_b128 v[172:175], v134 offset:33792
	ds_read_b128 v[176:179], v134 offset:34816
	ds_read_b128 v[202:205], v134 offset:35840
	ds_read_b128 v[206:209], v134 offset:36864
	ds_read_b128 v[216:219], v134 offset:37888
	ds_read_b128 v[220:223], v134 offset:38912
	ds_read_b128 v[224:227], v134 offset:39936
	s_add_u32 s58, s58, s6
	s_addc_u32 s59, s59, s7
	s_mov_b32 m0, s30
	s_nop 0
	global_load_lds_dwordx4 v0, s[58:59]
	s_mov_b32 m0, s31
	s_nop 0
	global_load_lds_dwordx4 v131, s[58:59]
	s_waitcnt vmcnt(8) lgkmcnt(0)
	s_barrier
	s_setprio 1
	v_mfma_f32_16x16x32_bf16 v[126:129], v[136:139], v[168:171], v[126:129]
	v_mfma_f32_16x16x32_bf16 v[122:125], v[144:147], v[168:171], v[122:125]
	v_mfma_f32_16x16x32_bf16 v[118:121], v[136:139], v[176:179], v[118:121]
	v_mfma_f32_16x16x32_bf16 v[114:117], v[144:147], v[176:179], v[114:117]
	v_mfma_f32_16x16x32_bf16 v[106:109], v[136:139], v[206:209], v[106:109]
	v_mfma_f32_16x16x32_bf16 v[98:101], v[144:147], v[206:209], v[98:101]
	v_mfma_f32_16x16x32_bf16 v[90:93], v[136:139], v[220:223], v[90:93]
	v_mfma_f32_16x16x32_bf16 v[82:85], v[144:147], v[220:223], v[82:85]
	v_mfma_f32_16x16x32_bf16 v[126:129], v[140:143], v[172:175], v[126:129]
	v_mfma_f32_16x16x32_bf16 v[122:125], v[148:151], v[172:175], v[122:125]
	v_mfma_f32_16x16x32_bf16 v[118:121], v[140:143], v[202:205], v[118:121]
	v_mfma_f32_16x16x32_bf16 v[114:117], v[148:151], v[202:205], v[114:117]
	v_mfma_f32_16x16x32_bf16 v[106:109], v[140:143], v[216:219], v[106:109]
	v_mfma_f32_16x16x32_bf16 v[98:101], v[148:151], v[216:219], v[98:101]
	v_mfma_f32_16x16x32_bf16 v[90:93], v[140:143], v[224:227], v[90:93]
	v_mfma_f32_16x16x32_bf16 v[82:85], v[148:151], v[224:227], v[82:85]
	v_mfma_f32_16x16x32_bf16 v[110:113], v[152:155], v[168:171], v[110:113]
	v_mfma_f32_16x16x32_bf16 v[102:105], v[160:163], v[168:171], v[102:105]
	v_mfma_f32_16x16x32_bf16 v[94:97], v[152:155], v[176:179], v[94:97]
	v_mfma_f32_16x16x32_bf16 v[86:89], v[160:163], v[176:179], v[86:89]
	v_mfma_f32_16x16x32_bf16 v[78:81], v[152:155], v[206:209], v[78:81]
	v_mfma_f32_16x16x32_bf16 v[74:77], v[160:163], v[206:209], v[74:77]
	v_mfma_f32_16x16x32_bf16 v[70:73], v[152:155], v[220:223], v[70:73]
	v_mfma_f32_16x16x32_bf16 v[66:69], v[160:163], v[220:223], v[66:69]
	v_mfma_f32_16x16x32_bf16 v[110:113], v[156:159], v[172:175], v[110:113]
	v_mfma_f32_16x16x32_bf16 v[102:105], v[164:167], v[172:175], v[102:105]
	v_mfma_f32_16x16x32_bf16 v[94:97], v[156:159], v[202:205], v[94:97]
	v_mfma_f32_16x16x32_bf16 v[86:89], v[164:167], v[202:205], v[86:89]
	v_mfma_f32_16x16x32_bf16 v[78:81], v[156:159], v[216:219], v[78:81]
	v_mfma_f32_16x16x32_bf16 v[74:77], v[164:167], v[216:219], v[74:77]
	v_mfma_f32_16x16x32_bf16 v[70:73], v[156:159], v[224:227], v[70:73]
	v_mfma_f32_16x16x32_bf16 v[66:69], v[164:167], v[224:227], v[66:69]
	s_setprio 0
	s_barrier
	ds_read_b128 v[168:171], v134 offset:49152
	ds_read_b128 v[172:175], v134 offset:50176
	ds_read_b128 v[176:179], v134 offset:51200
	ds_read_b128 v[202:205], v134 offset:52224
	ds_read_b128 v[206:209], v134 offset:53248
	ds_read_b128 v[216:219], v134 offset:54272
	ds_read_b128 v[220:223], v134 offset:55296
	ds_read_b128 v[224:227], v134 offset:56320
	s_add_u32 s56, s56, 0x80
	s_addc_u32 s57, s57, 0
	s_mov_b32 m0, s63
	s_nop 0
	global_load_lds_dwordx4 v130, s[56:57]
	s_mov_b32 m0, s64
	s_nop 0
	global_load_lds_dwordx4 v132, s[56:57]
	s_add_u32 s56, s60, 0x80
	s_addc_u32 s57, s61, 0
	s_mov_b32 m0, s67
	s_nop 0
	global_load_lds_dwordx4 v130, s[56:57]
	s_mov_b32 m0, s68
	s_nop 0
	global_load_lds_dwordx4 v132, s[56:57]
	s_mov_b32 m0, s65
	s_nop 0
	global_load_lds_dwordx4 v0, s[54:55]
	s_mov_b32 m0, s66
	s_nop 0
	global_load_lds_dwordx4 v131, s[54:55]
	s_waitcnt vmcnt(8) lgkmcnt(0)
	s_barrier
	s_setprio 1
	v_mfma_f32_16x16x32_bf16 v[62:65], v[136:139], v[168:171], v[62:65]
	v_mfma_f32_16x16x32_bf16 v[58:61], v[144:147], v[168:171], v[58:61]
	v_mfma_f32_16x16x32_bf16 v[54:57], v[136:139], v[176:179], v[54:57]
	v_mfma_f32_16x16x32_bf16 v[50:53], v[144:147], v[176:179], v[50:53]
	v_mfma_f32_16x16x32_bf16 v[38:41], v[136:139], v[206:209], v[38:41]
	v_mfma_f32_16x16x32_bf16 v[34:37], v[144:147], v[206:209], v[34:37]
	v_mfma_f32_16x16x32_bf16 v[22:25], v[136:139], v[220:223], v[22:25]
	v_mfma_f32_16x16x32_bf16 v[18:21], v[144:147], v[220:223], v[18:21]
	v_mfma_f32_16x16x32_bf16 v[62:65], v[140:143], v[172:175], v[62:65]
	v_mfma_f32_16x16x32_bf16 v[58:61], v[148:151], v[172:175], v[58:61]
	v_mfma_f32_16x16x32_bf16 v[54:57], v[140:143], v[202:205], v[54:57]
	v_mfma_f32_16x16x32_bf16 v[50:53], v[148:151], v[202:205], v[50:53]
	v_mfma_f32_16x16x32_bf16 v[38:41], v[140:143], v[216:219], v[38:41]
	v_mfma_f32_16x16x32_bf16 v[34:37], v[148:151], v[216:219], v[34:37]
	v_mfma_f32_16x16x32_bf16 v[22:25], v[140:143], v[224:227], v[22:25]
	v_mfma_f32_16x16x32_bf16 v[18:21], v[148:151], v[224:227], v[18:21]
	v_mfma_f32_16x16x32_bf16 v[46:49], v[152:155], v[168:171], v[46:49]
	v_mfma_f32_16x16x32_bf16 v[42:45], v[160:163], v[168:171], v[42:45]
	v_mfma_f32_16x16x32_bf16 v[30:33], v[152:155], v[176:179], v[30:33]
	v_mfma_f32_16x16x32_bf16 v[26:29], v[160:163], v[176:179], v[26:29]
	v_mfma_f32_16x16x32_bf16 v[14:17], v[152:155], v[206:209], v[14:17]
	v_mfma_f32_16x16x32_bf16 v[10:13], v[160:163], v[206:209], v[10:13]
	v_mfma_f32_16x16x32_bf16 v[6:9], v[152:155], v[220:223], v[6:9]
	v_mfma_f32_16x16x32_bf16 v[2:5], v[160:163], v[220:223], v[2:5]
	v_mfma_f32_16x16x32_bf16 v[46:49], v[156:159], v[172:175], v[46:49]
	v_mfma_f32_16x16x32_bf16 v[42:45], v[164:167], v[172:175], v[42:45]
	v_mfma_f32_16x16x32_bf16 v[30:33], v[156:159], v[202:205], v[30:33]
	v_mfma_f32_16x16x32_bf16 v[26:29], v[164:167], v[202:205], v[26:29]
	v_mfma_f32_16x16x32_bf16 v[14:17], v[156:159], v[216:219], v[14:17]
	v_mfma_f32_16x16x32_bf16 v[10:13], v[164:167], v[216:219], v[10:13]
	v_mfma_f32_16x16x32_bf16 v[6:9], v[156:159], v[224:227], v[6:9]
	v_mfma_f32_16x16x32_bf16 v[2:5], v[164:167], v[224:227], v[2:5]
	s_setprio 0
	s_barrier
	s_add_i32 s81, s81, 2
	s_add_u32 s11, s11, 0x100
	s_addc_u32 s45, s45, 0
	s_add_u32 s79, s79, 0x100
	s_addc_u32 s80, s80, 0
	s_cmp_gt_u32 s81, 13
	s_cbranch_scc0 .LBB0_608
	s_and_b64 vcc, exec, s[50:51]
	s_cbranch_vccz .LBB0_611
	s_barrier

.LBB0_634:
	s_and_b64 vcc, exec, s[2:3]
	s_cbranch_vccz .LBB0_1481
	v_readlane_b32 s2, v254, 55
	s_cmpk_lt_i32 s2, 0x180
	s_cselect_b32 s0, s2, 0
	s_ashr_i32 s3, s0, 31
	s_lshr_b32 s3, s3, 29
	s_add_i32 s3, s0, s3
	s_ashr_i32 s4, s3, 3
	s_and_b32 s3, s3, -8
	s_sub_i32 s0, s0, s3
	s_cmp_lt_i32 s0, 0
	s_cselect_b32 s3, 49, 48
	s_mul_i32 s0, s0, s3
	s_add_i32 s0, s0, s4
	s_ashr_i32 s3, s0, 31
	s_lshr_b32 s3, s3, 27
	s_add_i32 s3, s0, s3
	s_ashr_i32 s4, s3, 5
	s_lshl_b32 s4, s4, 3
	s_sub_i32 s5, 0x60, s4
	s_min_i32 s5, s5, 8
	s_abs_i32 s6, s5
	v_cvt_f32_u32_e32 v2, s6
	s_sub_i32 s11, 0, s6
	s_andn2_b32 s3, s3, 31
	s_sub_i32 s0, s0, s3
	v_rcp_iflag_f32_e32 v2, v2
	s_abs_i32 s7, s0
	s_xor_b32 s3, s0, s5
	s_ashr_i32 s3, s3, 31
	v_mul_f32_e32 v2, 0x4f7ffffe, v2
	v_cvt_u32_f32_e32 v2, v2
	v_mov_b32_e32 v0, v249
	s_movk_i32 s38, 0xb00
	v_readfirstlane_b32 s20, v2
	s_mul_i32 s11, s11, s20
	s_mul_hi_u32 s11, s20, s11
	s_add_i32 s20, s20, s11
	s_mul_hi_u32 s11, s7, s20
	s_mul_i32 s20, s11, s6
	s_sub_i32 s7, s7, s20
	s_add_i32 s20, s11, 1
	s_sub_i32 s21, s7, s6
	s_cmp_ge_u32 s7, s6
	s_cselect_b32 s11, s20, s11
	s_cselect_b32 s7, s21, s7
	s_add_i32 s20, s11, 1
	s_cmp_ge_u32 s7, s6
	s_cselect_b32 s6, s20, s11
	s_xor_b32 s6, s6, s3
	s_sub_i32 s3, s6, s3
	s_mul_i32 s5, s3, s5
	s_sub_i32 s0, s0, s5
	s_add_i32 s58, s4, s0
	v_readfirstlane_b32 s10, v0
	s_movk_i32 s40, 0xb00
	s_cmpk_gt_i32 s2, 0x17f
	s_cbranch_scc1 .LBB0_717
	v_bfe_i32 v4, v0, 27, 1
	v_lshlrev_b32_e32 v2, 4, v0
	v_lshrrev_b32_e32 v4, 22, v4
	v_add_u32_e32 v4, v2, v4
	v_and_b32_e32 v4, 0xfffffc00, v4
	v_sub_u32_e32 v4, v2, v4
	v_lshrrev_b32_e32 v5, 4, v4
	v_ashrrev_i32_e32 v3, 31, v0
	v_bitop3_b32 v4, v5, v4, 32 bitop3:0x6c
	v_lshrrev_b32_e32 v3, 26, v3
	v_ashrrev_i32_e32 v6, 31, v4
	v_add_u32_e32 v3, v0, v3
	v_lshrrev_b32_e32 v6, 26, v6
	v_ashrrev_i32_e32 v3, 6, v3
	v_add_u32_e32 v6, v4, v6
	v_lshlrev_b32_e32 v5, 3, v3
	v_ashrrev_i32_e32 v7, 6, v6
	v_and_b32_e32 v6, 0xc0, v6
	v_and_b32_e32 v5, -16, v5
	v_lshlrev_b32_e32 v3, 5, v3
	v_sub_u32_e32 v4, v4, v6
	v_add_u32_e32 v5, v7, v5
	v_and_b32_e32 v3, 32, v3
	v_ashrrev_i16_sdwa v4, v214, sext(v4) dst_sel:DWORD dst_unused:UNUSED_PAD src0_sel:DWORD src1_sel:BYTE_0
	v_add_u32_sdwa v3, v3, sext(v4) dst_sel:DWORD dst_unused:UNUSED_PAD src0_sel:DWORD src1_sel:WORD_0
	v_mul_lo_u32 v4, v5, s40
	v_add_lshl_u32 v215, v3, v4, 1
	v_lshlrev_b32_e32 v4, 1, v5
	v_and_b32_e32 v5, 31, v5
	s_mov_b32 s2, 0x7fffffc0
	s_add_u32 s0, s52, 0xa128000
	v_and_or_b32 v4, v4, s2, v5
	s_addc_u32 s28, s53, 0
	s_mul_i32 s5, s35, 0x580000
	v_mul_lo_u32 v4, v4, s38
	v_add_u32_e32 v2, 0x2000, v2
	s_mul_hi_i32 s4, s35, 0x580000
	s_add_u32 s5, s52, s5
	v_add_lshl_u32 v216, v4, v3, 1
	v_ashrrev_i32_e32 v3, 31, v2
	s_addc_u32 s4, s53, s4
	v_lshrrev_b32_e32 v3, 22, v3
	s_add_u32 s29, s5, 0x4328000
	v_add_u32_e32 v3, v2, v3
	s_addc_u32 s30, s4, 0
	v_ashrrev_i32_e32 v3, 10, v3
	s_ashr_i32 s41, s40, 31
	v_mul_i32_i24_e32 v4, 0x400, v3
	s_lshl_b64 s[6:7], s[40:41], 9
	s_ashr_i32 s26, s58, 31
	v_sub_u32_e32 v2, v2, v4
	s_mul_i32 s26, s6, s26
	s_mul_hi_u32 s27, s6, s58
	v_lshrrev_b32_e32 v4, 4, v2
	s_add_i32 s31, s27, s26
	s_lshr_b64 s[26:27], s[40:41], 23
	s_ashr_i32 s11, s10, 6
	v_bitop3_b32 v2, v4, v2, 32 bitop3:0x6c
	s_ashr_i32 s39, s38, 31
	s_mul_i32 s26, s26, s58
	v_ashrrev_i32_e32 v5, 31, v2
	s_ashr_i32 s24, s10, 8
	s_lshl_b64 s[4:5], s[40:41], 8
	s_lshl_b64 s[20:21], s[38:39], 6
	s_lshl_b64 s[22:23], s[38:39], 9
	s_lshl_b32 s25, s11, 10
	s_add_i32 s31, s31, s26
	s_mul_i32 s26, s6, s58
	v_lshrrev_b32_e32 v5, 26, v5
	s_add_u32 s62, s0, s26
	v_add_u32_e32 v5, v2, v5
	s_addc_u32 s63, s28, s31
	s_ashr_i32 s26, s3, 31
	v_lshlrev_b32_e32 v4, 3, v3
	v_ashrrev_i32_e32 v6, 6, v5
	v_and_b32_e32 v5, 0xc0, v5
	s_mul_i32 s26, s22, s26
	s_mul_hi_u32 s27, s22, s3
	v_and_b32_e32 v4, -16, v4
	v_lshlrev_b32_e32 v3, 5, v3
	v_sub_u32_e32 v2, v2, v5
	s_add_i32 s31, s27, s26
	s_lshr_b64 s[26:27], s[38:39], 23
	v_add_u32_e32 v4, v6, v4
	v_and_b32_e32 v3, 32, v3
	v_ashrrev_i16_sdwa v2, v214, sext(v2) dst_sel:DWORD dst_unused:UNUSED_PAD src0_sel:DWORD src1_sel:BYTE_0
	s_mul_i32 s26, s26, s3
	v_add_u32_sdwa v2, v3, sext(v2) dst_sel:DWORD dst_unused:UNUSED_PAD src0_sel:DWORD src1_sel:WORD_0
	v_mul_lo_u32 v3, v4, s40
	s_add_i32 s31, s31, s26
	s_mul_i32 s26, s22, s3
	v_add_lshl_u32 v217, v2, v3, 1
	v_lshlrev_b32_e32 v3, 1, v4
	v_and_b32_e32 v4, 31, v4
	s_add_u32 s54, s29, s26
	v_and_or_b32 v3, v3, s2, v4
	s_addc_u32 s55, s30, s31
	s_add_i32 s31, s25, 0
	v_mul_lo_u32 v3, v3, s38
	s_add_i32 s70, s31, 0x10000
	s_add_i32 s71, s31, 0x12000
	v_add_lshl_u32 v218, v3, v2, 1
	s_mov_b32 m0, s70
	s_nop 0
	global_load_lds_dwordx4 v216, s[54:55]
	s_mov_b32 m0, s71
	s_nop 0
	global_load_lds_dwordx4 v218, s[54:55]
	s_add_u32 s38, s54, s20
	s_addc_u32 s39, s55, s21
	s_add_i32 s72, s31, 0x14000
	s_add_i32 s73, s31, 0x16000
	s_mov_b32 m0, s72
	s_nop 0
	global_load_lds_dwordx4 v216, s[38:39]
	s_mov_b32 m0, s73
	s_nop 0
	global_load_lds_dwordx4 v218, s[38:39]
	s_add_i32 s74, s31, 0x2000
	s_mov_b32 m0, s31
	s_nop 0
	global_load_lds_dwordx4 v215, s[62:63]
	s_mov_b32 m0, s74
	s_nop 0
	global_load_lds_dwordx4 v217, s[62:63]
	s_add_u32 s26, s62, s4
	s_addc_u32 s27, s63, s5
	s_add_i32 s75, s31, 0x4000
	s_add_i32 s79, s31, 0x6000
	s_mov_b32 m0, s75
	s_nop 0
	global_load_lds_dwordx4 v215, s[26:27]
	s_mov_b32 m0, s79
	s_nop 0
	global_load_lds_dwordx4 v217, s[26:27]
	s_cmp_eq_u32 s24, 1
	v_mov_b32_e32 v194, 0x1600
	s_cselect_b64 s[44:45], -1, 0
	s_cmp_lg_u32 s24, 1
	s_cbranch_scc1 .LBB0_638
	s_barrier
.LBB0_638:
	s_add_u32 s46, s52, 0x16de8000
	s_addc_u32 s47, s53, 0
	s_sub_i32 s25, s85, 28
	v_readlane_b32 s40, v254, 51
	s_cmp_lt_u32 s25, 9
	v_readlane_b32 s41, v254, 52
	s_mul_i32 s26, s35, 0x36000
	s_cselect_b32 s49, s41, 0
	s_cselect_b32 s48, s40, 0
	s_mul_hi_i32 s25, s35, 0x36000
	s_add_u32 s80, s52, s26
	s_addc_u32 s81, s53, s25
	v_and_b32_e32 v2, 48, v0
	v_lshlrev_b32_e32 v3, 6, v0
	s_movk_i32 s25, 0x3c0
	v_lshlrev_b32_e32 v0, 2, v0
	s_and_b32 s11, s11, 3
	s_lshl_b32 s82, s24, 6
	s_lshl_b32 s24, s24, 13
	v_and_or_b32 v2, v3, s25, v2
	v_and_b32_e32 v0, 32, v0
	v_bitop3_b32 v3, v2, s24, v0 bitop3:0xde
	s_lshl_b32 s24, s11, 12
	v_bitop3_b32 v0, v2, s24, v0 bitop3:0xde
	s_add_u32 s24, s54, 0x80
	s_addc_u32 s25, s55, 0
	s_add_i32 s83, s31, 0x18000
	s_add_i32 s84, s31, 0x1a000
	s_waitcnt vmcnt(2)
	s_barrier
	s_mov_b32 m0, s83
	s_nop 0
	global_load_lds_dwordx4 v216, s[24:25]
	s_mov_b32 m0, s84
	s_nop 0
	global_load_lds_dwordx4 v218, s[24:25]
	s_add_u32 s24, s62, 0x80
	s_mov_b32 s2, s85
	s_addc_u32 s25, s63, 0
	s_add_i32 s85, s31, 0x8000
	s_add_i32 s86, s31, 0xa000
	s_mov_b32 m0, s85
	s_nop 0
	global_load_lds_dwordx4 v215, s[24:25]
	s_mov_b32 m0, s86
	s_nop 0
	global_load_lds_dwordx4 v217, s[24:25]
	s_add_u32 s24, s38, 0x80
	s_addc_u32 s25, s39, 0
	s_add_i32 s87, s31, 0x1c000
	s_add_i32 s88, s31, 0x1e000
	s_add_i32 s89, s31, 0xc000
	s_add_i32 s90, s31, 0xe000
	s_mov_b32 m0, s87
	s_nop 0
	global_load_lds_dwordx4 v216, s[24:25]
	s_mov_b32 m0, s88
	s_nop 0
	global_load_lds_dwordx4 v218, s[24:25]
	s_cmpk_lt_u32 s10, 0x100
	v_readlane_b32 s10, v254, 55
	s_waitcnt vmcnt(6)
	s_cselect_b64 s[50:51], -1, 0
	s_lshl_b32 s91, s11, 6
	s_ashr_i32 s97, s82, 31
	s_ashr_i32 s92, s10, 31
	v_mov_b32_e32 v2, 0
	s_cmp_lg_u64 s[48:49], 0
	s_mov_b32 s93, 0
	s_cselect_b64 s[52:53], -1, 0
	v_add_u32_e32 v219, 0, v0
	v_add_u32_e32 v220, 0, v3
	v_mov_b32_e32 v3, v2
	v_mov_b32_e32 v4, v2
	v_mov_b32_e32 v5, v2
	v_mov_b32_e32 v6, v2
	v_mov_b32_e32 v7, v2
	v_mov_b32_e32 v8, v2
	v_mov_b32_e32 v9, v2
	v_mov_b32_e32 v10, v2
	v_mov_b32_e32 v11, v2
	v_mov_b32_e32 v12, v2
	v_mov_b32_e32 v13, v2
	v_mov_b32_e32 v14, v2
	v_mov_b32_e32 v15, v2
	v_mov_b32_e32 v16, v2
	v_mov_b32_e32 v17, v2
	v_mov_b32_e32 v18, v2
	v_mov_b32_e32 v19, v2
	v_mov_b32_e32 v20, v2
	v_mov_b32_e32 v21, v2
	v_mov_b32_e32 v22, v2
	v_mov_b32_e32 v23, v2
	v_mov_b32_e32 v24, v2
	v_mov_b32_e32 v25, v2
	v_mov_b32_e32 v26, v2
	v_mov_b32_e32 v27, v2
	v_mov_b32_e32 v28, v2
	v_mov_b32_e32 v29, v2
	v_mov_b32_e32 v30, v2
	v_mov_b32_e32 v31, v2
	v_mov_b32_e32 v32, v2
	v_mov_b32_e32 v33, v2
	v_mov_b32_e32 v34, v2
	v_mov_b32_e32 v35, v2
	v_mov_b32_e32 v36, v2
	v_mov_b32_e32 v37, v2
	v_mov_b32_e32 v38, v2
	v_mov_b32_e32 v39, v2
	v_mov_b32_e32 v40, v2
	v_mov_b32_e32 v41, v2
	v_mov_b32_e32 v42, v2
	v_mov_b32_e32 v43, v2
	v_mov_b32_e32 v44, v2
	v_mov_b32_e32 v45, v2
	v_mov_b32_e32 v46, v2
	v_mov_b32_e32 v47, v2
	v_mov_b32_e32 v48, v2
	v_mov_b32_e32 v49, v2
	v_mov_b32_e32 v50, v2
	v_mov_b32_e32 v51, v2
	v_mov_b32_e32 v52, v2
	v_mov_b32_e32 v53, v2
	v_mov_b32_e32 v54, v2
	v_mov_b32_e32 v55, v2
	v_mov_b32_e32 v56, v2
	v_mov_b32_e32 v57, v2
	v_mov_b32_e32 v58, v2
	v_mov_b32_e32 v59, v2
	v_mov_b32_e32 v60, v2
	v_mov_b32_e32 v61, v2
	s_waitcnt vmcnt(0)
	v_mov_b32_e32 v62, v2
	v_mov_b32_e32 v63, v2
	v_mov_b32_e32 v64, v2
	v_mov_b32_e32 v65, v2
	v_mov_b32_e32 v66, v2
	v_mov_b32_e32 v67, v2
	v_mov_b32_e32 v68, v2
	v_mov_b32_e32 v69, v2
	v_mov_b32_e32 v70, v2
	v_mov_b32_e32 v71, v2
	v_mov_b32_e32 v72, v2
	v_mov_b32_e32 v73, v2
	v_mov_b32_e32 v74, v2
	v_mov_b32_e32 v75, v2
	v_mov_b32_e32 v76, v2
	v_mov_b32_e32 v77, v2
	v_mov_b32_e32 v78, v2
	v_mov_b32_e32 v79, v2
	v_mov_b32_e32 v80, v2
	v_mov_b32_e32 v81, v2
	v_mov_b32_e32 v82, v2
	v_mov_b32_e32 v83, v2
	v_mov_b32_e32 v84, v2
	v_mov_b32_e32 v85, v2
	v_mov_b32_e32 v86, v2
	v_mov_b32_e32 v87, v2
	v_mov_b32_e32 v88, v2
	v_mov_b32_e32 v89, v2
	v_mov_b32_e32 v90, v2
	v_mov_b32_e32 v91, v2
	v_mov_b32_e32 v92, v2
	v_mov_b32_e32 v93, v2
	v_mov_b32_e32 v94, v2
	v_mov_b32_e32 v95, v2
	v_mov_b32_e32 v96, v2
	v_mov_b32_e32 v97, v2
	v_mov_b32_e32 v98, v2
	v_mov_b32_e32 v99, v2
	v_mov_b32_e32 v100, v2
	v_mov_b32_e32 v101, v2
	v_mov_b32_e32 v102, v2
	v_mov_b32_e32 v103, v2
	v_mov_b32_e32 v104, v2
	v_mov_b32_e32 v105, v2
	v_mov_b32_e32 v106, v2
	v_mov_b32_e32 v107, v2
	v_mov_b32_e32 v108, v2
	v_mov_b32_e32 v109, v2
	v_mov_b32_e32 v110, v2
	v_mov_b32_e32 v111, v2
	v_mov_b32_e32 v112, v2
	v_mov_b32_e32 v113, v2
	v_mov_b32_e32 v114, v2
	v_mov_b32_e32 v115, v2
	v_mov_b32_e32 v116, v2
	v_mov_b32_e32 v117, v2
	v_mov_b32_e32 v118, v2
	v_mov_b32_e32 v119, v2
	v_mov_b32_e32 v120, v2
	v_mov_b32_e32 v121, v2
	v_mov_b32_e32 v122, v2
	v_mov_b32_e32 v123, v2
	v_mov_b32_e32 v124, v2
	v_mov_b32_e32 v125, v2
	v_mov_b32_e32 v126, v2
	v_mov_b32_e32 v127, v2
	v_mov_b32_e32 v128, v2
	v_mov_b32_e32 v129, v2
	s_mov_b64 s[56:57], s[62:63]
	v_readlane_b32 s42, v254, 53
	v_readlane_b32 s43, v254, 54
	s_barrier
	s_branch .LBB0_640

.LBB0_645:
	s_add_u32 s26, s76, s42
	v_add_u32_e32 v0, 0x10000, v219
	s_addc_u32 s27, s24, s43
	ds_read_b128 v[130:133], v0
	ds_read_b128 v[134:137], v0 offset:1024
	ds_read_b128 v[138:141], v0 offset:2048
	ds_read_b128 v[142:145], v0 offset:3072
	v_add_u32_e32 v0, 0x14000, v219
	s_add_u32 s59, s54, s42
	ds_read_b128 v[146:149], v0
	ds_read_b128 v[150:153], v0 offset:1024
	ds_read_b128 v[154:157], v0 offset:2048
	ds_read_b128 v[158:161], v0 offset:3072
	s_addc_u32 s62, s55, s43
	s_add_u32 s59, s59, 0x100
	s_addc_u32 s62, s62, 0
	s_cmp_eq_u32 s25, 40
	s_cselect_b32 s66, s56, s26
	s_cselect_b32 s67, s57, s27
	s_cselect_b32 s64, s60, s59
	s_cselect_b32 s65, s61, s62
	s_add_u32 s62, s66, 0x80
	s_addc_u32 s63, s67, 0
	ds_read_b128 v[162:165], v220
	ds_read_b128 v[166:169], v220 offset:1024
	ds_read_b128 v[170:173], v220 offset:2048
	ds_read_b128 v[174:177], v220 offset:3072
	ds_read_b128 v[178:181], v220 offset:4096
	ds_read_b128 v[182:185], v220 offset:5120
	ds_read_b128 v[186:189], v220 offset:6144
	ds_read_b128 v[190:193], v220 offset:7168
	s_add_u32 s26, s10, s42
	s_addc_u32 s27, s11, s43
	s_mov_b32 m0, s89
	s_nop 0
	global_load_lds_dwordx4 v215, s[26:27]
	s_mov_b32 m0, s90
	s_nop 0
	global_load_lds_dwordx4 v217, s[26:27]
	s_waitcnt vmcnt(8) lgkmcnt(0)
	s_barrier
	s_setprio 1
	v_mfma_f32_16x16x32_bf16 v[126:129], v[130:133], v[162:165], v[126:129]
	v_mfma_f32_16x16x32_bf16 v[122:125], v[138:141], v[162:165], v[122:125]
	v_mfma_f32_16x16x32_bf16 v[118:121], v[130:133], v[170:173], v[118:121]
	v_mfma_f32_16x16x32_bf16 v[114:117], v[138:141], v[170:173], v[114:117]
	v_mfma_f32_16x16x32_bf16 v[110:113], v[130:133], v[178:181], v[110:113]
	v_mfma_f32_16x16x32_bf16 v[106:109], v[138:141], v[178:181], v[106:109]
	v_mfma_f32_16x16x32_bf16 v[102:105], v[130:133], v[186:189], v[102:105]
	v_mfma_f32_16x16x32_bf16 v[98:101], v[138:141], v[186:189], v[98:101]
	v_mfma_f32_16x16x32_bf16 v[126:129], v[134:137], v[166:169], v[126:129]
	v_mfma_f32_16x16x32_bf16 v[122:125], v[142:145], v[166:169], v[122:125]
	v_mfma_f32_16x16x32_bf16 v[118:121], v[134:137], v[174:177], v[118:121]
	v_mfma_f32_16x16x32_bf16 v[114:117], v[142:145], v[174:177], v[114:117]
	v_mfma_f32_16x16x32_bf16 v[110:113], v[134:137], v[182:185], v[110:113]
	v_mfma_f32_16x16x32_bf16 v[106:109], v[142:145], v[182:185], v[106:109]
	v_mfma_f32_16x16x32_bf16 v[102:105], v[134:137], v[190:193], v[102:105]
	v_mfma_f32_16x16x32_bf16 v[98:101], v[142:145], v[190:193], v[98:101]
	v_mfma_f32_16x16x32_bf16 v[94:97], v[146:149], v[162:165], v[94:97]
	v_mfma_f32_16x16x32_bf16 v[90:93], v[154:157], v[162:165], v[90:93]
	v_mfma_f32_16x16x32_bf16 v[86:89], v[146:149], v[170:173], v[86:89]
	v_mfma_f32_16x16x32_bf16 v[82:85], v[154:157], v[170:173], v[82:85]
	v_mfma_f32_16x16x32_bf16 v[78:81], v[146:149], v[178:181], v[78:81]
	v_mfma_f32_16x16x32_bf16 v[74:77], v[154:157], v[178:181], v[74:77]
	v_mfma_f32_16x16x32_bf16 v[70:73], v[146:149], v[186:189], v[70:73]
	v_mfma_f32_16x16x32_bf16 v[66:69], v[154:157], v[186:189], v[66:69]
	v_mfma_f32_16x16x32_bf16 v[94:97], v[150:153], v[166:169], v[94:97]
	v_mfma_f32_16x16x32_bf16 v[90:93], v[158:161], v[166:169], v[90:93]
	v_mfma_f32_16x16x32_bf16 v[86:89], v[150:153], v[174:177], v[86:89]
	v_mfma_f32_16x16x32_bf16 v[82:85], v[158:161], v[174:177], v[82:85]
	v_mfma_f32_16x16x32_bf16 v[78:81], v[150:153], v[182:185], v[78:81]
	v_mfma_f32_16x16x32_bf16 v[74:77], v[158:161], v[182:185], v[74:77]
	v_mfma_f32_16x16x32_bf16 v[70:73], v[150:153], v[190:193], v[70:73]
	v_mfma_f32_16x16x32_bf16 v[66:69], v[158:161], v[190:193], v[66:69]
	s_setprio 0
	s_barrier
	ds_read_b128 v[162:165], v220 offset:16384
	ds_read_b128 v[166:169], v220 offset:17408
	ds_read_b128 v[170:173], v220 offset:18432
	ds_read_b128 v[174:177], v220 offset:19456
	ds_read_b128 v[178:181], v220 offset:20480
	ds_read_b128 v[182:185], v220 offset:21504
	ds_read_b128 v[186:189], v220 offset:22528
	ds_read_b128 v[190:193], v220 offset:23552
	s_mov_b32 m0, s70
	s_nop 0
	global_load_lds_dwordx4 v216, s[64:65]
	s_mov_b32 m0, s71
	s_nop 0
	global_load_lds_dwordx4 v218, s[64:65]
	s_add_u32 s68, s64, s20
	s_addc_u32 s69, s65, s21
	s_mov_b32 m0, s72
	s_nop 0
	global_load_lds_dwordx4 v216, s[68:69]
	s_mov_b32 m0, s73
	s_nop 0
	global_load_lds_dwordx4 v218, s[68:69]
	s_nop 0
	s_mov_b32 m0, s31
	s_nop 0
	global_load_lds_dwordx4 v215, s[66:67]
	s_mov_b32 m0, s74
	s_nop 0
	global_load_lds_dwordx4 v217, s[66:67]
	s_waitcnt vmcnt(8) lgkmcnt(0)
	s_barrier
	s_setprio 1
	v_mfma_f32_16x16x32_bf16 v[62:65], v[130:133], v[162:165], v[62:65]
	v_mfma_f32_16x16x32_bf16 v[58:61], v[138:141], v[162:165], v[58:61]
	v_mfma_f32_16x16x32_bf16 v[54:57], v[130:133], v[170:173], v[54:57]
	v_mfma_f32_16x16x32_bf16 v[50:53], v[138:141], v[170:173], v[50:53]
	v_mfma_f32_16x16x32_bf16 v[46:49], v[130:133], v[178:181], v[46:49]
	v_mfma_f32_16x16x32_bf16 v[42:45], v[138:141], v[178:181], v[42:45]
	v_mfma_f32_16x16x32_bf16 v[38:41], v[130:133], v[186:189], v[38:41]
	v_mfma_f32_16x16x32_bf16 v[34:37], v[138:141], v[186:189], v[34:37]
	v_mfma_f32_16x16x32_bf16 v[62:65], v[134:137], v[166:169], v[62:65]
	v_mfma_f32_16x16x32_bf16 v[58:61], v[142:145], v[166:169], v[58:61]
	v_mfma_f32_16x16x32_bf16 v[54:57], v[134:137], v[174:177], v[54:57]
	v_mfma_f32_16x16x32_bf16 v[50:53], v[142:145], v[174:177], v[50:53]
	v_mfma_f32_16x16x32_bf16 v[46:49], v[134:137], v[182:185], v[46:49]
	v_mfma_f32_16x16x32_bf16 v[42:45], v[142:145], v[182:185], v[42:45]
	v_mfma_f32_16x16x32_bf16 v[38:41], v[134:137], v[190:193], v[38:41]
	v_mfma_f32_16x16x32_bf16 v[34:37], v[142:145], v[190:193], v[34:37]
	v_mfma_f32_16x16x32_bf16 v[30:33], v[146:149], v[162:165], v[30:33]
	v_mfma_f32_16x16x32_bf16 v[26:29], v[154:157], v[162:165], v[26:29]
	v_mfma_f32_16x16x32_bf16 v[22:25], v[146:149], v[170:173], v[22:25]
	v_mfma_f32_16x16x32_bf16 v[18:21], v[154:157], v[170:173], v[18:21]
	v_mfma_f32_16x16x32_bf16 v[14:17], v[146:149], v[178:181], v[14:17]
	v_mfma_f32_16x16x32_bf16 v[10:13], v[154:157], v[178:181], v[10:13]
	v_mfma_f32_16x16x32_bf16 v[6:9], v[146:149], v[186:189], v[6:9]
	v_mfma_f32_16x16x32_bf16 v[2:5], v[154:157], v[186:189], v[2:5]
	v_mfma_f32_16x16x32_bf16 v[30:33], v[150:153], v[166:169], v[30:33]
	v_mfma_f32_16x16x32_bf16 v[26:29], v[158:161], v[166:169], v[26:29]
	v_mfma_f32_16x16x32_bf16 v[22:25], v[150:153], v[174:177], v[22:25]
	v_mfma_f32_16x16x32_bf16 v[18:21], v[158:161], v[174:177], v[18:21]
	v_mfma_f32_16x16x32_bf16 v[14:17], v[150:153], v[182:185], v[14:17]
	v_mfma_f32_16x16x32_bf16 v[10:13], v[158:161], v[182:185], v[10:13]
	v_mfma_f32_16x16x32_bf16 v[6:9], v[150:153], v[190:193], v[6:9]
	v_mfma_f32_16x16x32_bf16 v[2:5], v[158:161], v[190:193], v[2:5]
	s_setprio 0
	s_barrier
	v_add_u32_e32 v0, 0x18000, v219
	ds_read_b128 v[130:133], v0
	ds_read_b128 v[134:137], v0 offset:1024
	ds_read_b128 v[138:141], v0 offset:2048
	ds_read_b128 v[142:145], v0 offset:3072
	v_add_u32_e32 v0, 0x1c000, v219
	ds_read_b128 v[146:149], v0
	ds_read_b128 v[150:153], v0 offset:1024
	ds_read_b128 v[154:157], v0 offset:2048
	ds_read_b128 v[158:161], v0 offset:3072
	ds_read_b128 v[162:165], v220 offset:32768
	ds_read_b128 v[166:169], v220 offset:33792
	ds_read_b128 v[170:173], v220 offset:34816
	ds_read_b128 v[174:177], v220 offset:35840
	ds_read_b128 v[178:181], v220 offset:36864
	ds_read_b128 v[182:185], v220 offset:37888
	ds_read_b128 v[186:189], v220 offset:38912
	ds_read_b128 v[190:193], v220 offset:39936
	s_add_u32 s26, s66, s4
	s_addc_u32 s27, s67, s5
	s_mov_b32 m0, s75
	s_nop 0
	global_load_lds_dwordx4 v215, s[26:27]
	s_mov_b32 m0, s79
	s_nop 0
	global_load_lds_dwordx4 v217, s[26:27]
	s_waitcnt vmcnt(8) lgkmcnt(0)
	s_barrier
	s_setprio 1
	v_mfma_f32_16x16x32_bf16 v[126:129], v[130:133], v[162:165], v[126:129]
	v_mfma_f32_16x16x32_bf16 v[122:125], v[138:141], v[162:165], v[122:125]
	v_mfma_f32_16x16x32_bf16 v[118:121], v[130:133], v[170:173], v[118:121]
	v_mfma_f32_16x16x32_bf16 v[114:117], v[138:141], v[170:173], v[114:117]
	v_mfma_f32_16x16x32_bf16 v[110:113], v[130:133], v[178:181], v[110:113]
	v_mfma_f32_16x16x32_bf16 v[106:109], v[138:141], v[178:181], v[106:109]
	v_mfma_f32_16x16x32_bf16 v[102:105], v[130:133], v[186:189], v[102:105]
	v_mfma_f32_16x16x32_bf16 v[98:101], v[138:141], v[186:189], v[98:101]
	v_mfma_f32_16x16x32_bf16 v[126:129], v[134:137], v[166:169], v[126:129]
	v_mfma_f32_16x16x32_bf16 v[122:125], v[142:145], v[166:169], v[122:125]
	v_mfma_f32_16x16x32_bf16 v[118:121], v[134:137], v[174:177], v[118:121]
	v_mfma_f32_16x16x32_bf16 v[114:117], v[142:145], v[174:177], v[114:117]
	v_mfma_f32_16x16x32_bf16 v[110:113], v[134:137], v[182:185], v[110:113]
	v_mfma_f32_16x16x32_bf16 v[106:109], v[142:145], v[182:185], v[106:109]
	v_mfma_f32_16x16x32_bf16 v[102:105], v[134:137], v[190:193], v[102:105]
	v_mfma_f32_16x16x32_bf16 v[98:101], v[142:145], v[190:193], v[98:101]
	v_mfma_f32_16x16x32_bf16 v[94:97], v[146:149], v[162:165], v[94:97]
	v_mfma_f32_16x16x32_bf16 v[90:93], v[154:157], v[162:165], v[90:93]
	v_mfma_f32_16x16x32_bf16 v[86:89], v[146:149], v[170:173], v[86:89]
	v_mfma_f32_16x16x32_bf16 v[82:85], v[154:157], v[170:173], v[82:85]
	v_mfma_f32_16x16x32_bf16 v[78:81], v[146:149], v[178:181], v[78:81]
	v_mfma_f32_16x16x32_bf16 v[74:77], v[154:157], v[178:181], v[74:77]
	v_mfma_f32_16x16x32_bf16 v[70:73], v[146:149], v[186:189], v[70:73]
	v_mfma_f32_16x16x32_bf16 v[66:69], v[154:157], v[186:189], v[66:69]
	v_mfma_f32_16x16x32_bf16 v[94:97], v[150:153], v[166:169], v[94:97]
	v_mfma_f32_16x16x32_bf16 v[90:93], v[158:161], v[166:169], v[90:93]
	v_mfma_f32_16x16x32_bf16 v[86:89], v[150:153], v[174:177], v[86:89]
	v_mfma_f32_16x16x32_bf16 v[82:85], v[158:161], v[174:177], v[82:85]
	v_mfma_f32_16x16x32_bf16 v[78:81], v[150:153], v[182:185], v[78:81]
	v_mfma_f32_16x16x32_bf16 v[74:77], v[158:161], v[182:185], v[74:77]
	v_mfma_f32_16x16x32_bf16 v[70:73], v[150:153], v[190:193], v[70:73]
	v_mfma_f32_16x16x32_bf16 v[66:69], v[158:161], v[190:193], v[66:69]
	s_setprio 0
	s_barrier
	ds_read_b128 v[162:165], v220 offset:49152
	ds_read_b128 v[166:169], v220 offset:50176
	ds_read_b128 v[170:173], v220 offset:51200
	ds_read_b128 v[174:177], v220 offset:52224
	ds_read_b128 v[178:181], v220 offset:53248
	ds_read_b128 v[182:185], v220 offset:54272
	ds_read_b128 v[186:189], v220 offset:55296
	ds_read_b128 v[190:193], v220 offset:56320
	s_add_u32 s26, s64, 0x80
	s_addc_u32 s27, s65, 0
	s_mov_b32 m0, s83
	s_nop 0
	global_load_lds_dwordx4 v216, s[26:27]
	s_mov_b32 m0, s84
	s_nop 0
	global_load_lds_dwordx4 v218, s[26:27]
	s_add_u32 s26, s68, 0x80
	s_addc_u32 s27, s69, 0
	s_mov_b32 m0, s87
	s_nop 0
	global_load_lds_dwordx4 v216, s[26:27]
	s_mov_b32 m0, s88
	s_nop 0
	global_load_lds_dwordx4 v218, s[26:27]
	s_mov_b32 m0, s85
	s_nop 0
	global_load_lds_dwordx4 v215, s[62:63]
	s_mov_b32 m0, s86
	s_nop 0
	global_load_lds_dwordx4 v217, s[62:63]
	s_waitcnt vmcnt(8) lgkmcnt(0)
	s_barrier
	s_setprio 1
	v_mfma_f32_16x16x32_bf16 v[62:65], v[130:133], v[162:165], v[62:65]
	v_mfma_f32_16x16x32_bf16 v[58:61], v[138:141], v[162:165], v[58:61]
	v_mfma_f32_16x16x32_bf16 v[54:57], v[130:133], v[170:173], v[54:57]
	v_mfma_f32_16x16x32_bf16 v[50:53], v[138:141], v[170:173], v[50:53]
	v_mfma_f32_16x16x32_bf16 v[46:49], v[130:133], v[178:181], v[46:49]
	v_mfma_f32_16x16x32_bf16 v[42:45], v[138:141], v[178:181], v[42:45]
	v_mfma_f32_16x16x32_bf16 v[38:41], v[130:133], v[186:189], v[38:41]
	v_mfma_f32_16x16x32_bf16 v[34:37], v[138:141], v[186:189], v[34:37]
	v_mfma_f32_16x16x32_bf16 v[62:65], v[134:137], v[166:169], v[62:65]
	v_mfma_f32_16x16x32_bf16 v[58:61], v[142:145], v[166:169], v[58:61]
	v_mfma_f32_16x16x32_bf16 v[54:57], v[134:137], v[174:177], v[54:57]
	v_mfma_f32_16x16x32_bf16 v[50:53], v[142:145], v[174:177], v[50:53]
	v_mfma_f32_16x16x32_bf16 v[46:49], v[134:137], v[182:185], v[46:49]
	v_mfma_f32_16x16x32_bf16 v[42:45], v[142:145], v[182:185], v[42:45]
	v_mfma_f32_16x16x32_bf16 v[38:41], v[134:137], v[190:193], v[38:41]
	v_mfma_f32_16x16x32_bf16 v[34:37], v[142:145], v[190:193], v[34:37]
	v_mfma_f32_16x16x32_bf16 v[30:33], v[146:149], v[162:165], v[30:33]
	v_mfma_f32_16x16x32_bf16 v[26:29], v[154:157], v[162:165], v[26:29]
	v_mfma_f32_16x16x32_bf16 v[22:25], v[146:149], v[170:173], v[22:25]
	v_mfma_f32_16x16x32_bf16 v[18:21], v[154:157], v[170:173], v[18:21]
	v_mfma_f32_16x16x32_bf16 v[14:17], v[146:149], v[178:181], v[14:17]
	v_mfma_f32_16x16x32_bf16 v[10:13], v[154:157], v[178:181], v[10:13]
	v_mfma_f32_16x16x32_bf16 v[6:9], v[146:149], v[186:189], v[6:9]
	v_mfma_f32_16x16x32_bf16 v[2:5], v[154:157], v[186:189], v[2:5]
	v_mfma_f32_16x16x32_bf16 v[30:33], v[150:153], v[166:169], v[30:33]
	v_mfma_f32_16x16x32_bf16 v[26:29], v[158:161], v[166:169], v[26:29]
	v_mfma_f32_16x16x32_bf16 v[22:25], v[150:153], v[174:177], v[22:25]
	v_mfma_f32_16x16x32_bf16 v[18:21], v[158:161], v[174:177], v[18:21]
	v_mfma_f32_16x16x32_bf16 v[14:17], v[150:153], v[182:185], v[14:17]
	v_mfma_f32_16x16x32_bf16 v[10:13], v[158:161], v[182:185], v[10:13]
	v_mfma_f32_16x16x32_bf16 v[6:9], v[150:153], v[190:193], v[6:9]
	v_mfma_f32_16x16x32_bf16 v[2:5], v[158:161], v[190:193], v[2:5]
	s_setprio 0
	s_barrier
	s_add_i32 s25, s25, 2
	s_add_u32 s42, s42, 0x100
	s_addc_u32 s43, s43, 0
	s_cmp_gt_u32 s25, 41
	s_cbranch_scc0 .LBB0_645
	s_and_b64 vcc, exec, s[50:51]
	s_cbranch_vccz .LBB0_648
	s_barrier
